# GEMM K-loops: hipcc's per-phase s_setprio flips neutralized (replaced by s_nop 0, same byte layout) - strategy 7.4 step b A/B
# speedup vs baseline: 1.0091x; 1.0091x over previous
; #define STAGE(bufoff, gbase) STAGE_(bufoff, gbase, voffA)
; #define STAGEB(bufoff, gbase) STAGE_(bufoff, gbase, voffB)
; #define LDA(dst, b, h) do { _Pragma("unroll") for (int m = 0; m < 4; ++m) _Pragma("unroll") for (int k = 0; k < 2; ++k) dst[m][k] = *LDSP(const bf16x8, lds + SA(b, h) + aoff + m * 2048 + k * 1024); } while (0)
; #define LDB(dst, b, h) do { _Pragma("unroll") for (int n = 0; n < 2; ++n) _Pragma("unroll") for (int k = 0; k < 2; ++k) dst[n][k] = *LDSP(const bf16x8, lds + SB(b, h) + boff + n * 2048 + k * 1024); } while (0)
; #define MMA(ai, bj, AT, BT) do { __builtin_amdgcn_s_setprio(1); \
;     _Pragma("unroll") for (int m = 0; m < 4; ++m) _Pragma("unroll") for (int n = 0; n < 2; ++n) _Pragma("unroll") for (int k = 0; k < 2; ++k) \
;       acc[ai][bj][m][n] = __builtin_amdgcn_mfma_f32_16x16x32_bf16(BT[n][k], AT[m][k], acc[ai][bj][m][n], 0, 0, 0); \
;     __builtin_amdgcn_s_setprio(0); } while (0)
; #define WAIT_V(n) asm volatile("s_waitcnt vmcnt(" #n ")" ::: "memory")
; #define WAIT_L(n) asm volatile("s_waitcnt lgkmcnt(" #n ")" ::: "memory")
; #define BAR __builtin_amdgcn_s_barrier()
; #define SCHED __builtin_amdgcn_sched_barrier(0)
; #define WAIT_V(n) asm volatile("s_waitcnt vmcnt(" #n ")" ::: "memory")
; #define BAR do { __builtin_amdgcn_sched_barrier(0); __builtin_amdgcn_s_barrier(); asm volatile("" ::: "memory"); __builtin_amdgcn_sched_barrier(0); } while (0)
; template <bool SP2, bool ALIGN_EPI, bool DUAL, class Epi> DI void gemm_phase2(const bf16_t* A, const bf16_t* Bt, const bf16_t* A2, const bf16_t* Bt2, int M, int N, int K, const Epi& E, lds_t* lds) {
;     ...
;     for (int t = 0; t < nt; t += 2) {
;       const bool last = (t == nt - 2);
;       const char* a1 = cA + (size_t)(t + 1) * kstep;
;       const char* a2 = last ? nA : cA + (size_t)(t + 2) * kstep; const char* b2 = last ? nB : cB + (size_t)(t + 2) * kstep;
;       const char* a3 = a2 + kstep; const char* b3 = b2 + kstep;
;       if constexpr (SP2) {
;         LDB(B0, 0, 0); LDB(B1, 0, 1); SCHED; LDA(At, 0, 0); STAGE(SA(1, 1), a1 + hstep);
;         WAIT_V(8); WAIT_L(0); BAR; MMA(0, 0, At, B0); MMA(0, 1, At, B1); BAR; SCHED;
;         LDA(At, 0, 1); STAGEB(SB(0, 0), b2); STAGEB(SB(0, 1), b2 + bstep); STAGE(SA(0, 0), a2);
;         WAIT_V(8); WAIT_L(0); BAR; MMA(1, 0, At, B0); MMA(1, 1, At, B1); BAR; SCHED;
.LBB0_157:
	ds_read_b128 v[144:147], v161
	ds_read_b128 v[148:151], v161 offset:1024
	ds_read_b128 v[166:169], v161 offset:2048
	ds_read_b128 v[170:173], v161 offset:3072
	ds_read_b128 v[174:177], v162
	ds_read_b128 v[178:181], v162 offset:1024
	ds_read_b128 v[182:185], v162 offset:2048
	ds_read_b128 v[186:189], v162 offset:3072
	s_add_u32 s22, s8, 0xfffc0080
	s_addc_u32 s23, s9, -1
	s_cmp_eq_u32 s21, 12
	s_cselect_b32 s91, s0, s23
	s_cselect_b32 s90, s1, s22
	s_cselect_b32 s89, s11, s20
	s_cselect_b32 s88, s18, s19
	v_lshl_add_u64 v[152:153], s[8:9], 0, v[140:141]
	s_add_i32 m0, s3, 0xc000
	ds_read_b128 v[190:193], v163
	ds_read_b128 v[194:197], v163 offset:1024
	ds_read_b128 v[198:201], v163 offset:2048
	ds_read_b128 v[202:205], v163 offset:3072
	ds_read_b128 v[206:209], v163 offset:4096
	ds_read_b128 v[214:217], v163 offset:5120
	ds_read_b128 v[218:221], v163 offset:6144
	ds_read_b128 v[222:225], v163 offset:7168
	global_load_lds_dwordx4 v[152:153], off
	v_lshl_add_u64 v[152:153], s[8:9], 0, v[142:143]
	s_add_i32 m0, s3, 0xe000
	s_nop 0
	global_load_lds_dwordx4 v[152:153], off
	s_waitcnt vmcnt(8)
	s_waitcnt lgkmcnt(0)
	s_barrier
	s_nop 0
	s_waitcnt lgkmcnt(0)
	v_mfma_f32_16x16x32_bf16 v[124:127], v[144:147], v[190:193], v[124:127]
	v_mfma_f32_16x16x32_bf16 v[120:123], v[166:169], v[190:193], v[120:123]
	v_mfma_f32_16x16x32_bf16 v[108:111], v[144:147], v[198:201], v[108:111]
	v_mfma_f32_16x16x32_bf16 v[104:107], v[166:169], v[198:201], v[104:107]
	v_mfma_f32_16x16x32_bf16 v[92:95], v[144:147], v[206:209], v[92:95]
	v_mfma_f32_16x16x32_bf16 v[88:91], v[166:169], v[206:209], v[88:91]
	v_mfma_f32_16x16x32_bf16 v[76:79], v[144:147], v[218:221], v[76:79]
	v_mfma_f32_16x16x32_bf16 v[72:75], v[166:169], v[218:221], v[72:75]
	v_mfma_f32_16x16x32_bf16 v[124:127], v[148:151], v[194:197], v[124:127]
	v_mfma_f32_16x16x32_bf16 v[120:123], v[170:173], v[194:197], v[120:123]
	v_mfma_f32_16x16x32_bf16 v[108:111], v[148:151], v[202:205], v[108:111]
	v_mfma_f32_16x16x32_bf16 v[104:107], v[170:173], v[202:205], v[104:107]
	v_mfma_f32_16x16x32_bf16 v[92:95], v[148:151], v[214:217], v[92:95]
	v_mfma_f32_16x16x32_bf16 v[88:91], v[170:173], v[214:217], v[88:91]
	v_mfma_f32_16x16x32_bf16 v[76:79], v[148:151], v[222:225], v[76:79]
	v_mfma_f32_16x16x32_bf16 v[72:75], v[170:173], v[222:225], v[72:75]
	s_nop 0
	s_nop 0
	v_mfma_f32_16x16x32_bf16 v[116:119], v[174:177], v[190:193], v[116:119]
	v_mfma_f32_16x16x32_bf16 v[112:115], v[182:185], v[190:193], v[112:115]
	v_mfma_f32_16x16x32_bf16 v[100:103], v[174:177], v[198:201], v[100:103]
	v_mfma_f32_16x16x32_bf16 v[96:99], v[182:185], v[198:201], v[96:99]
	v_mfma_f32_16x16x32_bf16 v[84:87], v[174:177], v[206:209], v[84:87]
	v_mfma_f32_16x16x32_bf16 v[80:83], v[182:185], v[206:209], v[80:83]
	v_mfma_f32_16x16x32_bf16 v[68:71], v[174:177], v[218:221], v[68:71]
	v_mfma_f32_16x16x32_bf16 v[64:67], v[182:185], v[218:221], v[64:67]
	v_mfma_f32_16x16x32_bf16 v[116:119], v[178:181], v[194:197], v[116:119]
	v_mfma_f32_16x16x32_bf16 v[112:115], v[186:189], v[194:197], v[112:115]
	v_mfma_f32_16x16x32_bf16 v[100:103], v[178:181], v[202:205], v[100:103]
	v_mfma_f32_16x16x32_bf16 v[96:99], v[186:189], v[202:205], v[96:99]
	v_mfma_f32_16x16x32_bf16 v[84:87], v[178:181], v[214:217], v[84:87]
	v_mfma_f32_16x16x32_bf16 v[80:83], v[186:189], v[214:217], v[80:83]
	v_mfma_f32_16x16x32_bf16 v[68:71], v[178:181], v[222:225], v[68:71]
	v_mfma_f32_16x16x32_bf16 v[64:67], v[186:189], v[222:225], v[64:67]
	s_nop 0
	s_barrier
	s_add_i32 s22, s12, s2
	v_lshl_add_u64 v[152:153], s[88:89], 0, v[130:131]
	s_mov_b32 m0, s22
	ds_read_b128 v[190:193], v163 offset:16384
	ds_read_b128 v[194:197], v163 offset:17408
	ds_read_b128 v[198:201], v163 offset:18432
	ds_read_b128 v[202:205], v163 offset:19456
	ds_read_b128 v[206:209], v163 offset:20480
	ds_read_b128 v[214:217], v163 offset:21504
	ds_read_b128 v[218:221], v163 offset:22528
	ds_read_b128 v[222:225], v163 offset:23552
	global_load_lds_dwordx4 v[152:153], off
	s_add_i32 m0, s22, 0x2000
	s_add_u32 s22, s88, 0x10000
	v_lshl_add_u64 v[210:211], s[88:89], 0, v[134:135]
	s_addc_u32 s23, s89, 0
	s_add_i32 s33, s13, s2
	global_load_lds_dwordx4 v[210:211], off
	v_lshl_add_u64 v[226:227], s[22:23], 0, v[130:131]
	s_mov_b32 m0, s33
	v_lshl_add_u64 v[228:229], s[90:91], 0, v[132:133]
	global_load_lds_dwordx4 v[226:227], off
	v_lshl_add_u64 v[226:227], s[22:23], 0, v[134:135]
	s_add_i32 m0, s33, 0x2000
	s_nop 0
	global_load_lds_dwordx4 v[226:227], off
	v_lshl_add_u64 v[226:227], s[90:91], 0, v[128:129]
	s_mov_b32 m0, s3
	s_nop 0
	global_load_lds_dwordx4 v[226:227], off
	s_mov_b32 m0, s14
	s_nop 0
	global_load_lds_dwordx4 v[228:229], off
	s_waitcnt vmcnt(8)
	s_waitcnt lgkmcnt(0)
	s_barrier
; #define STAGE(bufoff, gbase) STAGE_(bufoff, gbase, voffA)
; #define LDA(dst, b, h) do { _Pragma("unroll") for (int m = 0; m < 4; ++m) _Pragma("unroll") for (int k = 0; k < 2; ++k) dst[m][k] = *LDSP(const bf16x8, lds + SA(b, h) + aoff + m * 2048 + k * 1024); } while (0)
; #define LDB(dst, b, h) do { _Pragma("unroll") for (int n = 0; n < 2; ++n) _Pragma("unroll") for (int k = 0; k < 2; ++k) dst[n][k] = *LDSP(const bf16x8, lds + SB(b, h) + boff + n * 2048 + k * 1024); } while (0)
; #define MMA(ai, bj, AT, BT) do { __builtin_amdgcn_s_setprio(1); \
;     _Pragma("unroll") for (int m = 0; m < 4; ++m) _Pragma("unroll") for (int n = 0; n < 2; ++n) _Pragma("unroll") for (int k = 0; k < 2; ++k) \
;       acc[ai][bj][m][n] = __builtin_amdgcn_mfma_f32_16x16x32_bf16(BT[n][k], AT[m][k], acc[ai][bj][m][n], 0, 0, 0); \
;     __builtin_amdgcn_s_setprio(0); } while (0)
; #define WAIT_V(n) asm volatile("s_waitcnt vmcnt(" #n ")" ::: "memory")
; #define WAIT_L(n) asm volatile("s_waitcnt lgkmcnt(" #n ")" ::: "memory")
; #define BAR __builtin_amdgcn_s_barrier()
; #define SCHED __builtin_amdgcn_sched_barrier(0)
; #define WAIT_V(n) asm volatile("s_waitcnt vmcnt(" #n ")" ::: "memory")
; #define BAR do { __builtin_amdgcn_sched_barrier(0); __builtin_amdgcn_s_barrier(); asm volatile("" ::: "memory"); __builtin_amdgcn_sched_barrier(0); } while (0)
; template <bool SP2, bool ALIGN_EPI, bool DUAL, class Epi> DI void gemm_phase2(const bf16_t* A, const bf16_t* Bt, const bf16_t* A2, const bf16_t* Bt2, int M, int N, int K, const Epi& E, lds_t* lds) {
;     ...
;         WAIT_V(8); WAIT_L(0); BAR; MMA(1, 0, At, B0); MMA(1, 1, At, B1); BAR; SCHED;
;         LDB(B0, 1, 0); LDB(B1, 1, 1); SCHED; LDA(At, 1, 0); STAGE(SA(0, 1), a2 + hstep);
;         WAIT_V(8); WAIT_L(0); BAR; MMA(0, 0, At, B0); MMA(0, 1, At, B1); BAR; SCHED;
	s_nop 0
	s_waitcnt lgkmcnt(0)
	v_mfma_f32_16x16x32_bf16 v[60:63], v[144:147], v[190:193], v[60:63]
	v_mfma_f32_16x16x32_bf16 v[56:59], v[166:169], v[190:193], v[56:59]
	v_mfma_f32_16x16x32_bf16 v[44:47], v[144:147], v[198:201], v[44:47]
	v_mfma_f32_16x16x32_bf16 v[40:43], v[166:169], v[198:201], v[40:43]
	v_mfma_f32_16x16x32_bf16 v[28:31], v[144:147], v[206:209], v[28:31]
	v_mfma_f32_16x16x32_bf16 v[24:27], v[166:169], v[206:209], v[24:27]
	v_mfma_f32_16x16x32_bf16 v[12:15], v[144:147], v[218:221], v[12:15]
	v_mfma_f32_16x16x32_bf16 v[8:11], v[166:169], v[218:221], v[8:11]
	v_mfma_f32_16x16x32_bf16 v[60:63], v[148:151], v[194:197], v[60:63]
	v_mfma_f32_16x16x32_bf16 v[56:59], v[170:173], v[194:197], v[56:59]
	v_mfma_f32_16x16x32_bf16 v[44:47], v[148:151], v[202:205], v[44:47]
	v_mfma_f32_16x16x32_bf16 v[40:43], v[170:173], v[202:205], v[40:43]
	v_mfma_f32_16x16x32_bf16 v[28:31], v[148:151], v[214:217], v[28:31]
	v_mfma_f32_16x16x32_bf16 v[24:27], v[170:173], v[214:217], v[24:27]
	v_mfma_f32_16x16x32_bf16 v[12:15], v[148:151], v[222:225], v[12:15]
	v_mfma_f32_16x16x32_bf16 v[8:11], v[170:173], v[222:225], v[8:11]
	s_nop 0
	s_nop 0
	v_mfma_f32_16x16x32_bf16 v[52:55], v[174:177], v[190:193], v[52:55]
	v_mfma_f32_16x16x32_bf16 v[48:51], v[182:185], v[190:193], v[48:51]
	v_mfma_f32_16x16x32_bf16 v[36:39], v[174:177], v[198:201], v[36:39]
	v_mfma_f32_16x16x32_bf16 v[32:35], v[182:185], v[198:201], v[32:35]
	v_mfma_f32_16x16x32_bf16 v[20:23], v[174:177], v[206:209], v[20:23]
	v_mfma_f32_16x16x32_bf16 v[16:19], v[182:185], v[206:209], v[16:19]
	v_mfma_f32_16x16x32_bf16 v[4:7], v[174:177], v[218:221], v[4:7]
	v_mfma_f32_16x16x32_bf16 v[0:3], v[182:185], v[218:221], v[0:3]
	v_mfma_f32_16x16x32_bf16 v[52:55], v[178:181], v[194:197], v[52:55]
	v_mfma_f32_16x16x32_bf16 v[48:51], v[186:189], v[194:197], v[48:51]
	v_mfma_f32_16x16x32_bf16 v[36:39], v[178:181], v[202:205], v[36:39]
	v_mfma_f32_16x16x32_bf16 v[32:35], v[186:189], v[202:205], v[32:35]
	v_mfma_f32_16x16x32_bf16 v[20:23], v[178:181], v[214:217], v[20:23]
	v_mfma_f32_16x16x32_bf16 v[16:19], v[186:189], v[214:217], v[16:19]
	v_mfma_f32_16x16x32_bf16 v[4:7], v[178:181], v[222:225], v[4:7]
	v_mfma_f32_16x16x32_bf16 v[0:3], v[186:189], v[222:225], v[0:3]
	s_nop 0
	s_barrier
	s_add_i32 s33, 0, 0x18000
	s_add_i32 s34, 0, 0x1c000
	v_add_u32_e32 v170, s33, v157
	v_add_u32_e32 v186, s34, v157
	ds_read_b128 v[144:147], v170
	ds_read_b128 v[148:151], v170 offset:1024
	ds_read_b128 v[166:169], v170 offset:2048
	ds_read_b128 v[170:173], v170 offset:3072
	ds_read_b128 v[174:177], v186
	ds_read_b128 v[178:181], v186 offset:1024
	ds_read_b128 v[182:185], v186 offset:2048
	ds_read_b128 v[186:189], v186 offset:3072
	s_add_u32 s22, s90, 0x40000
	s_addc_u32 s23, s91, 0
	s_mov_b32 m0, s15
	v_lshl_add_u64 v[230:231], s[22:23], 0, v[128:129]
	ds_read_b128 v[190:193], v163 offset:32768
	ds_read_b128 v[194:197], v163 offset:33792
	ds_read_b128 v[198:201], v163 offset:34816
	ds_read_b128 v[202:205], v163 offset:35840
	ds_read_b128 v[206:209], v163 offset:36864
	ds_read_b128 v[214:217], v163 offset:37888
	ds_read_b128 v[218:221], v163 offset:38912
	ds_read_b128 v[222:225], v163 offset:39936
	global_load_lds_dwordx4 v[230:231], off
	v_lshl_add_u64 v[230:231], s[22:23], 0, v[132:133]
	s_mov_b32 m0, s35
	s_nop 0
	global_load_lds_dwordx4 v[230:231], off
	s_waitcnt vmcnt(8)
	s_waitcnt lgkmcnt(0)
	s_barrier
	s_nop 0
	s_waitcnt lgkmcnt(0)
	v_mfma_f32_16x16x32_bf16 v[124:127], v[144:147], v[190:193], v[124:127]
	v_mfma_f32_16x16x32_bf16 v[120:123], v[166:169], v[190:193], v[120:123]
	v_mfma_f32_16x16x32_bf16 v[108:111], v[144:147], v[198:201], v[108:111]
	v_mfma_f32_16x16x32_bf16 v[104:107], v[166:169], v[198:201], v[104:107]
	v_mfma_f32_16x16x32_bf16 v[92:95], v[144:147], v[206:209], v[92:95]
	v_mfma_f32_16x16x32_bf16 v[88:91], v[166:169], v[206:209], v[88:91]
	v_mfma_f32_16x16x32_bf16 v[76:79], v[144:147], v[218:221], v[76:79]
	v_mfma_f32_16x16x32_bf16 v[72:75], v[166:169], v[218:221], v[72:75]
	v_mfma_f32_16x16x32_bf16 v[124:127], v[148:151], v[194:197], v[124:127]
	v_mfma_f32_16x16x32_bf16 v[120:123], v[170:173], v[194:197], v[120:123]
	v_mfma_f32_16x16x32_bf16 v[108:111], v[148:151], v[202:205], v[108:111]
	v_mfma_f32_16x16x32_bf16 v[104:107], v[170:173], v[202:205], v[104:107]
	v_mfma_f32_16x16x32_bf16 v[92:95], v[148:151], v[214:217], v[92:95]
	v_mfma_f32_16x16x32_bf16 v[88:91], v[170:173], v[214:217], v[88:91]
	v_mfma_f32_16x16x32_bf16 v[76:79], v[148:151], v[222:225], v[76:79]
	v_mfma_f32_16x16x32_bf16 v[72:75], v[170:173], v[222:225], v[72:75]
	s_nop 0
	s_nop 0
	v_mfma_f32_16x16x32_bf16 v[116:119], v[174:177], v[190:193], v[116:119]
	v_mfma_f32_16x16x32_bf16 v[112:115], v[182:185], v[190:193], v[112:115]
	v_mfma_f32_16x16x32_bf16 v[100:103], v[174:177], v[198:201], v[100:103]
	v_mfma_f32_16x16x32_bf16 v[96:99], v[182:185], v[198:201], v[96:99]
	v_mfma_f32_16x16x32_bf16 v[84:87], v[174:177], v[206:209], v[84:87]
	v_mfma_f32_16x16x32_bf16 v[80:83], v[182:185], v[206:209], v[80:83]
	v_mfma_f32_16x16x32_bf16 v[68:71], v[174:177], v[218:221], v[68:71]
	v_mfma_f32_16x16x32_bf16 v[64:67], v[182:185], v[218:221], v[64:67]
	v_mfma_f32_16x16x32_bf16 v[116:119], v[178:181], v[194:197], v[116:119]
	v_mfma_f32_16x16x32_bf16 v[112:115], v[186:189], v[194:197], v[112:115]
	v_mfma_f32_16x16x32_bf16 v[100:103], v[178:181], v[202:205], v[100:103]
	v_mfma_f32_16x16x32_bf16 v[96:99], v[186:189], v[202:205], v[96:99]
	v_mfma_f32_16x16x32_bf16 v[84:87], v[178:181], v[214:217], v[84:87]
	v_mfma_f32_16x16x32_bf16 v[80:83], v[186:189], v[214:217], v[80:83]
	v_mfma_f32_16x16x32_bf16 v[68:71], v[178:181], v[222:225], v[68:71]
	v_mfma_f32_16x16x32_bf16 v[64:67], v[186:189], v[222:225], v[64:67]
	s_nop 0
	s_barrier
; #define STAGE(bufoff, gbase) STAGE_(bufoff, gbase, voffA)
; #define STAGEB(bufoff, gbase) STAGE_(bufoff, gbase, voffB)
; #define LDA(dst, b, h) do { _Pragma("unroll") for (int m = 0; m < 4; ++m) _Pragma("unroll") for (int k = 0; k < 2; ++k) dst[m][k] = *LDSP(const bf16x8, lds + SA(b, h) + aoff + m * 2048 + k * 1024); } while (0)
; #define MMA(ai, bj, AT, BT) do { __builtin_amdgcn_s_setprio(1); \
;     _Pragma("unroll") for (int m = 0; m < 4; ++m) _Pragma("unroll") for (int n = 0; n < 2; ++n) _Pragma("unroll") for (int k = 0; k < 2; ++k) \
;       acc[ai][bj][m][n] = __builtin_amdgcn_mfma_f32_16x16x32_bf16(BT[n][k], AT[m][k], acc[ai][bj][m][n], 0, 0, 0); \
;     __builtin_amdgcn_s_setprio(0); } while (0)
; #define WAIT_V(n) asm volatile("s_waitcnt vmcnt(" #n ")" ::: "memory")
; #define WAIT_L(n) asm volatile("s_waitcnt lgkmcnt(" #n ")" ::: "memory")
; #define BAR __builtin_amdgcn_s_barrier()
; #define SCHED __builtin_amdgcn_sched_barrier(0)
; #define WAIT_V(n) asm volatile("s_waitcnt vmcnt(" #n ")" ::: "memory")
; #define BAR do { __builtin_amdgcn_sched_barrier(0); __builtin_amdgcn_s_barrier(); asm volatile("" ::: "memory"); __builtin_amdgcn_sched_barrier(0); } while (0)
; template <bool SP2, bool ALIGN_EPI, bool DUAL, class Epi> DI void gemm_phase2(const bf16_t* A, const bf16_t* Bt, const bf16_t* A2, const bf16_t* Bt2, int M, int N, int K, const Epi& E, lds_t* lds) {
;     ...
;     for (int t = 0; t < nt; t += 2) {
;       const bool last = (t == nt - 2);
;       const char* a1 = cA + (size_t)(t + 1) * kstep;
;       const char* a2 = last ? nA : cA + (size_t)(t + 2) * kstep; const char* b2 = last ? nB : cB + (size_t)(t + 2) * kstep;
;       const char* a3 = a2 + kstep; const char* b3 = b2 + kstep;
;     ...
;         LDA(At, 1, 1); STAGEB(SB(1, 0), b3); STAGEB(SB(1, 1), b3 + bstep); STAGE(SA(1, 0), a3);
;         WAIT_V(8); WAIT_L(0); BAR; MMA(1, 0, At, B0); MMA(1, 1, At, B1); BAR; SCHED;
	s_add_i32 s22, s33, s2
	v_lshl_add_u64 v[152:153], v[152:153], 0, s[58:59]
	s_mov_b32 m0, s22
	ds_read_b128 v[190:193], v163 offset:49152
	ds_read_b128 v[194:197], v163 offset:50176
	ds_read_b128 v[198:201], v163 offset:51200
	ds_read_b128 v[202:205], v163 offset:52224
	ds_read_b128 v[206:209], v163 offset:53248
	ds_read_b128 v[214:217], v163 offset:54272
	ds_read_b128 v[218:221], v163 offset:55296
	ds_read_b128 v[222:225], v163 offset:56320
	global_load_lds_dwordx4 v[152:153], off
	s_add_i32 m0, s22, 0x2000
	s_add_u32 s22, s88, 0x10080
	v_lshl_add_u64 v[152:153], v[210:211], 0, s[58:59]
	s_addc_u32 s23, s89, 0
	s_add_i32 s33, s34, s2
	global_load_lds_dwordx4 v[152:153], off
	v_lshl_add_u64 v[152:153], s[22:23], 0, v[130:131]
	s_mov_b32 m0, s33
	s_nop 0
	global_load_lds_dwordx4 v[152:153], off
	v_lshl_add_u64 v[152:153], s[22:23], 0, v[134:135]
	s_add_i32 m0, s33, 0x2000
	s_nop 0
	global_load_lds_dwordx4 v[152:153], off
	v_lshl_add_u64 v[152:153], v[226:227], 0, s[58:59]
	s_mov_b32 m0, s52
	s_nop 0
	global_load_lds_dwordx4 v[152:153], off
	v_lshl_add_u64 v[152:153], v[228:229], 0, s[58:59]
	s_mov_b32 m0, s53
	s_nop 0
	global_load_lds_dwordx4 v[152:153], off
	s_waitcnt vmcnt(8)
	s_waitcnt lgkmcnt(0)
	s_barrier
	s_nop 0
	s_waitcnt lgkmcnt(0)
	v_mfma_f32_16x16x32_bf16 v[60:63], v[144:147], v[190:193], v[60:63]
	v_mfma_f32_16x16x32_bf16 v[56:59], v[166:169], v[190:193], v[56:59]
	v_mfma_f32_16x16x32_bf16 v[44:47], v[144:147], v[198:201], v[44:47]
	v_mfma_f32_16x16x32_bf16 v[40:43], v[166:169], v[198:201], v[40:43]
	v_mfma_f32_16x16x32_bf16 v[28:31], v[144:147], v[206:209], v[28:31]
	v_mfma_f32_16x16x32_bf16 v[24:27], v[166:169], v[206:209], v[24:27]
	v_mfma_f32_16x16x32_bf16 v[12:15], v[144:147], v[218:221], v[12:15]
	v_mfma_f32_16x16x32_bf16 v[8:11], v[166:169], v[218:221], v[8:11]
	v_mfma_f32_16x16x32_bf16 v[60:63], v[148:151], v[194:197], v[60:63]
	v_mfma_f32_16x16x32_bf16 v[56:59], v[170:173], v[194:197], v[56:59]
	v_mfma_f32_16x16x32_bf16 v[44:47], v[148:151], v[202:205], v[44:47]
	v_mfma_f32_16x16x32_bf16 v[40:43], v[170:173], v[202:205], v[40:43]
	v_mfma_f32_16x16x32_bf16 v[28:31], v[148:151], v[214:217], v[28:31]
	v_mfma_f32_16x16x32_bf16 v[24:27], v[170:173], v[214:217], v[24:27]
	v_mfma_f32_16x16x32_bf16 v[12:15], v[148:151], v[222:225], v[12:15]
	v_mfma_f32_16x16x32_bf16 v[8:11], v[170:173], v[222:225], v[8:11]
	s_nop 0
	s_nop 0
	v_mfma_f32_16x16x32_bf16 v[52:55], v[174:177], v[190:193], v[52:55]
	v_mfma_f32_16x16x32_bf16 v[48:51], v[182:185], v[190:193], v[48:51]
	v_mfma_f32_16x16x32_bf16 v[36:39], v[174:177], v[198:201], v[36:39]
	v_mfma_f32_16x16x32_bf16 v[32:35], v[182:185], v[198:201], v[32:35]
	v_mfma_f32_16x16x32_bf16 v[20:23], v[174:177], v[206:209], v[20:23]
	v_mfma_f32_16x16x32_bf16 v[16:19], v[182:185], v[206:209], v[16:19]
	v_mfma_f32_16x16x32_bf16 v[4:7], v[174:177], v[218:221], v[4:7]
	v_mfma_f32_16x16x32_bf16 v[0:3], v[182:185], v[218:221], v[0:3]
	v_mfma_f32_16x16x32_bf16 v[52:55], v[178:181], v[194:197], v[52:55]
	v_mfma_f32_16x16x32_bf16 v[48:51], v[186:189], v[194:197], v[48:51]
	v_mfma_f32_16x16x32_bf16 v[36:39], v[178:181], v[202:205], v[36:39]
	v_mfma_f32_16x16x32_bf16 v[32:35], v[186:189], v[202:205], v[32:35]
	v_mfma_f32_16x16x32_bf16 v[20:23], v[178:181], v[214:217], v[20:23]
	v_mfma_f32_16x16x32_bf16 v[16:19], v[186:189], v[214:217], v[16:19]
	v_mfma_f32_16x16x32_bf16 v[4:7], v[178:181], v[222:225], v[4:7]
	v_mfma_f32_16x16x32_bf16 v[0:3], v[186:189], v[222:225], v[0:3]
	s_nop 0
	s_barrier
	s_add_i32 s21, s21, 2
	s_add_u32 s8, s8, 0x100
	s_addc_u32 s9, s9, 0
	s_add_u32 s19, s19, 0x100
	s_addc_u32 s20, s20, 0
	s_cmp_gt_u32 s21, 13
	s_cbranch_scc0 .LBB0_157
	s_and_b64 vcc, exec, s[60:61]
	s_cbranch_vccz .LBB0_160
	s_barrier

; #define STAGE(bufoff, gbase) STAGE_(bufoff, gbase, voffA)
; #define STAGEB(bufoff, gbase) STAGE_(bufoff, gbase, voffB)
; #define LDA(dst, b, h) do { _Pragma("unroll") for (int m = 0; m < 4; ++m) _Pragma("unroll") for (int k = 0; k < 2; ++k) dst[m][k] = *LDSP(const bf16x8, lds + SA(b, h) + aoff + m * 2048 + k * 1024); } while (0)
; #define LDB(dst, b, h) do { _Pragma("unroll") for (int n = 0; n < 2; ++n) _Pragma("unroll") for (int k = 0; k < 2; ++k) dst[n][k] = *LDSP(const bf16x8, lds + SB(b, h) + boff + n * 2048 + k * 1024); } while (0)
; #define MMA(ai, bj, AT, BT) do { __builtin_amdgcn_s_setprio(1); \
;     _Pragma("unroll") for (int m = 0; m < 4; ++m) _Pragma("unroll") for (int n = 0; n < 2; ++n) _Pragma("unroll") for (int k = 0; k < 2; ++k) \
;       acc[ai][bj][m][n] = __builtin_amdgcn_mfma_f32_16x16x32_bf16(BT[n][k], AT[m][k], acc[ai][bj][m][n], 0, 0, 0); \
;     __builtin_amdgcn_s_setprio(0); } while (0)
; #define WAIT_V(n) asm volatile("s_waitcnt vmcnt(" #n ")" ::: "memory")
; #define WAIT_L(n) asm volatile("s_waitcnt lgkmcnt(" #n ")" ::: "memory")
; #define BAR __builtin_amdgcn_s_barrier()
; #define SCHED __builtin_amdgcn_sched_barrier(0)
; #define WAIT_V(n) asm volatile("s_waitcnt vmcnt(" #n ")" ::: "memory")
; #define BAR do { __builtin_amdgcn_sched_barrier(0); __builtin_amdgcn_s_barrier(); asm volatile("" ::: "memory"); __builtin_amdgcn_sched_barrier(0); } while (0)
; template <bool SP2, bool ALIGN_EPI, bool DUAL, class Epi> DI void gemm_phase2(const bf16_t* A, const bf16_t* Bt, const bf16_t* A2, const bf16_t* Bt2, int M, int N, int K, const Epi& E, lds_t* lds) {
;     ...
;     for (int t = 0; t < nt; t += 2) {
;       const bool last = (t == nt - 2);
;       const char* a1 = cA + (size_t)(t + 1) * kstep;
;       const char* a2 = last ? nA : cA + (size_t)(t + 2) * kstep; const char* b2 = last ? nB : cB + (size_t)(t + 2) * kstep;
;       const char* a3 = a2 + kstep; const char* b3 = b2 + kstep;
;       if constexpr (SP2) {
;         LDB(B0, 0, 0); LDB(B1, 0, 1); SCHED; LDA(At, 0, 0); STAGE(SA(1, 1), a1 + hstep);
;         WAIT_V(8); WAIT_L(0); BAR; MMA(0, 0, At, B0); MMA(0, 1, At, B1); BAR; SCHED;
;         LDA(At, 0, 1); STAGEB(SB(0, 0), b2); STAGEB(SB(0, 1), b2 + bstep); STAGE(SA(0, 0), a2);
;         WAIT_V(8); WAIT_L(0); BAR; MMA(1, 0, At, B0); MMA(1, 1, At, B1); BAR; SCHED;
.LBB0_341:
	ds_read_b128 v[148:151], v145
	ds_read_b128 v[156:159], v145 offset:1024
	ds_read_b128 v[160:163], v145 offset:2048
	ds_read_b128 v[164:167], v145 offset:3072
	ds_read_b128 v[168:171], v146
	ds_read_b128 v[172:175], v146 offset:1024
	ds_read_b128 v[176:179], v146 offset:2048
	ds_read_b128 v[180:183], v146 offset:3072
	s_add_u32 s52, s68, 0xfffc0080
	s_addc_u32 s53, s69, -1
	s_cmp_eq_u32 s35, 12
	s_cselect_b32 s89, s0, s53
	s_cselect_b32 s88, s1, s52
	s_cselect_b32 s87, s11, s34
	s_cselect_b32 s86, s23, s33
	v_lshl_add_u64 v[152:153], s[68:69], 0, v[136:137]
	s_add_i32 m0, s3, 0xc000
	ds_read_b128 v[184:187], v147
	ds_read_b128 v[188:191], v147 offset:1024
	ds_read_b128 v[192:195], v147 offset:2048
	ds_read_b128 v[196:199], v147 offset:3072
	ds_read_b128 v[200:203], v147 offset:4096
	ds_read_b128 v[204:207], v147 offset:5120
	ds_read_b128 v[208:211], v147 offset:6144
	ds_read_b128 v[214:217], v147 offset:7168
	global_load_lds_dwordx4 v[152:153], off
	v_lshl_add_u64 v[152:153], s[68:69], 0, v[138:139]
	s_add_i32 m0, s3, 0xe000
	s_nop 0
	global_load_lds_dwordx4 v[152:153], off
	s_waitcnt vmcnt(8)
	s_waitcnt lgkmcnt(0)
	s_barrier
	s_nop 0
	s_waitcnt lgkmcnt(0)
	v_mfma_f32_16x16x32_bf16 v[124:127], v[148:151], v[184:187], v[124:127]
	v_mfma_f32_16x16x32_bf16 v[120:123], v[160:163], v[184:187], v[120:123]
	v_mfma_f32_16x16x32_bf16 v[108:111], v[148:151], v[192:195], v[108:111]
	v_mfma_f32_16x16x32_bf16 v[104:107], v[160:163], v[192:195], v[104:107]
	v_mfma_f32_16x16x32_bf16 v[92:95], v[148:151], v[200:203], v[92:95]
	v_mfma_f32_16x16x32_bf16 v[88:91], v[160:163], v[200:203], v[88:91]
	v_mfma_f32_16x16x32_bf16 v[76:79], v[148:151], v[208:211], v[76:79]
	v_mfma_f32_16x16x32_bf16 v[72:75], v[160:163], v[208:211], v[72:75]
	v_mfma_f32_16x16x32_bf16 v[124:127], v[156:159], v[188:191], v[124:127]
	v_mfma_f32_16x16x32_bf16 v[120:123], v[164:167], v[188:191], v[120:123]
	v_mfma_f32_16x16x32_bf16 v[108:111], v[156:159], v[196:199], v[108:111]
	v_mfma_f32_16x16x32_bf16 v[104:107], v[164:167], v[196:199], v[104:107]
	v_mfma_f32_16x16x32_bf16 v[92:95], v[156:159], v[204:207], v[92:95]
	v_mfma_f32_16x16x32_bf16 v[88:91], v[164:167], v[204:207], v[88:91]
	v_mfma_f32_16x16x32_bf16 v[76:79], v[156:159], v[214:217], v[76:79]
	v_mfma_f32_16x16x32_bf16 v[72:75], v[164:167], v[214:217], v[72:75]
	s_nop 0
	s_nop 0
	v_mfma_f32_16x16x32_bf16 v[116:119], v[168:171], v[184:187], v[116:119]
	v_mfma_f32_16x16x32_bf16 v[112:115], v[176:179], v[184:187], v[112:115]
	v_mfma_f32_16x16x32_bf16 v[100:103], v[168:171], v[192:195], v[100:103]
	v_mfma_f32_16x16x32_bf16 v[96:99], v[176:179], v[192:195], v[96:99]
	v_mfma_f32_16x16x32_bf16 v[84:87], v[168:171], v[200:203], v[84:87]
	v_mfma_f32_16x16x32_bf16 v[80:83], v[176:179], v[200:203], v[80:83]
	v_mfma_f32_16x16x32_bf16 v[68:71], v[168:171], v[208:211], v[68:71]
	v_mfma_f32_16x16x32_bf16 v[64:67], v[176:179], v[208:211], v[64:67]
	v_mfma_f32_16x16x32_bf16 v[116:119], v[172:175], v[188:191], v[116:119]
	v_mfma_f32_16x16x32_bf16 v[112:115], v[180:183], v[188:191], v[112:115]
	v_mfma_f32_16x16x32_bf16 v[100:103], v[172:175], v[196:199], v[100:103]
	v_mfma_f32_16x16x32_bf16 v[96:99], v[180:183], v[196:199], v[96:99]
	v_mfma_f32_16x16x32_bf16 v[84:87], v[172:175], v[204:207], v[84:87]
	v_mfma_f32_16x16x32_bf16 v[80:83], v[180:183], v[204:207], v[80:83]
	v_mfma_f32_16x16x32_bf16 v[68:71], v[172:175], v[214:217], v[68:71]
	v_mfma_f32_16x16x32_bf16 v[64:67], v[180:183], v[214:217], v[64:67]
	s_nop 0
	s_barrier
	s_add_i32 s52, s19, s2
	v_lshl_add_u64 v[152:153], s[86:87], 0, v[130:131]
	s_mov_b32 m0, s52
	ds_read_b128 v[184:187], v147 offset:16384
	ds_read_b128 v[188:191], v147 offset:17408
	ds_read_b128 v[192:195], v147 offset:18432
	ds_read_b128 v[196:199], v147 offset:19456
	ds_read_b128 v[200:203], v147 offset:20480
	ds_read_b128 v[204:207], v147 offset:21504
	ds_read_b128 v[208:211], v147 offset:22528
	ds_read_b128 v[214:217], v147 offset:23552
	global_load_lds_dwordx4 v[152:153], off
	s_add_i32 m0, s52, 0x2000
	s_add_u32 s52, s86, 0x10000
	v_lshl_add_u64 v[218:219], s[86:87], 0, v[134:135]
	s_addc_u32 s53, s87, 0
	s_add_i32 s61, s20, s2
	global_load_lds_dwordx4 v[218:219], off
	v_lshl_add_u64 v[220:221], s[52:53], 0, v[130:131]
	s_mov_b32 m0, s61
	v_lshl_add_u64 v[222:223], s[88:89], 0, v[132:133]
	global_load_lds_dwordx4 v[220:221], off
	v_lshl_add_u64 v[220:221], s[52:53], 0, v[134:135]
	s_add_i32 m0, s61, 0x2000
	s_nop 0
	global_load_lds_dwordx4 v[220:221], off
	v_lshl_add_u64 v[220:221], s[88:89], 0, v[128:129]
	s_mov_b32 m0, s3
	s_nop 0
	global_load_lds_dwordx4 v[220:221], off
	s_mov_b32 m0, s12
	s_nop 0
	global_load_lds_dwordx4 v[222:223], off
	s_waitcnt vmcnt(8)
	s_waitcnt lgkmcnt(0)
	s_barrier
; #define STAGE(bufoff, gbase) STAGE_(bufoff, gbase, voffA)
; #define LDA(dst, b, h) do { _Pragma("unroll") for (int m = 0; m < 4; ++m) _Pragma("unroll") for (int k = 0; k < 2; ++k) dst[m][k] = *LDSP(const bf16x8, lds + SA(b, h) + aoff + m * 2048 + k * 1024); } while (0)
; #define LDB(dst, b, h) do { _Pragma("unroll") for (int n = 0; n < 2; ++n) _Pragma("unroll") for (int k = 0; k < 2; ++k) dst[n][k] = *LDSP(const bf16x8, lds + SB(b, h) + boff + n * 2048 + k * 1024); } while (0)
; #define MMA(ai, bj, AT, BT) do { __builtin_amdgcn_s_setprio(1); \
;     _Pragma("unroll") for (int m = 0; m < 4; ++m) _Pragma("unroll") for (int n = 0; n < 2; ++n) _Pragma("unroll") for (int k = 0; k < 2; ++k) \
;       acc[ai][bj][m][n] = __builtin_amdgcn_mfma_f32_16x16x32_bf16(BT[n][k], AT[m][k], acc[ai][bj][m][n], 0, 0, 0); \
;     __builtin_amdgcn_s_setprio(0); } while (0)
; #define WAIT_V(n) asm volatile("s_waitcnt vmcnt(" #n ")" ::: "memory")
; #define WAIT_L(n) asm volatile("s_waitcnt lgkmcnt(" #n ")" ::: "memory")
; #define BAR __builtin_amdgcn_s_barrier()
; #define SCHED __builtin_amdgcn_sched_barrier(0)
; #define WAIT_V(n) asm volatile("s_waitcnt vmcnt(" #n ")" ::: "memory")
; #define BAR do { __builtin_amdgcn_sched_barrier(0); __builtin_amdgcn_s_barrier(); asm volatile("" ::: "memory"); __builtin_amdgcn_sched_barrier(0); } while (0)
; template <bool SP2, bool ALIGN_EPI, bool DUAL, class Epi> DI void gemm_phase2(const bf16_t* A, const bf16_t* Bt, const bf16_t* A2, const bf16_t* Bt2, int M, int N, int K, const Epi& E, lds_t* lds) {
;     ...
;         WAIT_V(8); WAIT_L(0); BAR; MMA(1, 0, At, B0); MMA(1, 1, At, B1); BAR; SCHED;
;         LDB(B0, 1, 0); LDB(B1, 1, 1); SCHED; LDA(At, 1, 0); STAGE(SA(0, 1), a2 + hstep);
;         WAIT_V(8); WAIT_L(0); BAR; MMA(0, 0, At, B0); MMA(0, 1, At, B1); BAR; SCHED;
	s_nop 0
	s_waitcnt lgkmcnt(0)
	v_mfma_f32_16x16x32_bf16 v[60:63], v[148:151], v[184:187], v[60:63]
	v_mfma_f32_16x16x32_bf16 v[56:59], v[160:163], v[184:187], v[56:59]
	v_mfma_f32_16x16x32_bf16 v[44:47], v[148:151], v[192:195], v[44:47]
	v_mfma_f32_16x16x32_bf16 v[40:43], v[160:163], v[192:195], v[40:43]
	v_mfma_f32_16x16x32_bf16 v[28:31], v[148:151], v[200:203], v[28:31]
	v_mfma_f32_16x16x32_bf16 v[24:27], v[160:163], v[200:203], v[24:27]
	v_mfma_f32_16x16x32_bf16 v[12:15], v[148:151], v[208:211], v[12:15]
	v_mfma_f32_16x16x32_bf16 v[8:11], v[160:163], v[208:211], v[8:11]
	v_mfma_f32_16x16x32_bf16 v[60:63], v[156:159], v[188:191], v[60:63]
	v_mfma_f32_16x16x32_bf16 v[56:59], v[164:167], v[188:191], v[56:59]
	v_mfma_f32_16x16x32_bf16 v[44:47], v[156:159], v[196:199], v[44:47]
	v_mfma_f32_16x16x32_bf16 v[40:43], v[164:167], v[196:199], v[40:43]
	v_mfma_f32_16x16x32_bf16 v[28:31], v[156:159], v[204:207], v[28:31]
	v_mfma_f32_16x16x32_bf16 v[24:27], v[164:167], v[204:207], v[24:27]
	v_mfma_f32_16x16x32_bf16 v[12:15], v[156:159], v[214:217], v[12:15]
	v_mfma_f32_16x16x32_bf16 v[8:11], v[164:167], v[214:217], v[8:11]
	s_nop 0
	s_nop 0
	v_mfma_f32_16x16x32_bf16 v[52:55], v[168:171], v[184:187], v[52:55]
	v_mfma_f32_16x16x32_bf16 v[48:51], v[176:179], v[184:187], v[48:51]
	v_mfma_f32_16x16x32_bf16 v[36:39], v[168:171], v[192:195], v[36:39]
	v_mfma_f32_16x16x32_bf16 v[32:35], v[176:179], v[192:195], v[32:35]
	v_mfma_f32_16x16x32_bf16 v[20:23], v[168:171], v[200:203], v[20:23]
	v_mfma_f32_16x16x32_bf16 v[16:19], v[176:179], v[200:203], v[16:19]
	v_mfma_f32_16x16x32_bf16 v[4:7], v[168:171], v[208:211], v[4:7]
	v_mfma_f32_16x16x32_bf16 v[0:3], v[176:179], v[208:211], v[0:3]
	v_mfma_f32_16x16x32_bf16 v[52:55], v[172:175], v[188:191], v[52:55]
	v_mfma_f32_16x16x32_bf16 v[48:51], v[180:183], v[188:191], v[48:51]
	v_mfma_f32_16x16x32_bf16 v[36:39], v[172:175], v[196:199], v[36:39]
	v_mfma_f32_16x16x32_bf16 v[32:35], v[180:183], v[196:199], v[32:35]
	v_mfma_f32_16x16x32_bf16 v[20:23], v[172:175], v[204:207], v[20:23]
	v_mfma_f32_16x16x32_bf16 v[16:19], v[180:183], v[204:207], v[16:19]
	v_mfma_f32_16x16x32_bf16 v[4:7], v[172:175], v[214:217], v[4:7]
	v_mfma_f32_16x16x32_bf16 v[0:3], v[180:183], v[214:217], v[0:3]
	s_nop 0
	s_barrier
	s_add_i32 s61, 0, 0x18000
	v_add_u32_e32 v155, s61, v140
	s_add_i32 s65, 0, 0x1c000
	ds_read_b128 v[148:151], v155
	ds_read_b128 v[156:159], v155 offset:1024
	ds_read_b128 v[160:163], v155 offset:2048
	ds_read_b128 v[164:167], v155 offset:3072
	v_add_u32_e32 v155, s65, v140
	ds_read_b128 v[168:171], v155
	ds_read_b128 v[172:175], v155 offset:1024
	ds_read_b128 v[176:179], v155 offset:2048
	ds_read_b128 v[180:183], v155 offset:3072
	s_add_u32 s52, s88, 0x40000
	s_addc_u32 s53, s89, 0
	s_mov_b32 m0, s13
	v_lshl_add_u64 v[224:225], s[52:53], 0, v[128:129]
	ds_read_b128 v[184:187], v147 offset:32768
	ds_read_b128 v[188:191], v147 offset:33792
	ds_read_b128 v[192:195], v147 offset:34816
	ds_read_b128 v[196:199], v147 offset:35840
	ds_read_b128 v[200:203], v147 offset:36864
	ds_read_b128 v[204:207], v147 offset:37888
	ds_read_b128 v[208:211], v147 offset:38912
	ds_read_b128 v[214:217], v147 offset:39936
	global_load_lds_dwordx4 v[224:225], off
	v_lshl_add_u64 v[224:225], s[52:53], 0, v[132:133]
	s_mov_b32 m0, s14
	s_nop 0
	global_load_lds_dwordx4 v[224:225], off
	s_waitcnt vmcnt(8)
	s_waitcnt lgkmcnt(0)
	s_barrier
	s_nop 0
	s_waitcnt lgkmcnt(0)
	v_mfma_f32_16x16x32_bf16 v[124:127], v[148:151], v[184:187], v[124:127]
	v_mfma_f32_16x16x32_bf16 v[120:123], v[160:163], v[184:187], v[120:123]
	v_mfma_f32_16x16x32_bf16 v[108:111], v[148:151], v[192:195], v[108:111]
	v_mfma_f32_16x16x32_bf16 v[104:107], v[160:163], v[192:195], v[104:107]
	v_mfma_f32_16x16x32_bf16 v[92:95], v[148:151], v[200:203], v[92:95]
	v_mfma_f32_16x16x32_bf16 v[88:91], v[160:163], v[200:203], v[88:91]
	v_mfma_f32_16x16x32_bf16 v[76:79], v[148:151], v[208:211], v[76:79]
	v_mfma_f32_16x16x32_bf16 v[72:75], v[160:163], v[208:211], v[72:75]
	v_mfma_f32_16x16x32_bf16 v[124:127], v[156:159], v[188:191], v[124:127]
	v_mfma_f32_16x16x32_bf16 v[120:123], v[164:167], v[188:191], v[120:123]
	v_mfma_f32_16x16x32_bf16 v[108:111], v[156:159], v[196:199], v[108:111]
	v_mfma_f32_16x16x32_bf16 v[104:107], v[164:167], v[196:199], v[104:107]
	v_mfma_f32_16x16x32_bf16 v[92:95], v[156:159], v[204:207], v[92:95]
	v_mfma_f32_16x16x32_bf16 v[88:91], v[164:167], v[204:207], v[88:91]
	v_mfma_f32_16x16x32_bf16 v[76:79], v[156:159], v[214:217], v[76:79]
	v_mfma_f32_16x16x32_bf16 v[72:75], v[164:167], v[214:217], v[72:75]
	s_nop 0
	s_nop 0
	v_mfma_f32_16x16x32_bf16 v[116:119], v[168:171], v[184:187], v[116:119]
	v_mfma_f32_16x16x32_bf16 v[112:115], v[176:179], v[184:187], v[112:115]
	v_mfma_f32_16x16x32_bf16 v[100:103], v[168:171], v[192:195], v[100:103]
	v_mfma_f32_16x16x32_bf16 v[96:99], v[176:179], v[192:195], v[96:99]
	v_mfma_f32_16x16x32_bf16 v[84:87], v[168:171], v[200:203], v[84:87]
	v_mfma_f32_16x16x32_bf16 v[80:83], v[176:179], v[200:203], v[80:83]
	v_mfma_f32_16x16x32_bf16 v[68:71], v[168:171], v[208:211], v[68:71]
	v_mfma_f32_16x16x32_bf16 v[64:67], v[176:179], v[208:211], v[64:67]
	v_mfma_f32_16x16x32_bf16 v[116:119], v[172:175], v[188:191], v[116:119]
	v_mfma_f32_16x16x32_bf16 v[112:115], v[180:183], v[188:191], v[112:115]
	v_mfma_f32_16x16x32_bf16 v[100:103], v[172:175], v[196:199], v[100:103]
	v_mfma_f32_16x16x32_bf16 v[96:99], v[180:183], v[196:199], v[96:99]
	v_mfma_f32_16x16x32_bf16 v[84:87], v[172:175], v[204:207], v[84:87]
	v_mfma_f32_16x16x32_bf16 v[80:83], v[180:183], v[204:207], v[80:83]
	v_mfma_f32_16x16x32_bf16 v[68:71], v[172:175], v[214:217], v[68:71]
	v_mfma_f32_16x16x32_bf16 v[64:67], v[180:183], v[214:217], v[64:67]
	s_nop 0
	s_barrier
; #define STAGE(bufoff, gbase) STAGE_(bufoff, gbase, voffA)
; #define STAGEB(bufoff, gbase) STAGE_(bufoff, gbase, voffB)
; #define LDA(dst, b, h) do { _Pragma("unroll") for (int m = 0; m < 4; ++m) _Pragma("unroll") for (int k = 0; k < 2; ++k) dst[m][k] = *LDSP(const bf16x8, lds + SA(b, h) + aoff + m * 2048 + k * 1024); } while (0)
; #define MMA(ai, bj, AT, BT) do { __builtin_amdgcn_s_setprio(1); \
;     _Pragma("unroll") for (int m = 0; m < 4; ++m) _Pragma("unroll") for (int n = 0; n < 2; ++n) _Pragma("unroll") for (int k = 0; k < 2; ++k) \
;       acc[ai][bj][m][n] = __builtin_amdgcn_mfma_f32_16x16x32_bf16(BT[n][k], AT[m][k], acc[ai][bj][m][n], 0, 0, 0); \
;     __builtin_amdgcn_s_setprio(0); } while (0)
; #define WAIT_V(n) asm volatile("s_waitcnt vmcnt(" #n ")" ::: "memory")
; #define WAIT_L(n) asm volatile("s_waitcnt lgkmcnt(" #n ")" ::: "memory")
; #define BAR __builtin_amdgcn_s_barrier()
; #define SCHED __builtin_amdgcn_sched_barrier(0)
; #define WAIT_V(n) asm volatile("s_waitcnt vmcnt(" #n ")" ::: "memory")
; #define BAR do { __builtin_amdgcn_sched_barrier(0); __builtin_amdgcn_s_barrier(); asm volatile("" ::: "memory"); __builtin_amdgcn_sched_barrier(0); } while (0)
; template <bool SP2, bool ALIGN_EPI, bool DUAL, class Epi> DI void gemm_phase2(const bf16_t* A, const bf16_t* Bt, const bf16_t* A2, const bf16_t* Bt2, int M, int N, int K, const Epi& E, lds_t* lds) {
;     ...
;     for (int t = 0; t < nt; t += 2) {
;       const bool last = (t == nt - 2);
;       const char* a1 = cA + (size_t)(t + 1) * kstep;
;       const char* a2 = last ? nA : cA + (size_t)(t + 2) * kstep; const char* b2 = last ? nB : cB + (size_t)(t + 2) * kstep;
;       const char* a3 = a2 + kstep; const char* b3 = b2 + kstep;
;     ...
;         LDA(At, 1, 1); STAGEB(SB(1, 0), b3); STAGEB(SB(1, 1), b3 + bstep); STAGE(SA(1, 0), a3);
;         WAIT_V(8); WAIT_L(0); BAR; MMA(1, 0, At, B0); MMA(1, 1, At, B1); BAR; SCHED;
	s_add_i32 s52, s61, s2
	v_lshl_add_u64 v[152:153], v[152:153], 0, s[8:9]
	s_mov_b32 m0, s52
	ds_read_b128 v[184:187], v147 offset:49152
	ds_read_b128 v[188:191], v147 offset:50176
	ds_read_b128 v[192:195], v147 offset:51200
	ds_read_b128 v[196:199], v147 offset:52224
	ds_read_b128 v[200:203], v147 offset:53248
	ds_read_b128 v[204:207], v147 offset:54272
	ds_read_b128 v[208:211], v147 offset:55296
	ds_read_b128 v[214:217], v147 offset:56320
	global_load_lds_dwordx4 v[152:153], off
	s_add_i32 m0, s52, 0x2000
	s_add_u32 s52, s86, 0x10080
	v_lshl_add_u64 v[152:153], v[218:219], 0, s[8:9]
	s_addc_u32 s53, s87, 0
	s_add_i32 s61, s65, s2
	global_load_lds_dwordx4 v[152:153], off
	v_lshl_add_u64 v[152:153], s[52:53], 0, v[130:131]
	s_mov_b32 m0, s61
	s_nop 0
	global_load_lds_dwordx4 v[152:153], off
	v_lshl_add_u64 v[152:153], s[52:53], 0, v[134:135]
	s_add_i32 m0, s61, 0x2000
	s_nop 0
	global_load_lds_dwordx4 v[152:153], off
	v_lshl_add_u64 v[152:153], v[220:221], 0, s[8:9]
	s_mov_b32 m0, s15
	s_nop 0
	global_load_lds_dwordx4 v[152:153], off
	v_lshl_add_u64 v[152:153], v[222:223], 0, s[8:9]
	s_mov_b32 m0, s18
	s_nop 0
	global_load_lds_dwordx4 v[152:153], off
	s_waitcnt vmcnt(8)
	s_waitcnt lgkmcnt(0)
	s_barrier
	s_nop 0
	s_waitcnt lgkmcnt(0)
	v_mfma_f32_16x16x32_bf16 v[60:63], v[148:151], v[184:187], v[60:63]
	v_mfma_f32_16x16x32_bf16 v[56:59], v[160:163], v[184:187], v[56:59]
	v_mfma_f32_16x16x32_bf16 v[44:47], v[148:151], v[192:195], v[44:47]
	v_mfma_f32_16x16x32_bf16 v[40:43], v[160:163], v[192:195], v[40:43]
	v_mfma_f32_16x16x32_bf16 v[28:31], v[148:151], v[200:203], v[28:31]
	v_mfma_f32_16x16x32_bf16 v[24:27], v[160:163], v[200:203], v[24:27]
	v_mfma_f32_16x16x32_bf16 v[12:15], v[148:151], v[208:211], v[12:15]
	v_mfma_f32_16x16x32_bf16 v[8:11], v[160:163], v[208:211], v[8:11]
	v_mfma_f32_16x16x32_bf16 v[60:63], v[156:159], v[188:191], v[60:63]
	v_mfma_f32_16x16x32_bf16 v[56:59], v[164:167], v[188:191], v[56:59]
	v_mfma_f32_16x16x32_bf16 v[44:47], v[156:159], v[196:199], v[44:47]
	v_mfma_f32_16x16x32_bf16 v[40:43], v[164:167], v[196:199], v[40:43]
	v_mfma_f32_16x16x32_bf16 v[28:31], v[156:159], v[204:207], v[28:31]
	v_mfma_f32_16x16x32_bf16 v[24:27], v[164:167], v[204:207], v[24:27]
	v_mfma_f32_16x16x32_bf16 v[12:15], v[156:159], v[214:217], v[12:15]
	v_mfma_f32_16x16x32_bf16 v[8:11], v[164:167], v[214:217], v[8:11]
	s_nop 0
	s_nop 0
	v_mfma_f32_16x16x32_bf16 v[52:55], v[168:171], v[184:187], v[52:55]
	v_mfma_f32_16x16x32_bf16 v[48:51], v[176:179], v[184:187], v[48:51]
	v_mfma_f32_16x16x32_bf16 v[36:39], v[168:171], v[192:195], v[36:39]
	v_mfma_f32_16x16x32_bf16 v[32:35], v[176:179], v[192:195], v[32:35]
	v_mfma_f32_16x16x32_bf16 v[20:23], v[168:171], v[200:203], v[20:23]
	v_mfma_f32_16x16x32_bf16 v[16:19], v[176:179], v[200:203], v[16:19]
	v_mfma_f32_16x16x32_bf16 v[4:7], v[168:171], v[208:211], v[4:7]
	v_mfma_f32_16x16x32_bf16 v[0:3], v[176:179], v[208:211], v[0:3]
	v_mfma_f32_16x16x32_bf16 v[52:55], v[172:175], v[188:191], v[52:55]
	v_mfma_f32_16x16x32_bf16 v[48:51], v[180:183], v[188:191], v[48:51]
	v_mfma_f32_16x16x32_bf16 v[36:39], v[172:175], v[196:199], v[36:39]
	v_mfma_f32_16x16x32_bf16 v[32:35], v[180:183], v[196:199], v[32:35]
	v_mfma_f32_16x16x32_bf16 v[20:23], v[172:175], v[204:207], v[20:23]
	v_mfma_f32_16x16x32_bf16 v[16:19], v[180:183], v[204:207], v[16:19]
	v_mfma_f32_16x16x32_bf16 v[4:7], v[172:175], v[214:217], v[4:7]
	v_mfma_f32_16x16x32_bf16 v[0:3], v[180:183], v[214:217], v[0:3]
	s_nop 0
	s_barrier
	s_add_i32 s35, s35, 2
	s_add_u32 s68, s68, 0x100
	s_addc_u32 s69, s69, 0
	s_add_u32 s33, s33, 0x100
	s_addc_u32 s34, s34, 0
	s_cmp_gt_u32 s35, 13
	s_cbranch_scc0 .LBB0_341
	s_and_b64 vcc, exec, s[54:55]
	s_cbranch_vccz .LBB0_344
	s_barrier

; #define STAGE(bufoff, gbase) STAGE_(bufoff, gbase, voffA)
; #define STAGEB(bufoff, gbase) STAGE_(bufoff, gbase, voffB)
; #define LDA(dst, b, h) do { _Pragma("unroll") for (int m = 0; m < 4; ++m) _Pragma("unroll") for (int k = 0; k < 2; ++k) dst[m][k] = *LDSP(const bf16x8, lds + SA(b, h) + aoff + m * 2048 + k * 1024); } while (0)
; #define LDB(dst, b, h) do { _Pragma("unroll") for (int n = 0; n < 2; ++n) _Pragma("unroll") for (int k = 0; k < 2; ++k) dst[n][k] = *LDSP(const bf16x8, lds + SB(b, h) + boff + n * 2048 + k * 1024); } while (0)
; #define MMA(ai, bj, AT, BT) do { __builtin_amdgcn_s_setprio(1); \
;     _Pragma("unroll") for (int m = 0; m < 4; ++m) _Pragma("unroll") for (int n = 0; n < 2; ++n) _Pragma("unroll") for (int k = 0; k < 2; ++k) \
;       acc[ai][bj][m][n] = __builtin_amdgcn_mfma_f32_16x16x32_bf16(BT[n][k], AT[m][k], acc[ai][bj][m][n], 0, 0, 0); \
;     __builtin_amdgcn_s_setprio(0); } while (0)
; #define WAIT_V(n) asm volatile("s_waitcnt vmcnt(" #n ")" ::: "memory")
; #define WAIT_L(n) asm volatile("s_waitcnt lgkmcnt(" #n ")" ::: "memory")
; #define BAR __builtin_amdgcn_s_barrier()
; #define SCHED __builtin_amdgcn_sched_barrier(0)
; #define WAIT_V(n) asm volatile("s_waitcnt vmcnt(" #n ")" ::: "memory")
; #define BAR do { __builtin_amdgcn_sched_barrier(0); __builtin_amdgcn_s_barrier(); asm volatile("" ::: "memory"); __builtin_amdgcn_sched_barrier(0); } while (0)
; template <bool SP2, bool ALIGN_EPI, bool DUAL, class Epi> DI void gemm_phase2(const bf16_t* A, const bf16_t* Bt, const bf16_t* A2, const bf16_t* Bt2, int M, int N, int K, const Epi& E, lds_t* lds) {
;     ...
;     for (int t = 0; t < nt; t += 2) {
;       const bool last = (t == nt - 2);
;       const char* a1 = cA + (size_t)(t + 1) * kstep;
;       const char* a2 = last ? nA : cA + (size_t)(t + 2) * kstep; const char* b2 = last ? nB : cB + (size_t)(t + 2) * kstep;
;       const char* a3 = a2 + kstep; const char* b3 = b2 + kstep;
;       if constexpr (SP2) {
;         LDB(B0, 0, 0); LDB(B1, 0, 1); SCHED; LDA(At, 0, 0); STAGE(SA(1, 1), a1 + hstep);
;         WAIT_V(8); WAIT_L(0); BAR; MMA(0, 0, At, B0); MMA(0, 1, At, B1); BAR; SCHED;
;         LDA(At, 0, 1); STAGEB(SB(0, 0), b2); STAGEB(SB(0, 1), b2 + bstep); STAGE(SA(0, 0), a2);
;         WAIT_V(8); WAIT_L(0); BAR; MMA(1, 0, At, B0); MMA(1, 1, At, B1); BAR; SCHED;
.LBB0_482:
	v_add_u32_e32 v151, s20, v141
	ds_read_b128 v[152:155], v151
	ds_read_b128 v[156:159], v151 offset:1024
	ds_read_b128 v[160:163], v151 offset:2048
	ds_read_b128 v[164:167], v151 offset:3072
	v_add_u32_e32 v151, s21, v141
	ds_read_b128 v[168:171], v151
	ds_read_b128 v[172:175], v151 offset:1024
	ds_read_b128 v[176:179], v151 offset:2048
	ds_read_b128 v[180:183], v151 offset:3072
	s_add_u32 s41, s60, 0xfffc0080
	s_addc_u32 s59, s61, -1
	s_cmp_eq_u32 s37, 12
	s_cselect_b32 s65, s2, s59
	s_cselect_b32 s64, s3, s41
	s_cselect_b32 s63, s0, s35
	s_cselect_b32 s62, s1, s34
	v_lshl_add_u64 v[220:221], s[60:61], 0, v[136:137]
	s_add_i32 m0, s9, 0xc000
	ds_read_b128 v[184:187], v149
	ds_read_b128 v[188:191], v149 offset:1024
	ds_read_b128 v[192:195], v149 offset:2048
	ds_read_b128 v[196:199], v149 offset:3072
	ds_read_b128 v[200:203], v149 offset:4096
	ds_read_b128 v[204:207], v149 offset:5120
	ds_read_b128 v[208:211], v149 offset:6144
	ds_read_b128 v[216:219], v149 offset:7168
	global_load_lds_dwordx4 v[220:221], off
	v_lshl_add_u64 v[220:221], s[60:61], 0, v[138:139]
	s_add_i32 m0, s9, 0xe000
	s_nop 0
	global_load_lds_dwordx4 v[220:221], off
	s_waitcnt vmcnt(8)
	s_waitcnt lgkmcnt(0)
	s_barrier
	s_nop 0
	s_waitcnt lgkmcnt(0)
	v_mfma_f32_16x16x32_bf16 v[124:127], v[152:155], v[184:187], v[124:127]
	v_mfma_f32_16x16x32_bf16 v[120:123], v[160:163], v[184:187], v[120:123]
	v_mfma_f32_16x16x32_bf16 v[116:119], v[152:155], v[192:195], v[116:119]
	v_mfma_f32_16x16x32_bf16 v[112:115], v[160:163], v[192:195], v[112:115]
	v_mfma_f32_16x16x32_bf16 v[108:111], v[152:155], v[200:203], v[108:111]
	v_mfma_f32_16x16x32_bf16 v[104:107], v[160:163], v[200:203], v[104:107]
	v_mfma_f32_16x16x32_bf16 v[100:103], v[152:155], v[208:211], v[100:103]
	v_mfma_f32_16x16x32_bf16 v[96:99], v[160:163], v[208:211], v[96:99]
	v_mfma_f32_16x16x32_bf16 v[124:127], v[156:159], v[188:191], v[124:127]
	v_mfma_f32_16x16x32_bf16 v[120:123], v[164:167], v[188:191], v[120:123]
	v_mfma_f32_16x16x32_bf16 v[116:119], v[156:159], v[196:199], v[116:119]
	v_mfma_f32_16x16x32_bf16 v[112:115], v[164:167], v[196:199], v[112:115]
	v_mfma_f32_16x16x32_bf16 v[108:111], v[156:159], v[204:207], v[108:111]
	v_mfma_f32_16x16x32_bf16 v[104:107], v[164:167], v[204:207], v[104:107]
	v_mfma_f32_16x16x32_bf16 v[100:103], v[156:159], v[216:219], v[100:103]
	v_mfma_f32_16x16x32_bf16 v[96:99], v[164:167], v[216:219], v[96:99]
	s_nop 0
	s_nop 0
	v_mfma_f32_16x16x32_bf16 v[92:95], v[168:171], v[184:187], v[92:95]
	v_mfma_f32_16x16x32_bf16 v[88:91], v[176:179], v[184:187], v[88:91]
	v_mfma_f32_16x16x32_bf16 v[84:87], v[168:171], v[192:195], v[84:87]
	v_mfma_f32_16x16x32_bf16 v[80:83], v[176:179], v[192:195], v[80:83]
	v_mfma_f32_16x16x32_bf16 v[76:79], v[168:171], v[200:203], v[76:79]
	v_mfma_f32_16x16x32_bf16 v[72:75], v[176:179], v[200:203], v[72:75]
	v_mfma_f32_16x16x32_bf16 v[68:71], v[168:171], v[208:211], v[68:71]
	v_mfma_f32_16x16x32_bf16 v[64:67], v[176:179], v[208:211], v[64:67]
	v_mfma_f32_16x16x32_bf16 v[92:95], v[172:175], v[188:191], v[92:95]
	v_mfma_f32_16x16x32_bf16 v[88:91], v[180:183], v[188:191], v[88:91]
	v_mfma_f32_16x16x32_bf16 v[84:87], v[172:175], v[196:199], v[84:87]
	v_mfma_f32_16x16x32_bf16 v[80:83], v[180:183], v[196:199], v[80:83]
	v_mfma_f32_16x16x32_bf16 v[76:79], v[172:175], v[204:207], v[76:79]
	v_mfma_f32_16x16x32_bf16 v[72:75], v[180:183], v[204:207], v[72:75]
	v_mfma_f32_16x16x32_bf16 v[68:71], v[172:175], v[216:219], v[68:71]
	v_mfma_f32_16x16x32_bf16 v[64:67], v[180:183], v[216:219], v[64:67]
	s_nop 0
	s_barrier
	s_add_i32 s41, s20, s8
	v_lshl_add_u64 v[220:221], s[62:63], 0, v[130:131]
	s_mov_b32 m0, s41
	ds_read_b128 v[184:187], v149 offset:16384
	ds_read_b128 v[188:191], v149 offset:17408
	ds_read_b128 v[192:195], v149 offset:18432
	ds_read_b128 v[196:199], v149 offset:19456
	ds_read_b128 v[200:203], v149 offset:20480
	ds_read_b128 v[204:207], v149 offset:21504
	ds_read_b128 v[208:211], v149 offset:22528
	ds_read_b128 v[216:219], v149 offset:23552
	global_load_lds_dwordx4 v[220:221], off
	s_add_i32 m0, s41, 0x2000
	s_add_u32 s66, s62, 0x10000
	v_lshl_add_u64 v[222:223], s[62:63], 0, v[134:135]
	s_addc_u32 s67, s63, 0
	s_add_i32 s41, s21, s8
	global_load_lds_dwordx4 v[222:223], off
	v_lshl_add_u64 v[224:225], s[66:67], 0, v[130:131]
	s_mov_b32 m0, s41
	v_lshl_add_u64 v[226:227], s[64:65], 0, v[132:133]
	global_load_lds_dwordx4 v[224:225], off
	v_lshl_add_u64 v[224:225], s[66:67], 0, v[134:135]
	s_add_i32 m0, s41, 0x2000
	s_nop 0
	global_load_lds_dwordx4 v[224:225], off
	v_lshl_add_u64 v[224:225], s[64:65], 0, v[128:129]
	s_mov_b32 m0, s9
	s_nop 0
	global_load_lds_dwordx4 v[224:225], off
	s_mov_b32 m0, s10
	s_nop 0
	global_load_lds_dwordx4 v[226:227], off
	s_waitcnt vmcnt(8)
	s_waitcnt lgkmcnt(0)
	s_barrier
; #define STAGE(bufoff, gbase) STAGE_(bufoff, gbase, voffA)
; #define LDA(dst, b, h) do { _Pragma("unroll") for (int m = 0; m < 4; ++m) _Pragma("unroll") for (int k = 0; k < 2; ++k) dst[m][k] = *LDSP(const bf16x8, lds + SA(b, h) + aoff + m * 2048 + k * 1024); } while (0)
; #define LDB(dst, b, h) do { _Pragma("unroll") for (int n = 0; n < 2; ++n) _Pragma("unroll") for (int k = 0; k < 2; ++k) dst[n][k] = *LDSP(const bf16x8, lds + SB(b, h) + boff + n * 2048 + k * 1024); } while (0)
; #define MMA(ai, bj, AT, BT) do { __builtin_amdgcn_s_setprio(1); \
;     _Pragma("unroll") for (int m = 0; m < 4; ++m) _Pragma("unroll") for (int n = 0; n < 2; ++n) _Pragma("unroll") for (int k = 0; k < 2; ++k) \
;       acc[ai][bj][m][n] = __builtin_amdgcn_mfma_f32_16x16x32_bf16(BT[n][k], AT[m][k], acc[ai][bj][m][n], 0, 0, 0); \
;     __builtin_amdgcn_s_setprio(0); } while (0)
; #define WAIT_V(n) asm volatile("s_waitcnt vmcnt(" #n ")" ::: "memory")
; #define WAIT_L(n) asm volatile("s_waitcnt lgkmcnt(" #n ")" ::: "memory")
; #define BAR __builtin_amdgcn_s_barrier()
; #define SCHED __builtin_amdgcn_sched_barrier(0)
; #define WAIT_V(n) asm volatile("s_waitcnt vmcnt(" #n ")" ::: "memory")
; #define BAR do { __builtin_amdgcn_sched_barrier(0); __builtin_amdgcn_s_barrier(); asm volatile("" ::: "memory"); __builtin_amdgcn_sched_barrier(0); } while (0)
; template <bool SP2, bool ALIGN_EPI, bool DUAL, class Epi> DI void gemm_phase2(const bf16_t* A, const bf16_t* Bt, const bf16_t* A2, const bf16_t* Bt2, int M, int N, int K, const Epi& E, lds_t* lds) {
;     ...
;         WAIT_V(8); WAIT_L(0); BAR; MMA(1, 0, At, B0); MMA(1, 1, At, B1); BAR; SCHED;
;         LDB(B0, 1, 0); LDB(B1, 1, 1); SCHED; LDA(At, 1, 0); STAGE(SA(0, 1), a2 + hstep);
;         WAIT_V(8); WAIT_L(0); BAR; MMA(0, 0, At, B0); MMA(0, 1, At, B1); BAR; SCHED;
	s_nop 0
	s_waitcnt lgkmcnt(0)
	v_mfma_f32_16x16x32_bf16 v[60:63], v[152:155], v[184:187], v[60:63]
	v_mfma_f32_16x16x32_bf16 v[56:59], v[160:163], v[184:187], v[56:59]
	v_mfma_f32_16x16x32_bf16 v[52:55], v[152:155], v[192:195], v[52:55]
	v_mfma_f32_16x16x32_bf16 v[48:51], v[160:163], v[192:195], v[48:51]
	v_mfma_f32_16x16x32_bf16 v[44:47], v[152:155], v[200:203], v[44:47]
	v_mfma_f32_16x16x32_bf16 v[40:43], v[160:163], v[200:203], v[40:43]
	v_mfma_f32_16x16x32_bf16 v[36:39], v[152:155], v[208:211], v[36:39]
	v_mfma_f32_16x16x32_bf16 v[32:35], v[160:163], v[208:211], v[32:35]
	v_mfma_f32_16x16x32_bf16 v[60:63], v[156:159], v[188:191], v[60:63]
	v_mfma_f32_16x16x32_bf16 v[56:59], v[164:167], v[188:191], v[56:59]
	v_mfma_f32_16x16x32_bf16 v[52:55], v[156:159], v[196:199], v[52:55]
	v_mfma_f32_16x16x32_bf16 v[48:51], v[164:167], v[196:199], v[48:51]
	v_mfma_f32_16x16x32_bf16 v[44:47], v[156:159], v[204:207], v[44:47]
	v_mfma_f32_16x16x32_bf16 v[40:43], v[164:167], v[204:207], v[40:43]
	v_mfma_f32_16x16x32_bf16 v[36:39], v[156:159], v[216:219], v[36:39]
	v_mfma_f32_16x16x32_bf16 v[32:35], v[164:167], v[216:219], v[32:35]
	s_nop 0
	s_nop 0
	v_mfma_f32_16x16x32_bf16 v[28:31], v[168:171], v[184:187], v[28:31]
	v_mfma_f32_16x16x32_bf16 v[24:27], v[176:179], v[184:187], v[24:27]
	v_mfma_f32_16x16x32_bf16 v[20:23], v[168:171], v[192:195], v[20:23]
	v_mfma_f32_16x16x32_bf16 v[16:19], v[176:179], v[192:195], v[16:19]
	v_mfma_f32_16x16x32_bf16 v[12:15], v[168:171], v[200:203], v[12:15]
	v_mfma_f32_16x16x32_bf16 v[8:11], v[176:179], v[200:203], v[8:11]
	v_mfma_f32_16x16x32_bf16 v[4:7], v[168:171], v[208:211], v[4:7]
	v_mfma_f32_16x16x32_bf16 v[0:3], v[176:179], v[208:211], v[0:3]
	v_mfma_f32_16x16x32_bf16 v[28:31], v[172:175], v[188:191], v[28:31]
	v_mfma_f32_16x16x32_bf16 v[24:27], v[180:183], v[188:191], v[24:27]
	v_mfma_f32_16x16x32_bf16 v[20:23], v[172:175], v[196:199], v[20:23]
	v_mfma_f32_16x16x32_bf16 v[16:19], v[180:183], v[196:199], v[16:19]
	v_mfma_f32_16x16x32_bf16 v[12:15], v[172:175], v[204:207], v[12:15]
	v_mfma_f32_16x16x32_bf16 v[8:11], v[180:183], v[204:207], v[8:11]
	v_mfma_f32_16x16x32_bf16 v[4:7], v[172:175], v[216:219], v[4:7]
	v_mfma_f32_16x16x32_bf16 v[0:3], v[180:183], v[216:219], v[0:3]
	s_nop 0
	s_barrier
	s_add_i32 s41, 0, 0x18000
	v_add_u32_e32 v151, s41, v141
	s_add_i32 s59, 0, 0x1c000
	ds_read_b128 v[152:155], v151
	ds_read_b128 v[156:159], v151 offset:1024
	ds_read_b128 v[160:163], v151 offset:2048
	ds_read_b128 v[164:167], v151 offset:3072
	v_add_u32_e32 v151, s59, v141
	ds_read_b128 v[168:171], v151
	ds_read_b128 v[172:175], v151 offset:1024
	ds_read_b128 v[176:179], v151 offset:2048
	ds_read_b128 v[180:183], v151 offset:3072
	s_add_u32 s64, s64, 0x40000
	s_addc_u32 s65, s65, 0
	s_mov_b32 m0, s11
	v_lshl_add_u64 v[228:229], s[64:65], 0, v[128:129]
	ds_read_b128 v[184:187], v149 offset:32768
	ds_read_b128 v[188:191], v149 offset:33792
	ds_read_b128 v[192:195], v149 offset:34816
	ds_read_b128 v[196:199], v149 offset:35840
	ds_read_b128 v[200:203], v149 offset:36864
	ds_read_b128 v[204:207], v149 offset:37888
	ds_read_b128 v[208:211], v149 offset:38912
	ds_read_b128 v[216:219], v149 offset:39936
	global_load_lds_dwordx4 v[228:229], off
	v_lshl_add_u64 v[228:229], s[64:65], 0, v[132:133]
	s_mov_b32 m0, s14
	s_nop 0
	global_load_lds_dwordx4 v[228:229], off
	s_waitcnt vmcnt(8)
	s_waitcnt lgkmcnt(0)
	s_barrier
	s_nop 0
	s_waitcnt lgkmcnt(0)
	v_mfma_f32_16x16x32_bf16 v[124:127], v[152:155], v[184:187], v[124:127]
	v_mfma_f32_16x16x32_bf16 v[120:123], v[160:163], v[184:187], v[120:123]
	v_mfma_f32_16x16x32_bf16 v[116:119], v[152:155], v[192:195], v[116:119]
	v_mfma_f32_16x16x32_bf16 v[112:115], v[160:163], v[192:195], v[112:115]
	v_mfma_f32_16x16x32_bf16 v[108:111], v[152:155], v[200:203], v[108:111]
	v_mfma_f32_16x16x32_bf16 v[104:107], v[160:163], v[200:203], v[104:107]
	v_mfma_f32_16x16x32_bf16 v[100:103], v[152:155], v[208:211], v[100:103]
	v_mfma_f32_16x16x32_bf16 v[96:99], v[160:163], v[208:211], v[96:99]
	v_mfma_f32_16x16x32_bf16 v[124:127], v[156:159], v[188:191], v[124:127]
	v_mfma_f32_16x16x32_bf16 v[120:123], v[164:167], v[188:191], v[120:123]
	v_mfma_f32_16x16x32_bf16 v[116:119], v[156:159], v[196:199], v[116:119]
	v_mfma_f32_16x16x32_bf16 v[112:115], v[164:167], v[196:199], v[112:115]
	v_mfma_f32_16x16x32_bf16 v[108:111], v[156:159], v[204:207], v[108:111]
	v_mfma_f32_16x16x32_bf16 v[104:107], v[164:167], v[204:207], v[104:107]
	v_mfma_f32_16x16x32_bf16 v[100:103], v[156:159], v[216:219], v[100:103]
	v_mfma_f32_16x16x32_bf16 v[96:99], v[164:167], v[216:219], v[96:99]
	s_nop 0
	s_nop 0
	v_mfma_f32_16x16x32_bf16 v[92:95], v[168:171], v[184:187], v[92:95]
	v_mfma_f32_16x16x32_bf16 v[88:91], v[176:179], v[184:187], v[88:91]
	v_mfma_f32_16x16x32_bf16 v[84:87], v[168:171], v[192:195], v[84:87]
	v_mfma_f32_16x16x32_bf16 v[80:83], v[176:179], v[192:195], v[80:83]
	v_mfma_f32_16x16x32_bf16 v[76:79], v[168:171], v[200:203], v[76:79]
	v_mfma_f32_16x16x32_bf16 v[72:75], v[176:179], v[200:203], v[72:75]
	v_mfma_f32_16x16x32_bf16 v[68:71], v[168:171], v[208:211], v[68:71]
	v_mfma_f32_16x16x32_bf16 v[64:67], v[176:179], v[208:211], v[64:67]
	v_mfma_f32_16x16x32_bf16 v[92:95], v[172:175], v[188:191], v[92:95]
	v_mfma_f32_16x16x32_bf16 v[88:91], v[180:183], v[188:191], v[88:91]
	v_mfma_f32_16x16x32_bf16 v[84:87], v[172:175], v[196:199], v[84:87]
	v_mfma_f32_16x16x32_bf16 v[80:83], v[180:183], v[196:199], v[80:83]
	v_mfma_f32_16x16x32_bf16 v[76:79], v[172:175], v[204:207], v[76:79]
	v_mfma_f32_16x16x32_bf16 v[72:75], v[180:183], v[204:207], v[72:75]
	v_mfma_f32_16x16x32_bf16 v[68:71], v[172:175], v[216:219], v[68:71]
	v_mfma_f32_16x16x32_bf16 v[64:67], v[180:183], v[216:219], v[64:67]
	s_nop 0
	s_barrier
; #define STAGE(bufoff, gbase) STAGE_(bufoff, gbase, voffA)
; #define STAGEB(bufoff, gbase) STAGE_(bufoff, gbase, voffB)
; #define LDA(dst, b, h) do { _Pragma("unroll") for (int m = 0; m < 4; ++m) _Pragma("unroll") for (int k = 0; k < 2; ++k) dst[m][k] = *LDSP(const bf16x8, lds + SA(b, h) + aoff + m * 2048 + k * 1024); } while (0)
; #define MMA(ai, bj, AT, BT) do { __builtin_amdgcn_s_setprio(1); \
;     _Pragma("unroll") for (int m = 0; m < 4; ++m) _Pragma("unroll") for (int n = 0; n < 2; ++n) _Pragma("unroll") for (int k = 0; k < 2; ++k) \
;       acc[ai][bj][m][n] = __builtin_amdgcn_mfma_f32_16x16x32_bf16(BT[n][k], AT[m][k], acc[ai][bj][m][n], 0, 0, 0); \
;     __builtin_amdgcn_s_setprio(0); } while (0)
; #define WAIT_V(n) asm volatile("s_waitcnt vmcnt(" #n ")" ::: "memory")
; #define WAIT_L(n) asm volatile("s_waitcnt lgkmcnt(" #n ")" ::: "memory")
; #define BAR __builtin_amdgcn_s_barrier()
; #define SCHED __builtin_amdgcn_sched_barrier(0)
; #define WAIT_V(n) asm volatile("s_waitcnt vmcnt(" #n ")" ::: "memory")
; #define BAR do { __builtin_amdgcn_sched_barrier(0); __builtin_amdgcn_s_barrier(); asm volatile("" ::: "memory"); __builtin_amdgcn_sched_barrier(0); } while (0)
; template <bool SP2, bool ALIGN_EPI, bool DUAL, class Epi> DI void gemm_phase2(const bf16_t* A, const bf16_t* Bt, const bf16_t* A2, const bf16_t* Bt2, int M, int N, int K, const Epi& E, lds_t* lds) {
;     ...
;     for (int t = 0; t < nt; t += 2) {
;       const bool last = (t == nt - 2);
;       const char* a1 = cA + (size_t)(t + 1) * kstep;
;       const char* a2 = last ? nA : cA + (size_t)(t + 2) * kstep; const char* b2 = last ? nB : cB + (size_t)(t + 2) * kstep;
;       const char* a3 = a2 + kstep; const char* b3 = b2 + kstep;
;     ...
;         LDA(At, 1, 1); STAGEB(SB(1, 0), b3); STAGEB(SB(1, 1), b3 + bstep); STAGE(SA(1, 0), a3);
;         WAIT_V(8); WAIT_L(0); BAR; MMA(1, 0, At, B0); MMA(1, 1, At, B1); BAR; SCHED;
	s_add_i32 s41, s41, s8
	v_lshl_add_u64 v[220:221], v[220:221], 0, s[30:31]
	s_mov_b32 m0, s41
	ds_read_b128 v[184:187], v149 offset:49152
	ds_read_b128 v[188:191], v149 offset:50176
	ds_read_b128 v[192:195], v149 offset:51200
	ds_read_b128 v[196:199], v149 offset:52224
	ds_read_b128 v[200:203], v149 offset:53248
	ds_read_b128 v[204:207], v149 offset:54272
	ds_read_b128 v[208:211], v149 offset:55296
	ds_read_b128 v[216:219], v149 offset:56320
	global_load_lds_dwordx4 v[220:221], off
	s_add_i32 m0, s41, 0x2000
	s_add_u32 s62, s62, 0x10080
	v_lshl_add_u64 v[220:221], v[222:223], 0, s[30:31]
	s_addc_u32 s63, s63, 0
	s_add_i32 s41, s59, s8
	global_load_lds_dwordx4 v[220:221], off
	v_lshl_add_u64 v[220:221], s[62:63], 0, v[130:131]
	s_mov_b32 m0, s41
	s_nop 0
	global_load_lds_dwordx4 v[220:221], off
	v_lshl_add_u64 v[220:221], s[62:63], 0, v[134:135]
	s_add_i32 m0, s41, 0x2000
	s_nop 0
	global_load_lds_dwordx4 v[220:221], off
	v_lshl_add_u64 v[220:221], v[224:225], 0, s[30:31]
	s_mov_b32 m0, s18
	s_nop 0
	global_load_lds_dwordx4 v[220:221], off
	v_lshl_add_u64 v[220:221], v[226:227], 0, s[30:31]
	s_mov_b32 m0, s19
	s_nop 0
	global_load_lds_dwordx4 v[220:221], off
	s_waitcnt vmcnt(8)
	s_waitcnt lgkmcnt(0)
	s_barrier
	s_nop 0
	s_waitcnt lgkmcnt(0)
	v_mfma_f32_16x16x32_bf16 v[60:63], v[152:155], v[184:187], v[60:63]
	v_mfma_f32_16x16x32_bf16 v[56:59], v[160:163], v[184:187], v[56:59]
	v_mfma_f32_16x16x32_bf16 v[52:55], v[152:155], v[192:195], v[52:55]
	v_mfma_f32_16x16x32_bf16 v[48:51], v[160:163], v[192:195], v[48:51]
	v_mfma_f32_16x16x32_bf16 v[44:47], v[152:155], v[200:203], v[44:47]
	v_mfma_f32_16x16x32_bf16 v[40:43], v[160:163], v[200:203], v[40:43]
	v_mfma_f32_16x16x32_bf16 v[36:39], v[152:155], v[208:211], v[36:39]
	v_mfma_f32_16x16x32_bf16 v[32:35], v[160:163], v[208:211], v[32:35]
	v_mfma_f32_16x16x32_bf16 v[60:63], v[156:159], v[188:191], v[60:63]
	v_mfma_f32_16x16x32_bf16 v[56:59], v[164:167], v[188:191], v[56:59]
	v_mfma_f32_16x16x32_bf16 v[52:55], v[156:159], v[196:199], v[52:55]
	v_mfma_f32_16x16x32_bf16 v[48:51], v[164:167], v[196:199], v[48:51]
	v_mfma_f32_16x16x32_bf16 v[44:47], v[156:159], v[204:207], v[44:47]
	v_mfma_f32_16x16x32_bf16 v[40:43], v[164:167], v[204:207], v[40:43]
	v_mfma_f32_16x16x32_bf16 v[36:39], v[156:159], v[216:219], v[36:39]
	v_mfma_f32_16x16x32_bf16 v[32:35], v[164:167], v[216:219], v[32:35]
	s_nop 0
	s_nop 0
	v_mfma_f32_16x16x32_bf16 v[28:31], v[168:171], v[184:187], v[28:31]
	v_mfma_f32_16x16x32_bf16 v[24:27], v[176:179], v[184:187], v[24:27]
	v_mfma_f32_16x16x32_bf16 v[20:23], v[168:171], v[192:195], v[20:23]
	v_mfma_f32_16x16x32_bf16 v[16:19], v[176:179], v[192:195], v[16:19]
	v_mfma_f32_16x16x32_bf16 v[12:15], v[168:171], v[200:203], v[12:15]
	v_mfma_f32_16x16x32_bf16 v[8:11], v[176:179], v[200:203], v[8:11]
	v_mfma_f32_16x16x32_bf16 v[4:7], v[168:171], v[208:211], v[4:7]
	v_mfma_f32_16x16x32_bf16 v[0:3], v[176:179], v[208:211], v[0:3]
	v_mfma_f32_16x16x32_bf16 v[28:31], v[172:175], v[188:191], v[28:31]
	v_mfma_f32_16x16x32_bf16 v[24:27], v[180:183], v[188:191], v[24:27]
	v_mfma_f32_16x16x32_bf16 v[20:23], v[172:175], v[196:199], v[20:23]
	v_mfma_f32_16x16x32_bf16 v[16:19], v[180:183], v[196:199], v[16:19]
	v_mfma_f32_16x16x32_bf16 v[12:15], v[172:175], v[204:207], v[12:15]
	v_mfma_f32_16x16x32_bf16 v[8:11], v[180:183], v[204:207], v[8:11]
	v_mfma_f32_16x16x32_bf16 v[4:7], v[172:175], v[216:219], v[4:7]
	v_mfma_f32_16x16x32_bf16 v[0:3], v[180:183], v[216:219], v[0:3]
	s_nop 0
	s_barrier
	s_add_i32 s37, s37, 2
	s_add_u32 s60, s60, 0x100
	s_addc_u32 s61, s61, 0
	s_add_u32 s34, s34, 0x100
	s_addc_u32 s35, s35, 0
	s_cmp_gt_u32 s37, 13
	s_cbranch_scc0 .LBB0_482
	s_and_b64 vcc, exec, s[38:39]
	s_cbranch_vccz .LBB0_485
	s_barrier

; #define STAGE(bufoff, gbase) STAGE_(bufoff, gbase, voffA)
; #define STAGEB(bufoff, gbase) STAGE_(bufoff, gbase, voffB)
; #define LDA(dst, b, h) do { _Pragma("unroll") for (int m = 0; m < 4; ++m) _Pragma("unroll") for (int k = 0; k < 2; ++k) dst[m][k] = *LDSP(const bf16x8, lds + SA(b, h) + aoff + m * 2048 + k * 1024); } while (0)
; #define LDB(dst, b, h) do { _Pragma("unroll") for (int n = 0; n < 2; ++n) _Pragma("unroll") for (int k = 0; k < 2; ++k) dst[n][k] = *LDSP(const bf16x8, lds + SB(b, h) + boff + n * 2048 + k * 1024); } while (0)
; #define MMA(ai, bj, AT, BT) do { __builtin_amdgcn_s_setprio(1); \
;     _Pragma("unroll") for (int m = 0; m < 4; ++m) _Pragma("unroll") for (int n = 0; n < 2; ++n) _Pragma("unroll") for (int k = 0; k < 2; ++k) \
;       acc[ai][bj][m][n] = __builtin_amdgcn_mfma_f32_16x16x32_bf16(BT[n][k], AT[m][k], acc[ai][bj][m][n], 0, 0, 0); \
;     __builtin_amdgcn_s_setprio(0); } while (0)
; #define WAIT_V(n) asm volatile("s_waitcnt vmcnt(" #n ")" ::: "memory")
; #define WAIT_L(n) asm volatile("s_waitcnt lgkmcnt(" #n ")" ::: "memory")
; #define BAR __builtin_amdgcn_s_barrier()
; #define SCHED __builtin_amdgcn_sched_barrier(0)
; #define WAIT_V(n) asm volatile("s_waitcnt vmcnt(" #n ")" ::: "memory")
; #define BAR do { __builtin_amdgcn_sched_barrier(0); __builtin_amdgcn_s_barrier(); asm volatile("" ::: "memory"); __builtin_amdgcn_sched_barrier(0); } while (0)
; template <bool SP2, bool ALIGN_EPI, bool DUAL, class Epi> DI void gemm_phase2(const bf16_t* A, const bf16_t* Bt, const bf16_t* A2, const bf16_t* Bt2, int M, int N, int K, const Epi& E, lds_t* lds) {
;     ...
;     for (int t = 0; t < nt; t += 2) {
;       const bool last = (t == nt - 2);
;       const char* a1 = cA + (size_t)(t + 1) * kstep;
;       const char* a2 = last ? nA : cA + (size_t)(t + 2) * kstep; const char* b2 = last ? nB : cB + (size_t)(t + 2) * kstep;
;       const char* a3 = a2 + kstep; const char* b3 = b2 + kstep;
;       if constexpr (SP2) {
;         LDB(B0, 0, 0); LDB(B1, 0, 1); SCHED; LDA(At, 0, 0); STAGE(SA(1, 1), a1 + hstep);
;         WAIT_V(8); WAIT_L(0); BAR; MMA(0, 0, At, B0); MMA(0, 1, At, B1); BAR; SCHED;
;         LDA(At, 0, 1); STAGEB(SB(0, 0), b2); STAGEB(SB(0, 1), b2 + bstep); STAGE(SA(0, 0), a2);
;         WAIT_V(8); WAIT_L(0); BAR; MMA(1, 0, At, B0); MMA(1, 1, At, B1); BAR; SCHED;
.LBB0_551:
	ds_read_b128 v[152:155], v148
	ds_read_b128 v[156:159], v148 offset:1024
	ds_read_b128 v[160:163], v148 offset:2048
	ds_read_b128 v[164:167], v148 offset:3072
	ds_read_b128 v[168:171], v149
	ds_read_b128 v[172:175], v149 offset:1024
	ds_read_b128 v[176:179], v149 offset:2048
	ds_read_b128 v[180:183], v149 offset:3072
	s_add_u32 s35, s60, 0xfffc0080
	s_addc_u32 s37, s61, -1
	s_cmp_eq_u32 s34, 12
	s_cselect_b32 s65, s0, s37
	s_cselect_b32 s64, s1, s35
	s_cselect_b32 s63, s21, s33
	s_cselect_b32 s62, s22, s23
	v_lshl_add_u64 v[140:141], s[60:61], 0, v[136:137]
	s_add_i32 m0, s3, 0xc000
	ds_read_b128 v[184:187], v150
	ds_read_b128 v[188:191], v150 offset:1024
	ds_read_b128 v[192:195], v150 offset:2048
	ds_read_b128 v[196:199], v150 offset:3072
	ds_read_b128 v[200:203], v150 offset:4096
	ds_read_b128 v[204:207], v150 offset:5120
	ds_read_b128 v[208:211], v150 offset:6144
	ds_read_b128 v[216:219], v150 offset:7168
	global_load_lds_dwordx4 v[140:141], off
	v_lshl_add_u64 v[140:141], s[60:61], 0, v[138:139]
	s_add_i32 m0, s3, 0xe000
	s_nop 0
	global_load_lds_dwordx4 v[140:141], off
	s_waitcnt vmcnt(8)
	s_waitcnt lgkmcnt(0)
	s_barrier
	s_nop 0
	s_waitcnt lgkmcnt(0)
	v_mfma_f32_16x16x32_bf16 v[124:127], v[152:155], v[184:187], v[124:127]
	v_mfma_f32_16x16x32_bf16 v[120:123], v[160:163], v[184:187], v[120:123]
	v_mfma_f32_16x16x32_bf16 v[108:111], v[152:155], v[192:195], v[108:111]
	v_mfma_f32_16x16x32_bf16 v[104:107], v[160:163], v[192:195], v[104:107]
	v_mfma_f32_16x16x32_bf16 v[92:95], v[152:155], v[200:203], v[92:95]
	v_mfma_f32_16x16x32_bf16 v[88:91], v[160:163], v[200:203], v[88:91]
	v_mfma_f32_16x16x32_bf16 v[76:79], v[152:155], v[208:211], v[76:79]
	v_mfma_f32_16x16x32_bf16 v[72:75], v[160:163], v[208:211], v[72:75]
	v_mfma_f32_16x16x32_bf16 v[124:127], v[156:159], v[188:191], v[124:127]
	v_mfma_f32_16x16x32_bf16 v[120:123], v[164:167], v[188:191], v[120:123]
	v_mfma_f32_16x16x32_bf16 v[108:111], v[156:159], v[196:199], v[108:111]
	v_mfma_f32_16x16x32_bf16 v[104:107], v[164:167], v[196:199], v[104:107]
	v_mfma_f32_16x16x32_bf16 v[92:95], v[156:159], v[204:207], v[92:95]
	v_mfma_f32_16x16x32_bf16 v[88:91], v[164:167], v[204:207], v[88:91]
	v_mfma_f32_16x16x32_bf16 v[76:79], v[156:159], v[216:219], v[76:79]
	v_mfma_f32_16x16x32_bf16 v[72:75], v[164:167], v[216:219], v[72:75]
	s_nop 0
	s_nop 0
	v_mfma_f32_16x16x32_bf16 v[116:119], v[168:171], v[184:187], v[116:119]
	v_mfma_f32_16x16x32_bf16 v[112:115], v[176:179], v[184:187], v[112:115]
	v_mfma_f32_16x16x32_bf16 v[100:103], v[168:171], v[192:195], v[100:103]
	v_mfma_f32_16x16x32_bf16 v[96:99], v[176:179], v[192:195], v[96:99]
	v_mfma_f32_16x16x32_bf16 v[84:87], v[168:171], v[200:203], v[84:87]
	v_mfma_f32_16x16x32_bf16 v[80:83], v[176:179], v[200:203], v[80:83]
	v_mfma_f32_16x16x32_bf16 v[68:71], v[168:171], v[208:211], v[68:71]
	v_mfma_f32_16x16x32_bf16 v[64:67], v[176:179], v[208:211], v[64:67]
	v_mfma_f32_16x16x32_bf16 v[116:119], v[172:175], v[188:191], v[116:119]
	v_mfma_f32_16x16x32_bf16 v[112:115], v[180:183], v[188:191], v[112:115]
	v_mfma_f32_16x16x32_bf16 v[100:103], v[172:175], v[196:199], v[100:103]
	v_mfma_f32_16x16x32_bf16 v[96:99], v[180:183], v[196:199], v[96:99]
	v_mfma_f32_16x16x32_bf16 v[84:87], v[172:175], v[204:207], v[84:87]
	v_mfma_f32_16x16x32_bf16 v[80:83], v[180:183], v[204:207], v[80:83]
	v_mfma_f32_16x16x32_bf16 v[68:71], v[172:175], v[216:219], v[68:71]
	v_mfma_f32_16x16x32_bf16 v[64:67], v[180:183], v[216:219], v[64:67]
	s_nop 0
	s_barrier
	s_add_i32 s35, s18, s2
	v_lshl_add_u64 v[140:141], s[62:63], 0, v[130:131]
	s_mov_b32 m0, s35
	ds_read_b128 v[184:187], v150 offset:16384
	ds_read_b128 v[188:191], v150 offset:17408
	ds_read_b128 v[192:195], v150 offset:18432
	ds_read_b128 v[196:199], v150 offset:19456
	ds_read_b128 v[200:203], v150 offset:20480
	ds_read_b128 v[204:207], v150 offset:21504
	ds_read_b128 v[208:211], v150 offset:22528
	ds_read_b128 v[216:219], v150 offset:23552
	global_load_lds_dwordx4 v[140:141], off
	s_add_i32 m0, s35, 0x2000
	s_add_u32 s66, s62, 0x10000
	v_lshl_add_u64 v[220:221], s[62:63], 0, v[134:135]
	s_addc_u32 s67, s63, 0
	s_add_i32 s35, s19, s2
	global_load_lds_dwordx4 v[220:221], off
	v_lshl_add_u64 v[222:223], s[66:67], 0, v[130:131]
	s_mov_b32 m0, s35
	v_lshl_add_u64 v[224:225], s[64:65], 0, v[132:133]
	global_load_lds_dwordx4 v[222:223], off
	v_lshl_add_u64 v[222:223], s[66:67], 0, v[134:135]
	s_add_i32 m0, s35, 0x2000
	s_nop 0
	global_load_lds_dwordx4 v[222:223], off
	v_lshl_add_u64 v[222:223], s[64:65], 0, v[128:129]
	s_mov_b32 m0, s3
	s_nop 0
	global_load_lds_dwordx4 v[222:223], off
	s_mov_b32 m0, s8
	s_nop 0
	global_load_lds_dwordx4 v[224:225], off
	s_waitcnt vmcnt(8)
	s_waitcnt lgkmcnt(0)
	s_barrier
; #define STAGE(bufoff, gbase) STAGE_(bufoff, gbase, voffA)
; #define LDA(dst, b, h) do { _Pragma("unroll") for (int m = 0; m < 4; ++m) _Pragma("unroll") for (int k = 0; k < 2; ++k) dst[m][k] = *LDSP(const bf16x8, lds + SA(b, h) + aoff + m * 2048 + k * 1024); } while (0)
; #define LDB(dst, b, h) do { _Pragma("unroll") for (int n = 0; n < 2; ++n) _Pragma("unroll") for (int k = 0; k < 2; ++k) dst[n][k] = *LDSP(const bf16x8, lds + SB(b, h) + boff + n * 2048 + k * 1024); } while (0)
; #define MMA(ai, bj, AT, BT) do { __builtin_amdgcn_s_setprio(1); \
;     _Pragma("unroll") for (int m = 0; m < 4; ++m) _Pragma("unroll") for (int n = 0; n < 2; ++n) _Pragma("unroll") for (int k = 0; k < 2; ++k) \
;       acc[ai][bj][m][n] = __builtin_amdgcn_mfma_f32_16x16x32_bf16(BT[n][k], AT[m][k], acc[ai][bj][m][n], 0, 0, 0); \
;     __builtin_amdgcn_s_setprio(0); } while (0)
; #define WAIT_V(n) asm volatile("s_waitcnt vmcnt(" #n ")" ::: "memory")
; #define WAIT_L(n) asm volatile("s_waitcnt lgkmcnt(" #n ")" ::: "memory")
; #define BAR __builtin_amdgcn_s_barrier()
; #define SCHED __builtin_amdgcn_sched_barrier(0)
; #define WAIT_V(n) asm volatile("s_waitcnt vmcnt(" #n ")" ::: "memory")
; #define BAR do { __builtin_amdgcn_sched_barrier(0); __builtin_amdgcn_s_barrier(); asm volatile("" ::: "memory"); __builtin_amdgcn_sched_barrier(0); } while (0)
; template <bool SP2, bool ALIGN_EPI, bool DUAL, class Epi> DI void gemm_phase2(const bf16_t* A, const bf16_t* Bt, const bf16_t* A2, const bf16_t* Bt2, int M, int N, int K, const Epi& E, lds_t* lds) {
;     ...
;         WAIT_V(8); WAIT_L(0); BAR; MMA(1, 0, At, B0); MMA(1, 1, At, B1); BAR; SCHED;
;         LDB(B0, 1, 0); LDB(B1, 1, 1); SCHED; LDA(At, 1, 0); STAGE(SA(0, 1), a2 + hstep);
;         WAIT_V(8); WAIT_L(0); BAR; MMA(0, 0, At, B0); MMA(0, 1, At, B1); BAR; SCHED;
	s_nop 0
	s_waitcnt lgkmcnt(0)
	v_mfma_f32_16x16x32_bf16 v[60:63], v[152:155], v[184:187], v[60:63]
	v_mfma_f32_16x16x32_bf16 v[56:59], v[160:163], v[184:187], v[56:59]
	v_mfma_f32_16x16x32_bf16 v[44:47], v[152:155], v[192:195], v[44:47]
	v_mfma_f32_16x16x32_bf16 v[40:43], v[160:163], v[192:195], v[40:43]
	v_mfma_f32_16x16x32_bf16 v[28:31], v[152:155], v[200:203], v[28:31]
	v_mfma_f32_16x16x32_bf16 v[24:27], v[160:163], v[200:203], v[24:27]
	v_mfma_f32_16x16x32_bf16 v[12:15], v[152:155], v[208:211], v[12:15]
	v_mfma_f32_16x16x32_bf16 v[8:11], v[160:163], v[208:211], v[8:11]
	v_mfma_f32_16x16x32_bf16 v[60:63], v[156:159], v[188:191], v[60:63]
	v_mfma_f32_16x16x32_bf16 v[56:59], v[164:167], v[188:191], v[56:59]
	v_mfma_f32_16x16x32_bf16 v[44:47], v[156:159], v[196:199], v[44:47]
	v_mfma_f32_16x16x32_bf16 v[40:43], v[164:167], v[196:199], v[40:43]
	v_mfma_f32_16x16x32_bf16 v[28:31], v[156:159], v[204:207], v[28:31]
	v_mfma_f32_16x16x32_bf16 v[24:27], v[164:167], v[204:207], v[24:27]
	v_mfma_f32_16x16x32_bf16 v[12:15], v[156:159], v[216:219], v[12:15]
	v_mfma_f32_16x16x32_bf16 v[8:11], v[164:167], v[216:219], v[8:11]
	s_nop 0
	s_nop 0
	v_mfma_f32_16x16x32_bf16 v[52:55], v[168:171], v[184:187], v[52:55]
	v_mfma_f32_16x16x32_bf16 v[48:51], v[176:179], v[184:187], v[48:51]
	v_mfma_f32_16x16x32_bf16 v[36:39], v[168:171], v[192:195], v[36:39]
	v_mfma_f32_16x16x32_bf16 v[32:35], v[176:179], v[192:195], v[32:35]
	v_mfma_f32_16x16x32_bf16 v[20:23], v[168:171], v[200:203], v[20:23]
	v_mfma_f32_16x16x32_bf16 v[16:19], v[176:179], v[200:203], v[16:19]
	v_mfma_f32_16x16x32_bf16 v[4:7], v[168:171], v[208:211], v[4:7]
	v_mfma_f32_16x16x32_bf16 v[0:3], v[176:179], v[208:211], v[0:3]
	v_mfma_f32_16x16x32_bf16 v[52:55], v[172:175], v[188:191], v[52:55]
	v_mfma_f32_16x16x32_bf16 v[48:51], v[180:183], v[188:191], v[48:51]
	v_mfma_f32_16x16x32_bf16 v[36:39], v[172:175], v[196:199], v[36:39]
	v_mfma_f32_16x16x32_bf16 v[32:35], v[180:183], v[196:199], v[32:35]
	v_mfma_f32_16x16x32_bf16 v[20:23], v[172:175], v[204:207], v[20:23]
	v_mfma_f32_16x16x32_bf16 v[16:19], v[180:183], v[204:207], v[16:19]
	v_mfma_f32_16x16x32_bf16 v[4:7], v[172:175], v[216:219], v[4:7]
	v_mfma_f32_16x16x32_bf16 v[0:3], v[180:183], v[216:219], v[0:3]
	s_nop 0
	s_barrier
	s_add_i32 s35, 0, 0x18000
	s_add_i32 s37, 0, 0x1c000
	v_add_u32_e32 v164, s35, v143
	v_add_u32_e32 v180, s37, v143
	ds_read_b128 v[152:155], v164
	ds_read_b128 v[156:159], v164 offset:1024
	ds_read_b128 v[160:163], v164 offset:2048
	ds_read_b128 v[164:167], v164 offset:3072
	ds_read_b128 v[168:171], v180
	ds_read_b128 v[172:175], v180 offset:1024
	ds_read_b128 v[176:179], v180 offset:2048
	ds_read_b128 v[180:183], v180 offset:3072
	s_add_u32 s64, s64, 0x40000
	s_addc_u32 s65, s65, 0
	s_mov_b32 m0, s9
	v_lshl_add_u64 v[226:227], s[64:65], 0, v[128:129]
	ds_read_b128 v[184:187], v150 offset:32768
	ds_read_b128 v[188:191], v150 offset:33792
	ds_read_b128 v[192:195], v150 offset:34816
	ds_read_b128 v[196:199], v150 offset:35840
	ds_read_b128 v[200:203], v150 offset:36864
	ds_read_b128 v[204:207], v150 offset:37888
	ds_read_b128 v[208:211], v150 offset:38912
	ds_read_b128 v[216:219], v150 offset:39936
	global_load_lds_dwordx4 v[226:227], off
	v_lshl_add_u64 v[226:227], s[64:65], 0, v[132:133]
	s_mov_b32 m0, s10
	s_nop 0
	global_load_lds_dwordx4 v[226:227], off
	s_waitcnt vmcnt(8)
	s_waitcnt lgkmcnt(0)
	s_barrier
	s_nop 0
	s_waitcnt lgkmcnt(0)
	v_mfma_f32_16x16x32_bf16 v[124:127], v[152:155], v[184:187], v[124:127]
	v_mfma_f32_16x16x32_bf16 v[120:123], v[160:163], v[184:187], v[120:123]
	v_mfma_f32_16x16x32_bf16 v[108:111], v[152:155], v[192:195], v[108:111]
	v_mfma_f32_16x16x32_bf16 v[104:107], v[160:163], v[192:195], v[104:107]
	v_mfma_f32_16x16x32_bf16 v[92:95], v[152:155], v[200:203], v[92:95]
	v_mfma_f32_16x16x32_bf16 v[88:91], v[160:163], v[200:203], v[88:91]
	v_mfma_f32_16x16x32_bf16 v[76:79], v[152:155], v[208:211], v[76:79]
	v_mfma_f32_16x16x32_bf16 v[72:75], v[160:163], v[208:211], v[72:75]
	v_mfma_f32_16x16x32_bf16 v[124:127], v[156:159], v[188:191], v[124:127]
	v_mfma_f32_16x16x32_bf16 v[120:123], v[164:167], v[188:191], v[120:123]
	v_mfma_f32_16x16x32_bf16 v[108:111], v[156:159], v[196:199], v[108:111]
	v_mfma_f32_16x16x32_bf16 v[104:107], v[164:167], v[196:199], v[104:107]
	v_mfma_f32_16x16x32_bf16 v[92:95], v[156:159], v[204:207], v[92:95]
	v_mfma_f32_16x16x32_bf16 v[88:91], v[164:167], v[204:207], v[88:91]
	v_mfma_f32_16x16x32_bf16 v[76:79], v[156:159], v[216:219], v[76:79]
	v_mfma_f32_16x16x32_bf16 v[72:75], v[164:167], v[216:219], v[72:75]
	s_nop 0
	s_nop 0
	v_mfma_f32_16x16x32_bf16 v[116:119], v[168:171], v[184:187], v[116:119]
	v_mfma_f32_16x16x32_bf16 v[112:115], v[176:179], v[184:187], v[112:115]
	v_mfma_f32_16x16x32_bf16 v[100:103], v[168:171], v[192:195], v[100:103]
	v_mfma_f32_16x16x32_bf16 v[96:99], v[176:179], v[192:195], v[96:99]
	v_mfma_f32_16x16x32_bf16 v[84:87], v[168:171], v[200:203], v[84:87]
	v_mfma_f32_16x16x32_bf16 v[80:83], v[176:179], v[200:203], v[80:83]
	v_mfma_f32_16x16x32_bf16 v[68:71], v[168:171], v[208:211], v[68:71]
	v_mfma_f32_16x16x32_bf16 v[64:67], v[176:179], v[208:211], v[64:67]
	v_mfma_f32_16x16x32_bf16 v[116:119], v[172:175], v[188:191], v[116:119]
	v_mfma_f32_16x16x32_bf16 v[112:115], v[180:183], v[188:191], v[112:115]
	v_mfma_f32_16x16x32_bf16 v[100:103], v[172:175], v[196:199], v[100:103]
	v_mfma_f32_16x16x32_bf16 v[96:99], v[180:183], v[196:199], v[96:99]
	v_mfma_f32_16x16x32_bf16 v[84:87], v[172:175], v[204:207], v[84:87]
	v_mfma_f32_16x16x32_bf16 v[80:83], v[180:183], v[204:207], v[80:83]
	v_mfma_f32_16x16x32_bf16 v[68:71], v[172:175], v[216:219], v[68:71]
	v_mfma_f32_16x16x32_bf16 v[64:67], v[180:183], v[216:219], v[64:67]
	s_nop 0
	s_barrier
; #define STAGE(bufoff, gbase) STAGE_(bufoff, gbase, voffA)
; #define STAGEB(bufoff, gbase) STAGE_(bufoff, gbase, voffB)
; #define LDA(dst, b, h) do { _Pragma("unroll") for (int m = 0; m < 4; ++m) _Pragma("unroll") for (int k = 0; k < 2; ++k) dst[m][k] = *LDSP(const bf16x8, lds + SA(b, h) + aoff + m * 2048 + k * 1024); } while (0)
; #define MMA(ai, bj, AT, BT) do { __builtin_amdgcn_s_setprio(1); \
;     _Pragma("unroll") for (int m = 0; m < 4; ++m) _Pragma("unroll") for (int n = 0; n < 2; ++n) _Pragma("unroll") for (int k = 0; k < 2; ++k) \
;       acc[ai][bj][m][n] = __builtin_amdgcn_mfma_f32_16x16x32_bf16(BT[n][k], AT[m][k], acc[ai][bj][m][n], 0, 0, 0); \
;     __builtin_amdgcn_s_setprio(0); } while (0)
; #define WAIT_V(n) asm volatile("s_waitcnt vmcnt(" #n ")" ::: "memory")
; #define WAIT_L(n) asm volatile("s_waitcnt lgkmcnt(" #n ")" ::: "memory")
; #define BAR __builtin_amdgcn_s_barrier()
; #define SCHED __builtin_amdgcn_sched_barrier(0)
; #define WAIT_V(n) asm volatile("s_waitcnt vmcnt(" #n ")" ::: "memory")
; #define BAR do { __builtin_amdgcn_sched_barrier(0); __builtin_amdgcn_s_barrier(); asm volatile("" ::: "memory"); __builtin_amdgcn_sched_barrier(0); } while (0)
; template <bool SP2, bool ALIGN_EPI, bool DUAL, class Epi> DI void gemm_phase2(const bf16_t* A, const bf16_t* Bt, const bf16_t* A2, const bf16_t* Bt2, int M, int N, int K, const Epi& E, lds_t* lds) {
;     ...
;     for (int t = 0; t < nt; t += 2) {
;       const bool last = (t == nt - 2);
;       const char* a1 = cA + (size_t)(t + 1) * kstep;
;       const char* a2 = last ? nA : cA + (size_t)(t + 2) * kstep; const char* b2 = last ? nB : cB + (size_t)(t + 2) * kstep;
;       const char* a3 = a2 + kstep; const char* b3 = b2 + kstep;
;     ...
;         LDA(At, 1, 1); STAGEB(SB(1, 0), b3); STAGEB(SB(1, 1), b3 + bstep); STAGE(SA(1, 0), a3);
;         WAIT_V(8); WAIT_L(0); BAR; MMA(1, 0, At, B0); MMA(1, 1, At, B1); BAR; SCHED;
	s_add_i32 s35, s35, s2
	v_lshl_add_u64 v[140:141], v[140:141], 0, s[30:31]
	s_mov_b32 m0, s35
	ds_read_b128 v[184:187], v150 offset:49152
	ds_read_b128 v[188:191], v150 offset:50176
	ds_read_b128 v[192:195], v150 offset:51200
	ds_read_b128 v[196:199], v150 offset:52224
	ds_read_b128 v[200:203], v150 offset:53248
	ds_read_b128 v[204:207], v150 offset:54272
	ds_read_b128 v[208:211], v150 offset:55296
	ds_read_b128 v[216:219], v150 offset:56320
	global_load_lds_dwordx4 v[140:141], off
	s_add_i32 m0, s35, 0x2000
	s_add_u32 s62, s62, 0x10080
	v_lshl_add_u64 v[140:141], v[220:221], 0, s[30:31]
	s_addc_u32 s63, s63, 0
	s_add_i32 s35, s37, s2
	global_load_lds_dwordx4 v[140:141], off
	v_lshl_add_u64 v[140:141], s[62:63], 0, v[130:131]
	s_mov_b32 m0, s35
	s_nop 0
	global_load_lds_dwordx4 v[140:141], off
	v_lshl_add_u64 v[140:141], s[62:63], 0, v[134:135]
	s_add_i32 m0, s35, 0x2000
	s_nop 0
	global_load_lds_dwordx4 v[140:141], off
	v_lshl_add_u64 v[140:141], v[222:223], 0, s[30:31]
	s_mov_b32 m0, s14
	s_nop 0
	global_load_lds_dwordx4 v[140:141], off
	v_lshl_add_u64 v[140:141], v[224:225], 0, s[30:31]
	s_mov_b32 m0, s15
	s_nop 0
	global_load_lds_dwordx4 v[140:141], off
	s_waitcnt vmcnt(8)
	s_waitcnt lgkmcnt(0)
	s_barrier
	s_nop 0
	s_waitcnt lgkmcnt(0)
	v_mfma_f32_16x16x32_bf16 v[60:63], v[152:155], v[184:187], v[60:63]
	v_mfma_f32_16x16x32_bf16 v[56:59], v[160:163], v[184:187], v[56:59]
	v_mfma_f32_16x16x32_bf16 v[44:47], v[152:155], v[192:195], v[44:47]
	v_mfma_f32_16x16x32_bf16 v[40:43], v[160:163], v[192:195], v[40:43]
	v_mfma_f32_16x16x32_bf16 v[28:31], v[152:155], v[200:203], v[28:31]
	v_mfma_f32_16x16x32_bf16 v[24:27], v[160:163], v[200:203], v[24:27]
	v_mfma_f32_16x16x32_bf16 v[12:15], v[152:155], v[208:211], v[12:15]
	v_mfma_f32_16x16x32_bf16 v[8:11], v[160:163], v[208:211], v[8:11]
	v_mfma_f32_16x16x32_bf16 v[60:63], v[156:159], v[188:191], v[60:63]
	v_mfma_f32_16x16x32_bf16 v[56:59], v[164:167], v[188:191], v[56:59]
	v_mfma_f32_16x16x32_bf16 v[44:47], v[156:159], v[196:199], v[44:47]
	v_mfma_f32_16x16x32_bf16 v[40:43], v[164:167], v[196:199], v[40:43]
	v_mfma_f32_16x16x32_bf16 v[28:31], v[156:159], v[204:207], v[28:31]
	v_mfma_f32_16x16x32_bf16 v[24:27], v[164:167], v[204:207], v[24:27]
	v_mfma_f32_16x16x32_bf16 v[12:15], v[156:159], v[216:219], v[12:15]
	v_mfma_f32_16x16x32_bf16 v[8:11], v[164:167], v[216:219], v[8:11]
	s_nop 0
	s_nop 0
	v_mfma_f32_16x16x32_bf16 v[52:55], v[168:171], v[184:187], v[52:55]
	v_mfma_f32_16x16x32_bf16 v[48:51], v[176:179], v[184:187], v[48:51]
	v_mfma_f32_16x16x32_bf16 v[36:39], v[168:171], v[192:195], v[36:39]
	v_mfma_f32_16x16x32_bf16 v[32:35], v[176:179], v[192:195], v[32:35]
	v_mfma_f32_16x16x32_bf16 v[20:23], v[168:171], v[200:203], v[20:23]
	v_mfma_f32_16x16x32_bf16 v[16:19], v[176:179], v[200:203], v[16:19]
	v_mfma_f32_16x16x32_bf16 v[4:7], v[168:171], v[208:211], v[4:7]
	v_mfma_f32_16x16x32_bf16 v[0:3], v[176:179], v[208:211], v[0:3]
	v_mfma_f32_16x16x32_bf16 v[52:55], v[172:175], v[188:191], v[52:55]
	v_mfma_f32_16x16x32_bf16 v[48:51], v[180:183], v[188:191], v[48:51]
	v_mfma_f32_16x16x32_bf16 v[36:39], v[172:175], v[196:199], v[36:39]
	v_mfma_f32_16x16x32_bf16 v[32:35], v[180:183], v[196:199], v[32:35]
	v_mfma_f32_16x16x32_bf16 v[20:23], v[172:175], v[204:207], v[20:23]
	v_mfma_f32_16x16x32_bf16 v[16:19], v[180:183], v[204:207], v[16:19]
	v_mfma_f32_16x16x32_bf16 v[4:7], v[172:175], v[216:219], v[4:7]
	v_mfma_f32_16x16x32_bf16 v[0:3], v[180:183], v[216:219], v[0:3]
	s_nop 0
	s_barrier
	s_add_i32 s34, s34, 2
	s_add_u32 s60, s60, 0x100
	s_addc_u32 s61, s61, 0
	s_add_u32 s23, s23, 0x100
	s_addc_u32 s33, s33, 0
	s_cmp_gt_u32 s34, 13
	s_cbranch_scc0 .LBB0_551
	s_and_b64 vcc, exec, s[38:39]
	s_cbranch_vccz .LBB0_554
	s_barrier

; #define STAGE(bufoff, gbase) STAGE_(bufoff, gbase, voffA)
; #define STAGEB(bufoff, gbase) STAGE_(bufoff, gbase, voffB)
; #define LDA(dst, b, h) do { _Pragma("unroll") for (int m = 0; m < 4; ++m) _Pragma("unroll") for (int k = 0; k < 2; ++k) dst[m][k] = *LDSP(const bf16x8, lds + SA(b, h) + aoff + m * 2048 + k * 1024); } while (0)
; #define LDB(dst, b, h) do { _Pragma("unroll") for (int n = 0; n < 2; ++n) _Pragma("unroll") for (int k = 0; k < 2; ++k) dst[n][k] = *LDSP(const bf16x8, lds + SB(b, h) + boff + n * 2048 + k * 1024); } while (0)
; #define MMA(ai, bj, AT, BT) do { __builtin_amdgcn_s_setprio(1); \
;     _Pragma("unroll") for (int m = 0; m < 4; ++m) _Pragma("unroll") for (int n = 0; n < 2; ++n) _Pragma("unroll") for (int k = 0; k < 2; ++k) \
;       acc[ai][bj][m][n] = __builtin_amdgcn_mfma_f32_16x16x32_bf16(BT[n][k], AT[m][k], acc[ai][bj][m][n], 0, 0, 0); \
;     __builtin_amdgcn_s_setprio(0); } while (0)
; #define WAIT_V(n) asm volatile("s_waitcnt vmcnt(" #n ")" ::: "memory")
; #define WAIT_L(n) asm volatile("s_waitcnt lgkmcnt(" #n ")" ::: "memory")
; #define BAR __builtin_amdgcn_s_barrier()
; #define SCHED __builtin_amdgcn_sched_barrier(0)
; #define WAIT_V(n) asm volatile("s_waitcnt vmcnt(" #n ")" ::: "memory")
; #define BAR do { __builtin_amdgcn_sched_barrier(0); __builtin_amdgcn_s_barrier(); asm volatile("" ::: "memory"); __builtin_amdgcn_sched_barrier(0); } while (0)
; template <bool SP2, bool ALIGN_EPI, bool DUAL, class Epi> DI void gemm_phase2(const bf16_t* A, const bf16_t* Bt, const bf16_t* A2, const bf16_t* Bt2, int M, int N, int K, const Epi& E, lds_t* lds) {
;     ...
;     for (int t = 0; t < nt; t += 2) {
;       const bool last = (t == nt - 2);
;       const char* a1 = cA + (size_t)(t + 1) * kstep;
;       const char* a2 = last ? nA : cA + (size_t)(t + 2) * kstep; const char* b2 = last ? nB : cB + (size_t)(t + 2) * kstep;
;       const char* a3 = a2 + kstep; const char* b3 = b2 + kstep;
;       if constexpr (SP2) {
;         LDB(B0, 0, 0); LDB(B1, 0, 1); SCHED; LDA(At, 0, 0); STAGE(SA(1, 1), a1 + hstep);
;         WAIT_V(8); WAIT_L(0); BAR; MMA(0, 0, At, B0); MMA(0, 1, At, B1); BAR; SCHED;
;         LDA(At, 0, 1); STAGEB(SB(0, 0), b2); STAGEB(SB(0, 1), b2 + bstep); STAGE(SA(0, 0), a2);
;         WAIT_V(8); WAIT_L(0); BAR; MMA(1, 0, At, B0); MMA(1, 1, At, B1); BAR; SCHED;
.LBB0_620:
	ds_read_b128 v[150:153], v146
	ds_read_b128 v[154:157], v146 offset:1024
	ds_read_b128 v[158:161], v146 offset:2048
	ds_read_b128 v[162:165], v146 offset:3072
	ds_read_b128 v[166:169], v147
	ds_read_b128 v[170:173], v147 offset:1024
	ds_read_b128 v[174:177], v147 offset:2048
	ds_read_b128 v[178:181], v147 offset:3072
	s_add_u32 s47, s52, 0xfffc0080
	s_addc_u32 s54, s53, -1
	s_cmp_eq_u32 s37, 12
	s_cselect_b32 s57, s1, s54
	s_cselect_b32 s56, s23, s47
	s_cselect_b32 s55, s29, s35
	s_cselect_b32 s54, s33, s34
	v_lshl_add_u64 v[210:211], s[52:53], 0, v[136:137]
	s_add_i32 m0, s3, 0xc000
	ds_read_b128 v[182:185], v148
	ds_read_b128 v[186:189], v148 offset:1024
	ds_read_b128 v[190:193], v148 offset:2048
	ds_read_b128 v[194:197], v148 offset:3072
	ds_read_b128 v[198:201], v148 offset:4096
	ds_read_b128 v[202:205], v148 offset:5120
	ds_read_b128 v[206:209], v148 offset:6144
	ds_read_b128 v[216:219], v148 offset:7168
	global_load_lds_dwordx4 v[210:211], off
	v_lshl_add_u64 v[210:211], s[52:53], 0, v[138:139]
	s_add_i32 m0, s3, 0xe000
	s_nop 0
	global_load_lds_dwordx4 v[210:211], off
	s_waitcnt vmcnt(8)
	s_waitcnt lgkmcnt(0)
	s_barrier
	s_nop 0
	s_waitcnt lgkmcnt(0)
	v_mfma_f32_16x16x32_bf16 v[124:127], v[150:153], v[182:185], v[124:127]
	v_mfma_f32_16x16x32_bf16 v[120:123], v[158:161], v[182:185], v[120:123]
	v_mfma_f32_16x16x32_bf16 v[108:111], v[150:153], v[190:193], v[108:111]
	v_mfma_f32_16x16x32_bf16 v[104:107], v[158:161], v[190:193], v[104:107]
	v_mfma_f32_16x16x32_bf16 v[92:95], v[150:153], v[198:201], v[92:95]
	v_mfma_f32_16x16x32_bf16 v[88:91], v[158:161], v[198:201], v[88:91]
	v_mfma_f32_16x16x32_bf16 v[76:79], v[150:153], v[206:209], v[76:79]
	v_mfma_f32_16x16x32_bf16 v[72:75], v[158:161], v[206:209], v[72:75]
	v_mfma_f32_16x16x32_bf16 v[124:127], v[154:157], v[186:189], v[124:127]
	v_mfma_f32_16x16x32_bf16 v[120:123], v[162:165], v[186:189], v[120:123]
	v_mfma_f32_16x16x32_bf16 v[108:111], v[154:157], v[194:197], v[108:111]
	v_mfma_f32_16x16x32_bf16 v[104:107], v[162:165], v[194:197], v[104:107]
	v_mfma_f32_16x16x32_bf16 v[92:95], v[154:157], v[202:205], v[92:95]
	v_mfma_f32_16x16x32_bf16 v[88:91], v[162:165], v[202:205], v[88:91]
	v_mfma_f32_16x16x32_bf16 v[76:79], v[154:157], v[216:219], v[76:79]
	v_mfma_f32_16x16x32_bf16 v[72:75], v[162:165], v[216:219], v[72:75]
	s_nop 0
	s_nop 0
	v_mfma_f32_16x16x32_bf16 v[116:119], v[166:169], v[182:185], v[116:119]
	v_mfma_f32_16x16x32_bf16 v[112:115], v[174:177], v[182:185], v[112:115]
	v_mfma_f32_16x16x32_bf16 v[100:103], v[166:169], v[190:193], v[100:103]
	v_mfma_f32_16x16x32_bf16 v[96:99], v[174:177], v[190:193], v[96:99]
	v_mfma_f32_16x16x32_bf16 v[84:87], v[166:169], v[198:201], v[84:87]
	v_mfma_f32_16x16x32_bf16 v[80:83], v[174:177], v[198:201], v[80:83]
	v_mfma_f32_16x16x32_bf16 v[68:71], v[166:169], v[206:209], v[68:71]
	v_mfma_f32_16x16x32_bf16 v[64:67], v[174:177], v[206:209], v[64:67]
	v_mfma_f32_16x16x32_bf16 v[116:119], v[170:173], v[186:189], v[116:119]
	v_mfma_f32_16x16x32_bf16 v[112:115], v[178:181], v[186:189], v[112:115]
	v_mfma_f32_16x16x32_bf16 v[100:103], v[170:173], v[194:197], v[100:103]
	v_mfma_f32_16x16x32_bf16 v[96:99], v[178:181], v[194:197], v[96:99]
	v_mfma_f32_16x16x32_bf16 v[84:87], v[170:173], v[202:205], v[84:87]
	v_mfma_f32_16x16x32_bf16 v[80:83], v[178:181], v[202:205], v[80:83]
	v_mfma_f32_16x16x32_bf16 v[68:71], v[170:173], v[216:219], v[68:71]
	v_mfma_f32_16x16x32_bf16 v[64:67], v[178:181], v[216:219], v[64:67]
	s_nop 0
	s_barrier
	s_add_i32 s47, s19, s2
	v_lshl_add_u64 v[210:211], s[54:55], 0, v[132:133]
	s_mov_b32 m0, s47
	ds_read_b128 v[182:185], v148 offset:16384
	ds_read_b128 v[186:189], v148 offset:17408
	ds_read_b128 v[190:193], v148 offset:18432
	ds_read_b128 v[194:197], v148 offset:19456
	ds_read_b128 v[198:201], v148 offset:20480
	ds_read_b128 v[202:205], v148 offset:21504
	ds_read_b128 v[206:209], v148 offset:22528
	ds_read_b128 v[216:219], v148 offset:23552
	global_load_lds_dwordx4 v[210:211], off
	s_add_i32 m0, s47, 0x2000
	s_add_u32 s58, s54, 0x10000
	v_lshl_add_u64 v[220:221], s[54:55], 0, v[128:129]
	s_addc_u32 s59, s55, 0
	s_add_i32 s47, s20, s2
	global_load_lds_dwordx4 v[220:221], off
	v_lshl_add_u64 v[222:223], s[58:59], 0, v[132:133]
	s_mov_b32 m0, s47
	v_lshl_add_u64 v[224:225], s[56:57], 0, v[130:131]
	global_load_lds_dwordx4 v[222:223], off
	v_lshl_add_u64 v[222:223], s[58:59], 0, v[128:129]
	s_add_i32 m0, s47, 0x2000
	s_nop 0
	global_load_lds_dwordx4 v[222:223], off
	v_lshl_add_u64 v[222:223], s[56:57], 0, v[134:135]
	s_mov_b32 m0, s3
	s_nop 0
	global_load_lds_dwordx4 v[222:223], off
	s_mov_b32 m0, s8
	s_nop 0
	global_load_lds_dwordx4 v[224:225], off
	s_waitcnt vmcnt(8)
	s_waitcnt lgkmcnt(0)
	s_barrier
; #define STAGE(bufoff, gbase) STAGE_(bufoff, gbase, voffA)
; #define LDA(dst, b, h) do { _Pragma("unroll") for (int m = 0; m < 4; ++m) _Pragma("unroll") for (int k = 0; k < 2; ++k) dst[m][k] = *LDSP(const bf16x8, lds + SA(b, h) + aoff + m * 2048 + k * 1024); } while (0)
; #define LDB(dst, b, h) do { _Pragma("unroll") for (int n = 0; n < 2; ++n) _Pragma("unroll") for (int k = 0; k < 2; ++k) dst[n][k] = *LDSP(const bf16x8, lds + SB(b, h) + boff + n * 2048 + k * 1024); } while (0)
; #define MMA(ai, bj, AT, BT) do { __builtin_amdgcn_s_setprio(1); \
;     _Pragma("unroll") for (int m = 0; m < 4; ++m) _Pragma("unroll") for (int n = 0; n < 2; ++n) _Pragma("unroll") for (int k = 0; k < 2; ++k) \
;       acc[ai][bj][m][n] = __builtin_amdgcn_mfma_f32_16x16x32_bf16(BT[n][k], AT[m][k], acc[ai][bj][m][n], 0, 0, 0); \
;     __builtin_amdgcn_s_setprio(0); } while (0)
; #define WAIT_V(n) asm volatile("s_waitcnt vmcnt(" #n ")" ::: "memory")
; #define WAIT_L(n) asm volatile("s_waitcnt lgkmcnt(" #n ")" ::: "memory")
; #define BAR __builtin_amdgcn_s_barrier()
; #define SCHED __builtin_amdgcn_sched_barrier(0)
; #define WAIT_V(n) asm volatile("s_waitcnt vmcnt(" #n ")" ::: "memory")
; #define BAR do { __builtin_amdgcn_sched_barrier(0); __builtin_amdgcn_s_barrier(); asm volatile("" ::: "memory"); __builtin_amdgcn_sched_barrier(0); } while (0)
; template <bool SP2, bool ALIGN_EPI, bool DUAL, class Epi> DI void gemm_phase2(const bf16_t* A, const bf16_t* Bt, const bf16_t* A2, const bf16_t* Bt2, int M, int N, int K, const Epi& E, lds_t* lds) {
;     ...
;         WAIT_V(8); WAIT_L(0); BAR; MMA(1, 0, At, B0); MMA(1, 1, At, B1); BAR; SCHED;
;         LDB(B0, 1, 0); LDB(B1, 1, 1); SCHED; LDA(At, 1, 0); STAGE(SA(0, 1), a2 + hstep);
;         WAIT_V(8); WAIT_L(0); BAR; MMA(0, 0, At, B0); MMA(0, 1, At, B1); BAR; SCHED;
	s_nop 0
	s_waitcnt lgkmcnt(0)
	v_mfma_f32_16x16x32_bf16 v[60:63], v[150:153], v[182:185], v[60:63]
	v_mfma_f32_16x16x32_bf16 v[56:59], v[158:161], v[182:185], v[56:59]
	v_mfma_f32_16x16x32_bf16 v[44:47], v[150:153], v[190:193], v[44:47]
	v_mfma_f32_16x16x32_bf16 v[40:43], v[158:161], v[190:193], v[40:43]
	v_mfma_f32_16x16x32_bf16 v[28:31], v[150:153], v[198:201], v[28:31]
	v_mfma_f32_16x16x32_bf16 v[24:27], v[158:161], v[198:201], v[24:27]
	v_mfma_f32_16x16x32_bf16 v[12:15], v[150:153], v[206:209], v[12:15]
	v_mfma_f32_16x16x32_bf16 v[8:11], v[158:161], v[206:209], v[8:11]
	v_mfma_f32_16x16x32_bf16 v[60:63], v[154:157], v[186:189], v[60:63]
	v_mfma_f32_16x16x32_bf16 v[56:59], v[162:165], v[186:189], v[56:59]
	v_mfma_f32_16x16x32_bf16 v[44:47], v[154:157], v[194:197], v[44:47]
	v_mfma_f32_16x16x32_bf16 v[40:43], v[162:165], v[194:197], v[40:43]
	v_mfma_f32_16x16x32_bf16 v[28:31], v[154:157], v[202:205], v[28:31]
	v_mfma_f32_16x16x32_bf16 v[24:27], v[162:165], v[202:205], v[24:27]
	v_mfma_f32_16x16x32_bf16 v[12:15], v[154:157], v[216:219], v[12:15]
	v_mfma_f32_16x16x32_bf16 v[8:11], v[162:165], v[216:219], v[8:11]
	s_nop 0
	s_nop 0
	v_mfma_f32_16x16x32_bf16 v[52:55], v[166:169], v[182:185], v[52:55]
	v_mfma_f32_16x16x32_bf16 v[48:51], v[174:177], v[182:185], v[48:51]
	v_mfma_f32_16x16x32_bf16 v[36:39], v[166:169], v[190:193], v[36:39]
	v_mfma_f32_16x16x32_bf16 v[32:35], v[174:177], v[190:193], v[32:35]
	v_mfma_f32_16x16x32_bf16 v[20:23], v[166:169], v[198:201], v[20:23]
	v_mfma_f32_16x16x32_bf16 v[16:19], v[174:177], v[198:201], v[16:19]
	v_mfma_f32_16x16x32_bf16 v[4:7], v[166:169], v[206:209], v[4:7]
	v_mfma_f32_16x16x32_bf16 v[0:3], v[174:177], v[206:209], v[0:3]
	v_mfma_f32_16x16x32_bf16 v[52:55], v[170:173], v[186:189], v[52:55]
	v_mfma_f32_16x16x32_bf16 v[48:51], v[178:181], v[186:189], v[48:51]
	v_mfma_f32_16x16x32_bf16 v[36:39], v[170:173], v[194:197], v[36:39]
	v_mfma_f32_16x16x32_bf16 v[32:35], v[178:181], v[194:197], v[32:35]
	v_mfma_f32_16x16x32_bf16 v[20:23], v[170:173], v[202:205], v[20:23]
	v_mfma_f32_16x16x32_bf16 v[16:19], v[178:181], v[202:205], v[16:19]
	v_mfma_f32_16x16x32_bf16 v[4:7], v[170:173], v[216:219], v[4:7]
	v_mfma_f32_16x16x32_bf16 v[0:3], v[178:181], v[216:219], v[0:3]
	s_nop 0
	s_barrier
	s_add_i32 s47, 0, 0x18000
	s_add_i32 s58, 0, 0x1c000
	v_add_u32_e32 v162, s47, v141
	v_add_u32_e32 v178, s58, v141
	ds_read_b128 v[150:153], v162
	ds_read_b128 v[154:157], v162 offset:1024
	ds_read_b128 v[158:161], v162 offset:2048
	ds_read_b128 v[162:165], v162 offset:3072
	ds_read_b128 v[166:169], v178
	ds_read_b128 v[170:173], v178 offset:1024
	ds_read_b128 v[174:177], v178 offset:2048
	ds_read_b128 v[178:181], v178 offset:3072
	s_add_u32 s56, s56, 0x40000
	s_addc_u32 s57, s57, 0
	s_mov_b32 m0, s9
	v_lshl_add_u64 v[226:227], s[56:57], 0, v[134:135]
	ds_read_b128 v[182:185], v148 offset:32768
	ds_read_b128 v[186:189], v148 offset:33792
	ds_read_b128 v[190:193], v148 offset:34816
	ds_read_b128 v[194:197], v148 offset:35840
	ds_read_b128 v[198:201], v148 offset:36864
	ds_read_b128 v[202:205], v148 offset:37888
	ds_read_b128 v[206:209], v148 offset:38912
	ds_read_b128 v[216:219], v148 offset:39936
	global_load_lds_dwordx4 v[226:227], off
	v_lshl_add_u64 v[226:227], s[56:57], 0, v[130:131]
	s_mov_b32 m0, s10
	s_nop 0
	global_load_lds_dwordx4 v[226:227], off
	s_waitcnt vmcnt(8)
	s_waitcnt lgkmcnt(0)
	s_barrier
	s_nop 0
	s_waitcnt lgkmcnt(0)
	v_mfma_f32_16x16x32_bf16 v[124:127], v[150:153], v[182:185], v[124:127]
	v_mfma_f32_16x16x32_bf16 v[120:123], v[158:161], v[182:185], v[120:123]
	v_mfma_f32_16x16x32_bf16 v[108:111], v[150:153], v[190:193], v[108:111]
	v_mfma_f32_16x16x32_bf16 v[104:107], v[158:161], v[190:193], v[104:107]
	v_mfma_f32_16x16x32_bf16 v[92:95], v[150:153], v[198:201], v[92:95]
	v_mfma_f32_16x16x32_bf16 v[88:91], v[158:161], v[198:201], v[88:91]
	v_mfma_f32_16x16x32_bf16 v[76:79], v[150:153], v[206:209], v[76:79]
	v_mfma_f32_16x16x32_bf16 v[72:75], v[158:161], v[206:209], v[72:75]
	v_mfma_f32_16x16x32_bf16 v[124:127], v[154:157], v[186:189], v[124:127]
	v_mfma_f32_16x16x32_bf16 v[120:123], v[162:165], v[186:189], v[120:123]
	v_mfma_f32_16x16x32_bf16 v[108:111], v[154:157], v[194:197], v[108:111]
	v_mfma_f32_16x16x32_bf16 v[104:107], v[162:165], v[194:197], v[104:107]
	v_mfma_f32_16x16x32_bf16 v[92:95], v[154:157], v[202:205], v[92:95]
	v_mfma_f32_16x16x32_bf16 v[88:91], v[162:165], v[202:205], v[88:91]
	v_mfma_f32_16x16x32_bf16 v[76:79], v[154:157], v[216:219], v[76:79]
	v_mfma_f32_16x16x32_bf16 v[72:75], v[162:165], v[216:219], v[72:75]
	s_nop 0
	s_nop 0
	v_mfma_f32_16x16x32_bf16 v[116:119], v[166:169], v[182:185], v[116:119]
	v_mfma_f32_16x16x32_bf16 v[112:115], v[174:177], v[182:185], v[112:115]
	v_mfma_f32_16x16x32_bf16 v[100:103], v[166:169], v[190:193], v[100:103]
	v_mfma_f32_16x16x32_bf16 v[96:99], v[174:177], v[190:193], v[96:99]
	v_mfma_f32_16x16x32_bf16 v[84:87], v[166:169], v[198:201], v[84:87]
	v_mfma_f32_16x16x32_bf16 v[80:83], v[174:177], v[198:201], v[80:83]
	v_mfma_f32_16x16x32_bf16 v[68:71], v[166:169], v[206:209], v[68:71]
	v_mfma_f32_16x16x32_bf16 v[64:67], v[174:177], v[206:209], v[64:67]
	v_mfma_f32_16x16x32_bf16 v[116:119], v[170:173], v[186:189], v[116:119]
	v_mfma_f32_16x16x32_bf16 v[112:115], v[178:181], v[186:189], v[112:115]
	v_mfma_f32_16x16x32_bf16 v[100:103], v[170:173], v[194:197], v[100:103]
	v_mfma_f32_16x16x32_bf16 v[96:99], v[178:181], v[194:197], v[96:99]
	v_mfma_f32_16x16x32_bf16 v[84:87], v[170:173], v[202:205], v[84:87]
	v_mfma_f32_16x16x32_bf16 v[80:83], v[178:181], v[202:205], v[80:83]
	v_mfma_f32_16x16x32_bf16 v[68:71], v[170:173], v[216:219], v[68:71]
	v_mfma_f32_16x16x32_bf16 v[64:67], v[178:181], v[216:219], v[64:67]
	s_nop 0
	s_barrier
; #define STAGE(bufoff, gbase) STAGE_(bufoff, gbase, voffA)
; #define STAGEB(bufoff, gbase) STAGE_(bufoff, gbase, voffB)
; #define LDA(dst, b, h) do { _Pragma("unroll") for (int m = 0; m < 4; ++m) _Pragma("unroll") for (int k = 0; k < 2; ++k) dst[m][k] = *LDSP(const bf16x8, lds + SA(b, h) + aoff + m * 2048 + k * 1024); } while (0)
; #define MMA(ai, bj, AT, BT) do { __builtin_amdgcn_s_setprio(1); \
;     _Pragma("unroll") for (int m = 0; m < 4; ++m) _Pragma("unroll") for (int n = 0; n < 2; ++n) _Pragma("unroll") for (int k = 0; k < 2; ++k) \
;       acc[ai][bj][m][n] = __builtin_amdgcn_mfma_f32_16x16x32_bf16(BT[n][k], AT[m][k], acc[ai][bj][m][n], 0, 0, 0); \
;     __builtin_amdgcn_s_setprio(0); } while (0)
; #define WAIT_V(n) asm volatile("s_waitcnt vmcnt(" #n ")" ::: "memory")
; #define WAIT_L(n) asm volatile("s_waitcnt lgkmcnt(" #n ")" ::: "memory")
; #define BAR __builtin_amdgcn_s_barrier()
; #define SCHED __builtin_amdgcn_sched_barrier(0)
; #define WAIT_V(n) asm volatile("s_waitcnt vmcnt(" #n ")" ::: "memory")
; #define BAR do { __builtin_amdgcn_sched_barrier(0); __builtin_amdgcn_s_barrier(); asm volatile("" ::: "memory"); __builtin_amdgcn_sched_barrier(0); } while (0)
; template <bool SP2, bool ALIGN_EPI, bool DUAL, class Epi> DI void gemm_phase2(const bf16_t* A, const bf16_t* Bt, const bf16_t* A2, const bf16_t* Bt2, int M, int N, int K, const Epi& E, lds_t* lds) {
;     ...
;     for (int t = 0; t < nt; t += 2) {
;       const bool last = (t == nt - 2);
;       const char* a1 = cA + (size_t)(t + 1) * kstep;
;       const char* a2 = last ? nA : cA + (size_t)(t + 2) * kstep; const char* b2 = last ? nB : cB + (size_t)(t + 2) * kstep;
;       const char* a3 = a2 + kstep; const char* b3 = b2 + kstep;
;     ...
;         LDA(At, 1, 1); STAGEB(SB(1, 0), b3); STAGEB(SB(1, 1), b3 + bstep); STAGE(SA(1, 0), a3);
;         WAIT_V(8); WAIT_L(0); BAR; MMA(1, 0, At, B0); MMA(1, 1, At, B1); BAR; SCHED;
	s_add_i32 s47, s47, s2
	v_lshl_add_u64 v[210:211], v[210:211], 0, s[16:17]
	s_mov_b32 m0, s47
	ds_read_b128 v[182:185], v148 offset:49152
	ds_read_b128 v[186:189], v148 offset:50176
	ds_read_b128 v[190:193], v148 offset:51200
	ds_read_b128 v[194:197], v148 offset:52224
	ds_read_b128 v[198:201], v148 offset:53248
	ds_read_b128 v[202:205], v148 offset:54272
	ds_read_b128 v[206:209], v148 offset:55296
	ds_read_b128 v[216:219], v148 offset:56320
	global_load_lds_dwordx4 v[210:211], off
	s_add_i32 m0, s47, 0x2000
	s_add_u32 s54, s54, 0x10080
	v_lshl_add_u64 v[210:211], v[220:221], 0, s[16:17]
	s_addc_u32 s55, s55, 0
	s_add_i32 s47, s58, s2
	global_load_lds_dwordx4 v[210:211], off
	v_lshl_add_u64 v[210:211], s[54:55], 0, v[132:133]
	s_mov_b32 m0, s47
	s_nop 0
	global_load_lds_dwordx4 v[210:211], off
	v_lshl_add_u64 v[210:211], s[54:55], 0, v[128:129]
	s_add_i32 m0, s47, 0x2000
	s_nop 0
	global_load_lds_dwordx4 v[210:211], off
	v_lshl_add_u64 v[210:211], v[222:223], 0, s[16:17]
	s_mov_b32 m0, s15
	s_nop 0
	global_load_lds_dwordx4 v[210:211], off
	v_lshl_add_u64 v[210:211], v[224:225], 0, s[16:17]
	s_mov_b32 m0, s18
	s_nop 0
	global_load_lds_dwordx4 v[210:211], off
	s_waitcnt vmcnt(8)
	s_waitcnt lgkmcnt(0)
	s_barrier
	s_nop 0
	s_waitcnt lgkmcnt(0)
	v_mfma_f32_16x16x32_bf16 v[60:63], v[150:153], v[182:185], v[60:63]
	v_mfma_f32_16x16x32_bf16 v[56:59], v[158:161], v[182:185], v[56:59]
	v_mfma_f32_16x16x32_bf16 v[44:47], v[150:153], v[190:193], v[44:47]
	v_mfma_f32_16x16x32_bf16 v[40:43], v[158:161], v[190:193], v[40:43]
	v_mfma_f32_16x16x32_bf16 v[28:31], v[150:153], v[198:201], v[28:31]
	v_mfma_f32_16x16x32_bf16 v[24:27], v[158:161], v[198:201], v[24:27]
	v_mfma_f32_16x16x32_bf16 v[12:15], v[150:153], v[206:209], v[12:15]
	v_mfma_f32_16x16x32_bf16 v[8:11], v[158:161], v[206:209], v[8:11]
	v_mfma_f32_16x16x32_bf16 v[60:63], v[154:157], v[186:189], v[60:63]
	v_mfma_f32_16x16x32_bf16 v[56:59], v[162:165], v[186:189], v[56:59]
	v_mfma_f32_16x16x32_bf16 v[44:47], v[154:157], v[194:197], v[44:47]
	v_mfma_f32_16x16x32_bf16 v[40:43], v[162:165], v[194:197], v[40:43]
	v_mfma_f32_16x16x32_bf16 v[28:31], v[154:157], v[202:205], v[28:31]
	v_mfma_f32_16x16x32_bf16 v[24:27], v[162:165], v[202:205], v[24:27]
	v_mfma_f32_16x16x32_bf16 v[12:15], v[154:157], v[216:219], v[12:15]
	v_mfma_f32_16x16x32_bf16 v[8:11], v[162:165], v[216:219], v[8:11]
	s_nop 0
	s_nop 0
	v_mfma_f32_16x16x32_bf16 v[52:55], v[166:169], v[182:185], v[52:55]
	v_mfma_f32_16x16x32_bf16 v[48:51], v[174:177], v[182:185], v[48:51]
	v_mfma_f32_16x16x32_bf16 v[36:39], v[166:169], v[190:193], v[36:39]
	v_mfma_f32_16x16x32_bf16 v[32:35], v[174:177], v[190:193], v[32:35]
	v_mfma_f32_16x16x32_bf16 v[20:23], v[166:169], v[198:201], v[20:23]
	v_mfma_f32_16x16x32_bf16 v[16:19], v[174:177], v[198:201], v[16:19]
	v_mfma_f32_16x16x32_bf16 v[4:7], v[166:169], v[206:209], v[4:7]
	v_mfma_f32_16x16x32_bf16 v[0:3], v[174:177], v[206:209], v[0:3]
	v_mfma_f32_16x16x32_bf16 v[52:55], v[170:173], v[186:189], v[52:55]
	v_mfma_f32_16x16x32_bf16 v[48:51], v[178:181], v[186:189], v[48:51]
	v_mfma_f32_16x16x32_bf16 v[36:39], v[170:173], v[194:197], v[36:39]
	v_mfma_f32_16x16x32_bf16 v[32:35], v[178:181], v[194:197], v[32:35]
	v_mfma_f32_16x16x32_bf16 v[20:23], v[170:173], v[202:205], v[20:23]
	v_mfma_f32_16x16x32_bf16 v[16:19], v[178:181], v[202:205], v[16:19]
	v_mfma_f32_16x16x32_bf16 v[4:7], v[170:173], v[216:219], v[4:7]
	v_mfma_f32_16x16x32_bf16 v[0:3], v[178:181], v[216:219], v[0:3]
	s_nop 0
	s_barrier
	s_add_i32 s37, s37, 2
	s_add_u32 s52, s52, 0x100
	s_addc_u32 s53, s53, 0
	s_add_u32 s34, s34, 0x100
	s_addc_u32 s35, s35, 0
	s_cmp_gt_u32 s37, 13
	s_cbranch_scc0 .LBB0_620
	s_and_b64 vcc, exec, s[30:31]
	s_cbranch_vccz .LBB0_623
	s_barrier

; #define STAGE(bufoff, gbase) STAGE_(bufoff, gbase, voffA)
; #define STAGEB(bufoff, gbase) STAGE_(bufoff, gbase, voffB)
; #define LDA(dst, b, h) do { _Pragma("unroll") for (int m = 0; m < 4; ++m) _Pragma("unroll") for (int k = 0; k < 2; ++k) dst[m][k] = *LDSP(const bf16x8, lds + SA(b, h) + aoff + m * 2048 + k * 1024); } while (0)
; #define LDB(dst, b, h) do { _Pragma("unroll") for (int n = 0; n < 2; ++n) _Pragma("unroll") for (int k = 0; k < 2; ++k) dst[n][k] = *LDSP(const bf16x8, lds + SB(b, h) + boff + n * 2048 + k * 1024); } while (0)
; #define MMA(ai, bj, AT, BT) do { __builtin_amdgcn_s_setprio(1); \
;     _Pragma("unroll") for (int m = 0; m < 4; ++m) _Pragma("unroll") for (int n = 0; n < 2; ++n) _Pragma("unroll") for (int k = 0; k < 2; ++k) \
;       acc[ai][bj][m][n] = __builtin_amdgcn_mfma_f32_16x16x32_bf16(BT[n][k], AT[m][k], acc[ai][bj][m][n], 0, 0, 0); \
;     __builtin_amdgcn_s_setprio(0); } while (0)
; #define WAIT_V(n) asm volatile("s_waitcnt vmcnt(" #n ")" ::: "memory")
; #define WAIT_L(n) asm volatile("s_waitcnt lgkmcnt(" #n ")" ::: "memory")
; #define BAR __builtin_amdgcn_s_barrier()
; #define SCHED __builtin_amdgcn_sched_barrier(0)
; #define WAIT_V(n) asm volatile("s_waitcnt vmcnt(" #n ")" ::: "memory")
; #define BAR do { __builtin_amdgcn_sched_barrier(0); __builtin_amdgcn_s_barrier(); asm volatile("" ::: "memory"); __builtin_amdgcn_sched_barrier(0); } while (0)
; template <bool SP2, bool ALIGN_EPI, bool DUAL, class Epi> DI void gemm_phase2(const bf16_t* A, const bf16_t* Bt, const bf16_t* A2, const bf16_t* Bt2, int M, int N, int K, const Epi& E, lds_t* lds) {
;     ...
;     for (int t = 0; t < nt; t += 2) {
;       const bool last = (t == nt - 2);
;       const char* a1 = cA + (size_t)(t + 1) * kstep;
;       const char* a2 = last ? nA : cA + (size_t)(t + 2) * kstep; const char* b2 = last ? nB : cB + (size_t)(t + 2) * kstep;
;       const char* a3 = a2 + kstep; const char* b3 = b2 + kstep;
;       if constexpr (SP2) {
;         LDB(B0, 0, 0); LDB(B1, 0, 1); SCHED; LDA(At, 0, 0); STAGE(SA(1, 1), a1 + hstep);
;         WAIT_V(8); WAIT_L(0); BAR; MMA(0, 0, At, B0); MMA(0, 1, At, B1); BAR; SCHED;
;         LDA(At, 0, 1); STAGEB(SB(0, 0), b2); STAGEB(SB(0, 1), b2 + bstep); STAGE(SA(0, 0), a2);
;         WAIT_V(8); WAIT_L(0); BAR; MMA(1, 0, At, B0); MMA(1, 1, At, B1); BAR; SCHED;
.LBB0_691:
	ds_read_b128 v[152:155], v148
	ds_read_b128 v[156:159], v148 offset:1024
	ds_read_b128 v[160:163], v148 offset:2048
	ds_read_b128 v[164:167], v148 offset:3072
	ds_read_b128 v[168:171], v149
	ds_read_b128 v[172:175], v149 offset:1024
	ds_read_b128 v[176:179], v149 offset:2048
	ds_read_b128 v[180:183], v149 offset:3072
	s_add_u32 s34, s52, 0xfffc0080
	s_addc_u32 s35, s53, -1
	s_cmp_eq_u32 s33, 12
	s_cselect_b32 s57, s0, s35
	s_cselect_b32 s56, s1, s34
	s_cselect_b32 s55, s21, s31
	s_cselect_b32 s54, s22, s23
	v_lshl_add_u64 v[140:141], s[52:53], 0, v[136:137]
	s_add_i32 m0, s3, 0xc000
	ds_read_b128 v[184:187], v150
	ds_read_b128 v[188:191], v150 offset:1024
	ds_read_b128 v[192:195], v150 offset:2048
	ds_read_b128 v[196:199], v150 offset:3072
	ds_read_b128 v[200:203], v150 offset:4096
	ds_read_b128 v[204:207], v150 offset:5120
	ds_read_b128 v[208:211], v150 offset:6144
	ds_read_b128 v[216:219], v150 offset:7168
	global_load_lds_dwordx4 v[140:141], off
	v_lshl_add_u64 v[140:141], s[52:53], 0, v[138:139]
	s_add_i32 m0, s3, 0xe000
	s_nop 0
	global_load_lds_dwordx4 v[140:141], off
	s_waitcnt vmcnt(8)
	s_waitcnt lgkmcnt(0)
	s_barrier
	s_nop 0
	s_waitcnt lgkmcnt(0)
	v_mfma_f32_16x16x32_bf16 v[124:127], v[152:155], v[184:187], v[124:127]
	v_mfma_f32_16x16x32_bf16 v[120:123], v[160:163], v[184:187], v[120:123]
	v_mfma_f32_16x16x32_bf16 v[108:111], v[152:155], v[192:195], v[108:111]
	v_mfma_f32_16x16x32_bf16 v[104:107], v[160:163], v[192:195], v[104:107]
	v_mfma_f32_16x16x32_bf16 v[92:95], v[152:155], v[200:203], v[92:95]
	v_mfma_f32_16x16x32_bf16 v[88:91], v[160:163], v[200:203], v[88:91]
	v_mfma_f32_16x16x32_bf16 v[76:79], v[152:155], v[208:211], v[76:79]
	v_mfma_f32_16x16x32_bf16 v[72:75], v[160:163], v[208:211], v[72:75]
	v_mfma_f32_16x16x32_bf16 v[124:127], v[156:159], v[188:191], v[124:127]
	v_mfma_f32_16x16x32_bf16 v[120:123], v[164:167], v[188:191], v[120:123]
	v_mfma_f32_16x16x32_bf16 v[108:111], v[156:159], v[196:199], v[108:111]
	v_mfma_f32_16x16x32_bf16 v[104:107], v[164:167], v[196:199], v[104:107]
	v_mfma_f32_16x16x32_bf16 v[92:95], v[156:159], v[204:207], v[92:95]
	v_mfma_f32_16x16x32_bf16 v[88:91], v[164:167], v[204:207], v[88:91]
	v_mfma_f32_16x16x32_bf16 v[76:79], v[156:159], v[216:219], v[76:79]
	v_mfma_f32_16x16x32_bf16 v[72:75], v[164:167], v[216:219], v[72:75]
	s_nop 0
	s_nop 0
	v_mfma_f32_16x16x32_bf16 v[116:119], v[168:171], v[184:187], v[116:119]
	v_mfma_f32_16x16x32_bf16 v[112:115], v[176:179], v[184:187], v[112:115]
	v_mfma_f32_16x16x32_bf16 v[100:103], v[168:171], v[192:195], v[100:103]
	v_mfma_f32_16x16x32_bf16 v[96:99], v[176:179], v[192:195], v[96:99]
	v_mfma_f32_16x16x32_bf16 v[84:87], v[168:171], v[200:203], v[84:87]
	v_mfma_f32_16x16x32_bf16 v[80:83], v[176:179], v[200:203], v[80:83]
	v_mfma_f32_16x16x32_bf16 v[68:71], v[168:171], v[208:211], v[68:71]
	v_mfma_f32_16x16x32_bf16 v[64:67], v[176:179], v[208:211], v[64:67]
	v_mfma_f32_16x16x32_bf16 v[116:119], v[172:175], v[188:191], v[116:119]
	v_mfma_f32_16x16x32_bf16 v[112:115], v[180:183], v[188:191], v[112:115]
	v_mfma_f32_16x16x32_bf16 v[100:103], v[172:175], v[196:199], v[100:103]
	v_mfma_f32_16x16x32_bf16 v[96:99], v[180:183], v[196:199], v[96:99]
	v_mfma_f32_16x16x32_bf16 v[84:87], v[172:175], v[204:207], v[84:87]
	v_mfma_f32_16x16x32_bf16 v[80:83], v[180:183], v[204:207], v[80:83]
	v_mfma_f32_16x16x32_bf16 v[68:71], v[172:175], v[216:219], v[68:71]
	v_mfma_f32_16x16x32_bf16 v[64:67], v[180:183], v[216:219], v[64:67]
	s_nop 0
	s_barrier
	s_add_i32 s34, s18, s2
	v_lshl_add_u64 v[140:141], s[54:55], 0, v[130:131]
	s_mov_b32 m0, s34
	ds_read_b128 v[184:187], v150 offset:16384
	ds_read_b128 v[188:191], v150 offset:17408
	ds_read_b128 v[192:195], v150 offset:18432
	ds_read_b128 v[196:199], v150 offset:19456
	ds_read_b128 v[200:203], v150 offset:20480
	ds_read_b128 v[204:207], v150 offset:21504
	ds_read_b128 v[208:211], v150 offset:22528
	ds_read_b128 v[216:219], v150 offset:23552
	global_load_lds_dwordx4 v[140:141], off
	s_add_i32 m0, s34, 0x2000
	s_add_u32 s34, s54, 0x10000
	v_lshl_add_u64 v[220:221], s[54:55], 0, v[134:135]
	s_addc_u32 s35, s55, 0
	s_add_i32 s41, s19, s2
	global_load_lds_dwordx4 v[220:221], off
	v_lshl_add_u64 v[222:223], s[34:35], 0, v[130:131]
	s_mov_b32 m0, s41
	v_lshl_add_u64 v[224:225], s[56:57], 0, v[132:133]
	global_load_lds_dwordx4 v[222:223], off
	v_lshl_add_u64 v[222:223], s[34:35], 0, v[134:135]
	s_add_i32 m0, s41, 0x2000
	s_nop 0
	global_load_lds_dwordx4 v[222:223], off
	v_lshl_add_u64 v[222:223], s[56:57], 0, v[128:129]
	s_mov_b32 m0, s3
	s_nop 0
	global_load_lds_dwordx4 v[222:223], off
	s_mov_b32 m0, s8
	s_nop 0
	global_load_lds_dwordx4 v[224:225], off
	s_waitcnt vmcnt(8)
	s_waitcnt lgkmcnt(0)
	s_barrier
; #define STAGE(bufoff, gbase) STAGE_(bufoff, gbase, voffA)
; #define LDA(dst, b, h) do { _Pragma("unroll") for (int m = 0; m < 4; ++m) _Pragma("unroll") for (int k = 0; k < 2; ++k) dst[m][k] = *LDSP(const bf16x8, lds + SA(b, h) + aoff + m * 2048 + k * 1024); } while (0)
; #define LDB(dst, b, h) do { _Pragma("unroll") for (int n = 0; n < 2; ++n) _Pragma("unroll") for (int k = 0; k < 2; ++k) dst[n][k] = *LDSP(const bf16x8, lds + SB(b, h) + boff + n * 2048 + k * 1024); } while (0)
; #define MMA(ai, bj, AT, BT) do { __builtin_amdgcn_s_setprio(1); \
;     _Pragma("unroll") for (int m = 0; m < 4; ++m) _Pragma("unroll") for (int n = 0; n < 2; ++n) _Pragma("unroll") for (int k = 0; k < 2; ++k) \
;       acc[ai][bj][m][n] = __builtin_amdgcn_mfma_f32_16x16x32_bf16(BT[n][k], AT[m][k], acc[ai][bj][m][n], 0, 0, 0); \
;     __builtin_amdgcn_s_setprio(0); } while (0)
; #define WAIT_V(n) asm volatile("s_waitcnt vmcnt(" #n ")" ::: "memory")
; #define WAIT_L(n) asm volatile("s_waitcnt lgkmcnt(" #n ")" ::: "memory")
; #define BAR __builtin_amdgcn_s_barrier()
; #define SCHED __builtin_amdgcn_sched_barrier(0)
; #define WAIT_V(n) asm volatile("s_waitcnt vmcnt(" #n ")" ::: "memory")
; #define BAR do { __builtin_amdgcn_sched_barrier(0); __builtin_amdgcn_s_barrier(); asm volatile("" ::: "memory"); __builtin_amdgcn_sched_barrier(0); } while (0)
; template <bool SP2, bool ALIGN_EPI, bool DUAL, class Epi> DI void gemm_phase2(const bf16_t* A, const bf16_t* Bt, const bf16_t* A2, const bf16_t* Bt2, int M, int N, int K, const Epi& E, lds_t* lds) {
;     ...
;         WAIT_V(8); WAIT_L(0); BAR; MMA(1, 0, At, B0); MMA(1, 1, At, B1); BAR; SCHED;
;         LDB(B0, 1, 0); LDB(B1, 1, 1); SCHED; LDA(At, 1, 0); STAGE(SA(0, 1), a2 + hstep);
;         WAIT_V(8); WAIT_L(0); BAR; MMA(0, 0, At, B0); MMA(0, 1, At, B1); BAR; SCHED;
	s_nop 0
	s_waitcnt lgkmcnt(0)
	v_mfma_f32_16x16x32_bf16 v[60:63], v[152:155], v[184:187], v[60:63]
	v_mfma_f32_16x16x32_bf16 v[56:59], v[160:163], v[184:187], v[56:59]
	v_mfma_f32_16x16x32_bf16 v[44:47], v[152:155], v[192:195], v[44:47]
	v_mfma_f32_16x16x32_bf16 v[40:43], v[160:163], v[192:195], v[40:43]
	v_mfma_f32_16x16x32_bf16 v[28:31], v[152:155], v[200:203], v[28:31]
	v_mfma_f32_16x16x32_bf16 v[24:27], v[160:163], v[200:203], v[24:27]
	v_mfma_f32_16x16x32_bf16 v[12:15], v[152:155], v[208:211], v[12:15]
	v_mfma_f32_16x16x32_bf16 v[8:11], v[160:163], v[208:211], v[8:11]
	v_mfma_f32_16x16x32_bf16 v[60:63], v[156:159], v[188:191], v[60:63]
	v_mfma_f32_16x16x32_bf16 v[56:59], v[164:167], v[188:191], v[56:59]
	v_mfma_f32_16x16x32_bf16 v[44:47], v[156:159], v[196:199], v[44:47]
	v_mfma_f32_16x16x32_bf16 v[40:43], v[164:167], v[196:199], v[40:43]
	v_mfma_f32_16x16x32_bf16 v[28:31], v[156:159], v[204:207], v[28:31]
	v_mfma_f32_16x16x32_bf16 v[24:27], v[164:167], v[204:207], v[24:27]
	v_mfma_f32_16x16x32_bf16 v[12:15], v[156:159], v[216:219], v[12:15]
	v_mfma_f32_16x16x32_bf16 v[8:11], v[164:167], v[216:219], v[8:11]
	s_nop 0
	s_nop 0
	v_mfma_f32_16x16x32_bf16 v[52:55], v[168:171], v[184:187], v[52:55]
	v_mfma_f32_16x16x32_bf16 v[48:51], v[176:179], v[184:187], v[48:51]
	v_mfma_f32_16x16x32_bf16 v[36:39], v[168:171], v[192:195], v[36:39]
	v_mfma_f32_16x16x32_bf16 v[32:35], v[176:179], v[192:195], v[32:35]
	v_mfma_f32_16x16x32_bf16 v[20:23], v[168:171], v[200:203], v[20:23]
	v_mfma_f32_16x16x32_bf16 v[16:19], v[176:179], v[200:203], v[16:19]
	v_mfma_f32_16x16x32_bf16 v[4:7], v[168:171], v[208:211], v[4:7]
	v_mfma_f32_16x16x32_bf16 v[0:3], v[176:179], v[208:211], v[0:3]
	v_mfma_f32_16x16x32_bf16 v[52:55], v[172:175], v[188:191], v[52:55]
	v_mfma_f32_16x16x32_bf16 v[48:51], v[180:183], v[188:191], v[48:51]
	v_mfma_f32_16x16x32_bf16 v[36:39], v[172:175], v[196:199], v[36:39]
	v_mfma_f32_16x16x32_bf16 v[32:35], v[180:183], v[196:199], v[32:35]
	v_mfma_f32_16x16x32_bf16 v[20:23], v[172:175], v[204:207], v[20:23]
	v_mfma_f32_16x16x32_bf16 v[16:19], v[180:183], v[204:207], v[16:19]
	v_mfma_f32_16x16x32_bf16 v[4:7], v[172:175], v[216:219], v[4:7]
	v_mfma_f32_16x16x32_bf16 v[0:3], v[180:183], v[216:219], v[0:3]
	s_nop 0
	s_barrier
	s_add_i32 s41, 0, 0x18000
	s_add_i32 s49, 0, 0x1c000
	v_add_u32_e32 v164, s41, v143
	v_add_u32_e32 v180, s49, v143
	ds_read_b128 v[152:155], v164
	ds_read_b128 v[156:159], v164 offset:1024
	ds_read_b128 v[160:163], v164 offset:2048
	ds_read_b128 v[164:167], v164 offset:3072
	ds_read_b128 v[168:171], v180
	ds_read_b128 v[172:175], v180 offset:1024
	ds_read_b128 v[176:179], v180 offset:2048
	ds_read_b128 v[180:183], v180 offset:3072
	s_add_u32 s34, s56, 0x40000
	s_addc_u32 s35, s57, 0
	s_mov_b32 m0, s9
	v_lshl_add_u64 v[226:227], s[34:35], 0, v[128:129]
	ds_read_b128 v[184:187], v150 offset:32768
	ds_read_b128 v[188:191], v150 offset:33792
	ds_read_b128 v[192:195], v150 offset:34816
	ds_read_b128 v[196:199], v150 offset:35840
	ds_read_b128 v[200:203], v150 offset:36864
	ds_read_b128 v[204:207], v150 offset:37888
	ds_read_b128 v[208:211], v150 offset:38912
	ds_read_b128 v[216:219], v150 offset:39936
	global_load_lds_dwordx4 v[226:227], off
	v_lshl_add_u64 v[226:227], s[34:35], 0, v[132:133]
	s_mov_b32 m0, s10
	s_nop 0
	global_load_lds_dwordx4 v[226:227], off
	s_waitcnt vmcnt(8)
	s_waitcnt lgkmcnt(0)
	s_barrier
	s_nop 0
	s_waitcnt lgkmcnt(0)
	v_mfma_f32_16x16x32_bf16 v[124:127], v[152:155], v[184:187], v[124:127]
	v_mfma_f32_16x16x32_bf16 v[120:123], v[160:163], v[184:187], v[120:123]
	v_mfma_f32_16x16x32_bf16 v[108:111], v[152:155], v[192:195], v[108:111]
	v_mfma_f32_16x16x32_bf16 v[104:107], v[160:163], v[192:195], v[104:107]
	v_mfma_f32_16x16x32_bf16 v[92:95], v[152:155], v[200:203], v[92:95]
	v_mfma_f32_16x16x32_bf16 v[88:91], v[160:163], v[200:203], v[88:91]
	v_mfma_f32_16x16x32_bf16 v[76:79], v[152:155], v[208:211], v[76:79]
	v_mfma_f32_16x16x32_bf16 v[72:75], v[160:163], v[208:211], v[72:75]
	v_mfma_f32_16x16x32_bf16 v[124:127], v[156:159], v[188:191], v[124:127]
	v_mfma_f32_16x16x32_bf16 v[120:123], v[164:167], v[188:191], v[120:123]
	v_mfma_f32_16x16x32_bf16 v[108:111], v[156:159], v[196:199], v[108:111]
	v_mfma_f32_16x16x32_bf16 v[104:107], v[164:167], v[196:199], v[104:107]
	v_mfma_f32_16x16x32_bf16 v[92:95], v[156:159], v[204:207], v[92:95]
	v_mfma_f32_16x16x32_bf16 v[88:91], v[164:167], v[204:207], v[88:91]
	v_mfma_f32_16x16x32_bf16 v[76:79], v[156:159], v[216:219], v[76:79]
	v_mfma_f32_16x16x32_bf16 v[72:75], v[164:167], v[216:219], v[72:75]
	s_nop 0
	s_nop 0
	v_mfma_f32_16x16x32_bf16 v[116:119], v[168:171], v[184:187], v[116:119]
	v_mfma_f32_16x16x32_bf16 v[112:115], v[176:179], v[184:187], v[112:115]
	v_mfma_f32_16x16x32_bf16 v[100:103], v[168:171], v[192:195], v[100:103]
	v_mfma_f32_16x16x32_bf16 v[96:99], v[176:179], v[192:195], v[96:99]
	v_mfma_f32_16x16x32_bf16 v[84:87], v[168:171], v[200:203], v[84:87]
	v_mfma_f32_16x16x32_bf16 v[80:83], v[176:179], v[200:203], v[80:83]
	v_mfma_f32_16x16x32_bf16 v[68:71], v[168:171], v[208:211], v[68:71]
	v_mfma_f32_16x16x32_bf16 v[64:67], v[176:179], v[208:211], v[64:67]
	v_mfma_f32_16x16x32_bf16 v[116:119], v[172:175], v[188:191], v[116:119]
	v_mfma_f32_16x16x32_bf16 v[112:115], v[180:183], v[188:191], v[112:115]
	v_mfma_f32_16x16x32_bf16 v[100:103], v[172:175], v[196:199], v[100:103]
	v_mfma_f32_16x16x32_bf16 v[96:99], v[180:183], v[196:199], v[96:99]
	v_mfma_f32_16x16x32_bf16 v[84:87], v[172:175], v[204:207], v[84:87]
	v_mfma_f32_16x16x32_bf16 v[80:83], v[180:183], v[204:207], v[80:83]
	v_mfma_f32_16x16x32_bf16 v[68:71], v[172:175], v[216:219], v[68:71]
	v_mfma_f32_16x16x32_bf16 v[64:67], v[180:183], v[216:219], v[64:67]
	s_nop 0
	s_barrier
; #define STAGE(bufoff, gbase) STAGE_(bufoff, gbase, voffA)
; #define STAGEB(bufoff, gbase) STAGE_(bufoff, gbase, voffB)
; #define LDA(dst, b, h) do { _Pragma("unroll") for (int m = 0; m < 4; ++m) _Pragma("unroll") for (int k = 0; k < 2; ++k) dst[m][k] = *LDSP(const bf16x8, lds + SA(b, h) + aoff + m * 2048 + k * 1024); } while (0)
; #define MMA(ai, bj, AT, BT) do { __builtin_amdgcn_s_setprio(1); \
;     _Pragma("unroll") for (int m = 0; m < 4; ++m) _Pragma("unroll") for (int n = 0; n < 2; ++n) _Pragma("unroll") for (int k = 0; k < 2; ++k) \
;       acc[ai][bj][m][n] = __builtin_amdgcn_mfma_f32_16x16x32_bf16(BT[n][k], AT[m][k], acc[ai][bj][m][n], 0, 0, 0); \
;     __builtin_amdgcn_s_setprio(0); } while (0)
; #define WAIT_V(n) asm volatile("s_waitcnt vmcnt(" #n ")" ::: "memory")
; #define WAIT_L(n) asm volatile("s_waitcnt lgkmcnt(" #n ")" ::: "memory")
; #define BAR __builtin_amdgcn_s_barrier()
; #define SCHED __builtin_amdgcn_sched_barrier(0)
; #define WAIT_V(n) asm volatile("s_waitcnt vmcnt(" #n ")" ::: "memory")
; #define BAR do { __builtin_amdgcn_sched_barrier(0); __builtin_amdgcn_s_barrier(); asm volatile("" ::: "memory"); __builtin_amdgcn_sched_barrier(0); } while (0)
; template <bool SP2, bool ALIGN_EPI, bool DUAL, class Epi> DI void gemm_phase2(const bf16_t* A, const bf16_t* Bt, const bf16_t* A2, const bf16_t* Bt2, int M, int N, int K, const Epi& E, lds_t* lds) {
;     ...
;     for (int t = 0; t < nt; t += 2) {
;       const bool last = (t == nt - 2);
;       const char* a1 = cA + (size_t)(t + 1) * kstep;
;       const char* a2 = last ? nA : cA + (size_t)(t + 2) * kstep; const char* b2 = last ? nB : cB + (size_t)(t + 2) * kstep;
;       const char* a3 = a2 + kstep; const char* b3 = b2 + kstep;
;     ...
;         LDA(At, 1, 1); STAGEB(SB(1, 0), b3); STAGEB(SB(1, 1), b3 + bstep); STAGE(SA(1, 0), a3);
;         WAIT_V(8); WAIT_L(0); BAR; MMA(1, 0, At, B0); MMA(1, 1, At, B1); BAR; SCHED;
	s_add_i32 s34, s41, s2
	v_lshl_add_u64 v[140:141], v[140:141], 0, s[28:29]
	s_mov_b32 m0, s34
	ds_read_b128 v[184:187], v150 offset:49152
	ds_read_b128 v[188:191], v150 offset:50176
	ds_read_b128 v[192:195], v150 offset:51200
	ds_read_b128 v[196:199], v150 offset:52224
	ds_read_b128 v[200:203], v150 offset:53248
	ds_read_b128 v[204:207], v150 offset:54272
	ds_read_b128 v[208:211], v150 offset:55296
	ds_read_b128 v[216:219], v150 offset:56320
	global_load_lds_dwordx4 v[140:141], off
	s_add_i32 m0, s34, 0x2000
	s_add_u32 s34, s54, 0x10080
	v_lshl_add_u64 v[140:141], v[220:221], 0, s[28:29]
	s_addc_u32 s35, s55, 0
	s_add_i32 s41, s49, s2
	global_load_lds_dwordx4 v[140:141], off
	v_lshl_add_u64 v[140:141], s[34:35], 0, v[130:131]
	s_mov_b32 m0, s41
	s_nop 0
	global_load_lds_dwordx4 v[140:141], off
	v_lshl_add_u64 v[140:141], s[34:35], 0, v[134:135]
	s_add_i32 m0, s41, 0x2000
	s_nop 0
	global_load_lds_dwordx4 v[140:141], off
	v_lshl_add_u64 v[140:141], v[222:223], 0, s[28:29]
	s_mov_b32 m0, s14
	s_nop 0
	global_load_lds_dwordx4 v[140:141], off
	v_lshl_add_u64 v[140:141], v[224:225], 0, s[28:29]
	s_mov_b32 m0, s15
	s_nop 0
	global_load_lds_dwordx4 v[140:141], off
	s_waitcnt vmcnt(8)
	s_waitcnt lgkmcnt(0)
	s_barrier
	s_nop 0
	s_waitcnt lgkmcnt(0)
	v_mfma_f32_16x16x32_bf16 v[60:63], v[152:155], v[184:187], v[60:63]
	v_mfma_f32_16x16x32_bf16 v[56:59], v[160:163], v[184:187], v[56:59]
	v_mfma_f32_16x16x32_bf16 v[44:47], v[152:155], v[192:195], v[44:47]
	v_mfma_f32_16x16x32_bf16 v[40:43], v[160:163], v[192:195], v[40:43]
	v_mfma_f32_16x16x32_bf16 v[28:31], v[152:155], v[200:203], v[28:31]
	v_mfma_f32_16x16x32_bf16 v[24:27], v[160:163], v[200:203], v[24:27]
	v_mfma_f32_16x16x32_bf16 v[12:15], v[152:155], v[208:211], v[12:15]
	v_mfma_f32_16x16x32_bf16 v[8:11], v[160:163], v[208:211], v[8:11]
	v_mfma_f32_16x16x32_bf16 v[60:63], v[156:159], v[188:191], v[60:63]
	v_mfma_f32_16x16x32_bf16 v[56:59], v[164:167], v[188:191], v[56:59]
	v_mfma_f32_16x16x32_bf16 v[44:47], v[156:159], v[196:199], v[44:47]
	v_mfma_f32_16x16x32_bf16 v[40:43], v[164:167], v[196:199], v[40:43]
	v_mfma_f32_16x16x32_bf16 v[28:31], v[156:159], v[204:207], v[28:31]
	v_mfma_f32_16x16x32_bf16 v[24:27], v[164:167], v[204:207], v[24:27]
	v_mfma_f32_16x16x32_bf16 v[12:15], v[156:159], v[216:219], v[12:15]
	v_mfma_f32_16x16x32_bf16 v[8:11], v[164:167], v[216:219], v[8:11]
	s_nop 0
	s_nop 0
	v_mfma_f32_16x16x32_bf16 v[52:55], v[168:171], v[184:187], v[52:55]
	v_mfma_f32_16x16x32_bf16 v[48:51], v[176:179], v[184:187], v[48:51]
	v_mfma_f32_16x16x32_bf16 v[36:39], v[168:171], v[192:195], v[36:39]
	v_mfma_f32_16x16x32_bf16 v[32:35], v[176:179], v[192:195], v[32:35]
	v_mfma_f32_16x16x32_bf16 v[20:23], v[168:171], v[200:203], v[20:23]
	v_mfma_f32_16x16x32_bf16 v[16:19], v[176:179], v[200:203], v[16:19]
	v_mfma_f32_16x16x32_bf16 v[4:7], v[168:171], v[208:211], v[4:7]
	v_mfma_f32_16x16x32_bf16 v[0:3], v[176:179], v[208:211], v[0:3]
	v_mfma_f32_16x16x32_bf16 v[52:55], v[172:175], v[188:191], v[52:55]
	v_mfma_f32_16x16x32_bf16 v[48:51], v[180:183], v[188:191], v[48:51]
	v_mfma_f32_16x16x32_bf16 v[36:39], v[172:175], v[196:199], v[36:39]
	v_mfma_f32_16x16x32_bf16 v[32:35], v[180:183], v[196:199], v[32:35]
	v_mfma_f32_16x16x32_bf16 v[20:23], v[172:175], v[204:207], v[20:23]
	v_mfma_f32_16x16x32_bf16 v[16:19], v[180:183], v[204:207], v[16:19]
	v_mfma_f32_16x16x32_bf16 v[4:7], v[172:175], v[216:219], v[4:7]
	v_mfma_f32_16x16x32_bf16 v[0:3], v[180:183], v[216:219], v[0:3]
	s_nop 0
	s_barrier
	s_add_i32 s33, s33, 2
	s_add_u32 s52, s52, 0x100
	s_addc_u32 s53, s53, 0
	s_add_u32 s23, s23, 0x100
	s_addc_u32 s31, s31, 0
	s_cmp_gt_u32 s33, 13
	s_cbranch_scc0 .LBB0_691
	s_and_b64 vcc, exec, s[36:37]
	s_cbranch_vccz .LBB0_694
	s_barrier

; #define STAGE(bufoff, gbase) STAGE_(bufoff, gbase, voffA)
; #define STAGEB(bufoff, gbase) STAGE_(bufoff, gbase, voffB)
; #define LDA(dst, b, h) do { _Pragma("unroll") for (int m = 0; m < 4; ++m) _Pragma("unroll") for (int k = 0; k < 2; ++k) dst[m][k] = *LDSP(const bf16x8, lds + SA(b, h) + aoff + m * 2048 + k * 1024); } while (0)
; #define LDB(dst, b, h) do { _Pragma("unroll") for (int n = 0; n < 2; ++n) _Pragma("unroll") for (int k = 0; k < 2; ++k) dst[n][k] = *LDSP(const bf16x8, lds + SB(b, h) + boff + n * 2048 + k * 1024); } while (0)
; #define MMA(ai, bj, AT, BT) do { __builtin_amdgcn_s_setprio(1); \
;     _Pragma("unroll") for (int m = 0; m < 4; ++m) _Pragma("unroll") for (int n = 0; n < 2; ++n) _Pragma("unroll") for (int k = 0; k < 2; ++k) \
;       acc[ai][bj][m][n] = __builtin_amdgcn_mfma_f32_16x16x32_bf16(BT[n][k], AT[m][k], acc[ai][bj][m][n], 0, 0, 0); \
;     __builtin_amdgcn_s_setprio(0); } while (0)
; #define WAIT_V(n) asm volatile("s_waitcnt vmcnt(" #n ")" ::: "memory")
; #define WAIT_L(n) asm volatile("s_waitcnt lgkmcnt(" #n ")" ::: "memory")
; #define BAR __builtin_amdgcn_s_barrier()
; #define SCHED __builtin_amdgcn_sched_barrier(0)
; #define WAIT_V(n) asm volatile("s_waitcnt vmcnt(" #n ")" ::: "memory")
; #define BAR do { __builtin_amdgcn_sched_barrier(0); __builtin_amdgcn_s_barrier(); asm volatile("" ::: "memory"); __builtin_amdgcn_sched_barrier(0); } while (0)
; template <bool SP2, bool ALIGN_EPI, bool DUAL, class Epi> DI void gemm_phase2(const bf16_t* A, const bf16_t* Bt, const bf16_t* A2, const bf16_t* Bt2, int M, int N, int K, const Epi& E, lds_t* lds) {
;     ...
;     for (int t = 0; t < nt; t += 2) {
;       const bool last = (t == nt - 2);
;       const char* a1 = cA + (size_t)(t + 1) * kstep;
;       const char* a2 = last ? nA : cA + (size_t)(t + 2) * kstep; const char* b2 = last ? nB : cB + (size_t)(t + 2) * kstep;
;       const char* a3 = a2 + kstep; const char* b3 = b2 + kstep;
;       if constexpr (SP2) {
;         LDB(B0, 0, 0); LDB(B1, 0, 1); SCHED; LDA(At, 0, 0); STAGE(SA(1, 1), a1 + hstep);
;         WAIT_V(8); WAIT_L(0); BAR; MMA(0, 0, At, B0); MMA(0, 1, At, B1); BAR; SCHED;
;         LDA(At, 0, 1); STAGEB(SB(0, 0), b2); STAGEB(SB(0, 1), b2 + bstep); STAGE(SA(0, 0), a2);
;         WAIT_V(8); WAIT_L(0); BAR; MMA(1, 0, At, B0); MMA(1, 1, At, B1); BAR; SCHED;
.LBB0_760:
	ds_read_b128 v[150:153], v146
	ds_read_b128 v[154:157], v146 offset:1024
	ds_read_b128 v[158:161], v146 offset:2048
	ds_read_b128 v[162:165], v146 offset:3072
	ds_read_b128 v[166:169], v147
	ds_read_b128 v[170:173], v147 offset:1024
	ds_read_b128 v[174:177], v147 offset:2048
	ds_read_b128 v[178:181], v147 offset:3072
	s_add_u32 s46, s44, 0xfffc0080
	s_addc_u32 s47, s45, -1
	s_cmp_eq_u32 s50, 12
	s_cselect_b32 s49, s0, s47
	s_cselect_b32 s48, s27, s46
	s_cselect_b32 s47, s31, s43
	s_cselect_b32 s46, s34, s35
	v_lshl_add_u64 v[210:211], s[44:45], 0, v[136:137]
	s_add_i32 m0, s3, 0xc000
	ds_read_b128 v[182:185], v148
	ds_read_b128 v[186:189], v148 offset:1024
	ds_read_b128 v[190:193], v148 offset:2048
	ds_read_b128 v[194:197], v148 offset:3072
	ds_read_b128 v[198:201], v148 offset:4096
	ds_read_b128 v[202:205], v148 offset:5120
	ds_read_b128 v[206:209], v148 offset:6144
	ds_read_b128 v[216:219], v148 offset:7168
	global_load_lds_dwordx4 v[210:211], off
	v_lshl_add_u64 v[210:211], s[44:45], 0, v[138:139]
	s_add_i32 m0, s3, 0xe000
	s_nop 0
	global_load_lds_dwordx4 v[210:211], off
	s_waitcnt vmcnt(8)
	s_waitcnt lgkmcnt(0)
	s_barrier
	s_nop 0
	s_waitcnt lgkmcnt(0)
	v_mfma_f32_16x16x32_bf16 v[124:127], v[150:153], v[182:185], v[124:127]
	v_mfma_f32_16x16x32_bf16 v[120:123], v[158:161], v[182:185], v[120:123]
	v_mfma_f32_16x16x32_bf16 v[108:111], v[150:153], v[190:193], v[108:111]
	v_mfma_f32_16x16x32_bf16 v[104:107], v[158:161], v[190:193], v[104:107]
	v_mfma_f32_16x16x32_bf16 v[92:95], v[150:153], v[198:201], v[92:95]
	v_mfma_f32_16x16x32_bf16 v[88:91], v[158:161], v[198:201], v[88:91]
	v_mfma_f32_16x16x32_bf16 v[76:79], v[150:153], v[206:209], v[76:79]
	v_mfma_f32_16x16x32_bf16 v[72:75], v[158:161], v[206:209], v[72:75]
	v_mfma_f32_16x16x32_bf16 v[124:127], v[154:157], v[186:189], v[124:127]
	v_mfma_f32_16x16x32_bf16 v[120:123], v[162:165], v[186:189], v[120:123]
	v_mfma_f32_16x16x32_bf16 v[108:111], v[154:157], v[194:197], v[108:111]
	v_mfma_f32_16x16x32_bf16 v[104:107], v[162:165], v[194:197], v[104:107]
	v_mfma_f32_16x16x32_bf16 v[92:95], v[154:157], v[202:205], v[92:95]
	v_mfma_f32_16x16x32_bf16 v[88:91], v[162:165], v[202:205], v[88:91]
	v_mfma_f32_16x16x32_bf16 v[76:79], v[154:157], v[216:219], v[76:79]
	v_mfma_f32_16x16x32_bf16 v[72:75], v[162:165], v[216:219], v[72:75]
	s_nop 0
	s_nop 0
	v_mfma_f32_16x16x32_bf16 v[116:119], v[166:169], v[182:185], v[116:119]
	v_mfma_f32_16x16x32_bf16 v[112:115], v[174:177], v[182:185], v[112:115]
	v_mfma_f32_16x16x32_bf16 v[100:103], v[166:169], v[190:193], v[100:103]
	v_mfma_f32_16x16x32_bf16 v[96:99], v[174:177], v[190:193], v[96:99]
	v_mfma_f32_16x16x32_bf16 v[84:87], v[166:169], v[198:201], v[84:87]
	v_mfma_f32_16x16x32_bf16 v[80:83], v[174:177], v[198:201], v[80:83]
	v_mfma_f32_16x16x32_bf16 v[68:71], v[166:169], v[206:209], v[68:71]
	v_mfma_f32_16x16x32_bf16 v[64:67], v[174:177], v[206:209], v[64:67]
	v_mfma_f32_16x16x32_bf16 v[116:119], v[170:173], v[186:189], v[116:119]
	v_mfma_f32_16x16x32_bf16 v[112:115], v[178:181], v[186:189], v[112:115]
	v_mfma_f32_16x16x32_bf16 v[100:103], v[170:173], v[194:197], v[100:103]
	v_mfma_f32_16x16x32_bf16 v[96:99], v[178:181], v[194:197], v[96:99]
	v_mfma_f32_16x16x32_bf16 v[84:87], v[170:173], v[202:205], v[84:87]
	v_mfma_f32_16x16x32_bf16 v[80:83], v[178:181], v[202:205], v[80:83]
	v_mfma_f32_16x16x32_bf16 v[68:71], v[170:173], v[216:219], v[68:71]
	v_mfma_f32_16x16x32_bf16 v[64:67], v[178:181], v[216:219], v[64:67]
	s_nop 0
	s_barrier
	s_add_i32 s51, s19, s2
	v_lshl_add_u64 v[210:211], s[46:47], 0, v[132:133]
	s_mov_b32 m0, s51
	ds_read_b128 v[182:185], v148 offset:16384
	ds_read_b128 v[186:189], v148 offset:17408
	ds_read_b128 v[190:193], v148 offset:18432
	ds_read_b128 v[194:197], v148 offset:19456
	ds_read_b128 v[198:201], v148 offset:20480
	ds_read_b128 v[202:205], v148 offset:21504
	ds_read_b128 v[206:209], v148 offset:22528
	ds_read_b128 v[216:219], v148 offset:23552
	global_load_lds_dwordx4 v[210:211], off
	s_add_i32 m0, s51, 0x2000
	s_add_u32 s52, s46, 0x10000
	v_lshl_add_u64 v[220:221], s[46:47], 0, v[128:129]
	s_addc_u32 s53, s47, 0
	s_add_i32 s51, s20, s2
	global_load_lds_dwordx4 v[220:221], off
	v_lshl_add_u64 v[222:223], s[52:53], 0, v[132:133]
	s_mov_b32 m0, s51
	v_lshl_add_u64 v[224:225], s[48:49], 0, v[130:131]
	global_load_lds_dwordx4 v[222:223], off
	v_lshl_add_u64 v[222:223], s[52:53], 0, v[128:129]
	s_add_i32 m0, s51, 0x2000
	s_nop 0
	global_load_lds_dwordx4 v[222:223], off
	v_lshl_add_u64 v[222:223], s[48:49], 0, v[134:135]
	s_mov_b32 m0, s3
	s_nop 0
	global_load_lds_dwordx4 v[222:223], off
	s_mov_b32 m0, s8
	s_nop 0
	global_load_lds_dwordx4 v[224:225], off
	s_waitcnt vmcnt(8)
	s_waitcnt lgkmcnt(0)
	s_barrier
; #define STAGE(bufoff, gbase) STAGE_(bufoff, gbase, voffA)
; #define LDA(dst, b, h) do { _Pragma("unroll") for (int m = 0; m < 4; ++m) _Pragma("unroll") for (int k = 0; k < 2; ++k) dst[m][k] = *LDSP(const bf16x8, lds + SA(b, h) + aoff + m * 2048 + k * 1024); } while (0)
; #define LDB(dst, b, h) do { _Pragma("unroll") for (int n = 0; n < 2; ++n) _Pragma("unroll") for (int k = 0; k < 2; ++k) dst[n][k] = *LDSP(const bf16x8, lds + SB(b, h) + boff + n * 2048 + k * 1024); } while (0)
; #define MMA(ai, bj, AT, BT) do { __builtin_amdgcn_s_setprio(1); \
;     _Pragma("unroll") for (int m = 0; m < 4; ++m) _Pragma("unroll") for (int n = 0; n < 2; ++n) _Pragma("unroll") for (int k = 0; k < 2; ++k) \
;       acc[ai][bj][m][n] = __builtin_amdgcn_mfma_f32_16x16x32_bf16(BT[n][k], AT[m][k], acc[ai][bj][m][n], 0, 0, 0); \
;     __builtin_amdgcn_s_setprio(0); } while (0)
; #define WAIT_V(n) asm volatile("s_waitcnt vmcnt(" #n ")" ::: "memory")
; #define WAIT_L(n) asm volatile("s_waitcnt lgkmcnt(" #n ")" ::: "memory")
; #define BAR __builtin_amdgcn_s_barrier()
; #define SCHED __builtin_amdgcn_sched_barrier(0)
; #define WAIT_V(n) asm volatile("s_waitcnt vmcnt(" #n ")" ::: "memory")
; #define BAR do { __builtin_amdgcn_sched_barrier(0); __builtin_amdgcn_s_barrier(); asm volatile("" ::: "memory"); __builtin_amdgcn_sched_barrier(0); } while (0)
; template <bool SP2, bool ALIGN_EPI, bool DUAL, class Epi> DI void gemm_phase2(const bf16_t* A, const bf16_t* Bt, const bf16_t* A2, const bf16_t* Bt2, int M, int N, int K, const Epi& E, lds_t* lds) {
;     ...
;         WAIT_V(8); WAIT_L(0); BAR; MMA(1, 0, At, B0); MMA(1, 1, At, B1); BAR; SCHED;
;         LDB(B0, 1, 0); LDB(B1, 1, 1); SCHED; LDA(At, 1, 0); STAGE(SA(0, 1), a2 + hstep);
;         WAIT_V(8); WAIT_L(0); BAR; MMA(0, 0, At, B0); MMA(0, 1, At, B1); BAR; SCHED;
	s_nop 0
	s_waitcnt lgkmcnt(0)
	v_mfma_f32_16x16x32_bf16 v[60:63], v[150:153], v[182:185], v[60:63]
	v_mfma_f32_16x16x32_bf16 v[56:59], v[158:161], v[182:185], v[56:59]
	v_mfma_f32_16x16x32_bf16 v[44:47], v[150:153], v[190:193], v[44:47]
	v_mfma_f32_16x16x32_bf16 v[40:43], v[158:161], v[190:193], v[40:43]
	v_mfma_f32_16x16x32_bf16 v[28:31], v[150:153], v[198:201], v[28:31]
	v_mfma_f32_16x16x32_bf16 v[24:27], v[158:161], v[198:201], v[24:27]
	v_mfma_f32_16x16x32_bf16 v[12:15], v[150:153], v[206:209], v[12:15]
	v_mfma_f32_16x16x32_bf16 v[8:11], v[158:161], v[206:209], v[8:11]
	v_mfma_f32_16x16x32_bf16 v[60:63], v[154:157], v[186:189], v[60:63]
	v_mfma_f32_16x16x32_bf16 v[56:59], v[162:165], v[186:189], v[56:59]
	v_mfma_f32_16x16x32_bf16 v[44:47], v[154:157], v[194:197], v[44:47]
	v_mfma_f32_16x16x32_bf16 v[40:43], v[162:165], v[194:197], v[40:43]
	v_mfma_f32_16x16x32_bf16 v[28:31], v[154:157], v[202:205], v[28:31]
	v_mfma_f32_16x16x32_bf16 v[24:27], v[162:165], v[202:205], v[24:27]
	v_mfma_f32_16x16x32_bf16 v[12:15], v[154:157], v[216:219], v[12:15]
	v_mfma_f32_16x16x32_bf16 v[8:11], v[162:165], v[216:219], v[8:11]
	s_nop 0
	s_nop 0
	v_mfma_f32_16x16x32_bf16 v[52:55], v[166:169], v[182:185], v[52:55]
	v_mfma_f32_16x16x32_bf16 v[48:51], v[174:177], v[182:185], v[48:51]
	v_mfma_f32_16x16x32_bf16 v[36:39], v[166:169], v[190:193], v[36:39]
	v_mfma_f32_16x16x32_bf16 v[32:35], v[174:177], v[190:193], v[32:35]
	v_mfma_f32_16x16x32_bf16 v[20:23], v[166:169], v[198:201], v[20:23]
	v_mfma_f32_16x16x32_bf16 v[16:19], v[174:177], v[198:201], v[16:19]
	v_mfma_f32_16x16x32_bf16 v[4:7], v[166:169], v[206:209], v[4:7]
	v_mfma_f32_16x16x32_bf16 v[0:3], v[174:177], v[206:209], v[0:3]
	v_mfma_f32_16x16x32_bf16 v[52:55], v[170:173], v[186:189], v[52:55]
	v_mfma_f32_16x16x32_bf16 v[48:51], v[178:181], v[186:189], v[48:51]
	v_mfma_f32_16x16x32_bf16 v[36:39], v[170:173], v[194:197], v[36:39]
	v_mfma_f32_16x16x32_bf16 v[32:35], v[178:181], v[194:197], v[32:35]
	v_mfma_f32_16x16x32_bf16 v[20:23], v[170:173], v[202:205], v[20:23]
	v_mfma_f32_16x16x32_bf16 v[16:19], v[178:181], v[202:205], v[16:19]
	v_mfma_f32_16x16x32_bf16 v[4:7], v[170:173], v[216:219], v[4:7]
	v_mfma_f32_16x16x32_bf16 v[0:3], v[178:181], v[216:219], v[0:3]
	s_nop 0
	s_barrier
	s_add_i32 s51, 0, 0x18000
	s_add_i32 s52, 0, 0x1c000
	v_add_u32_e32 v162, s51, v141
	v_add_u32_e32 v178, s52, v141
	ds_read_b128 v[150:153], v162
	ds_read_b128 v[154:157], v162 offset:1024
	ds_read_b128 v[158:161], v162 offset:2048
	ds_read_b128 v[162:165], v162 offset:3072
	ds_read_b128 v[166:169], v178
	ds_read_b128 v[170:173], v178 offset:1024
	ds_read_b128 v[174:177], v178 offset:2048
	ds_read_b128 v[178:181], v178 offset:3072
	s_add_u32 s48, s48, 0x40000
	s_addc_u32 s49, s49, 0
	s_mov_b32 m0, s9
	v_lshl_add_u64 v[226:227], s[48:49], 0, v[134:135]
	ds_read_b128 v[182:185], v148 offset:32768
	ds_read_b128 v[186:189], v148 offset:33792
	ds_read_b128 v[190:193], v148 offset:34816
	ds_read_b128 v[194:197], v148 offset:35840
	ds_read_b128 v[198:201], v148 offset:36864
	ds_read_b128 v[202:205], v148 offset:37888
	ds_read_b128 v[206:209], v148 offset:38912
	ds_read_b128 v[216:219], v148 offset:39936
	global_load_lds_dwordx4 v[226:227], off
	v_lshl_add_u64 v[226:227], s[48:49], 0, v[130:131]
	s_mov_b32 m0, s10
	s_nop 0
	global_load_lds_dwordx4 v[226:227], off
	s_waitcnt vmcnt(8)
	s_waitcnt lgkmcnt(0)
	s_barrier
	s_nop 0
	s_waitcnt lgkmcnt(0)
	v_mfma_f32_16x16x32_bf16 v[124:127], v[150:153], v[182:185], v[124:127]
	v_mfma_f32_16x16x32_bf16 v[120:123], v[158:161], v[182:185], v[120:123]
	v_mfma_f32_16x16x32_bf16 v[108:111], v[150:153], v[190:193], v[108:111]
	v_mfma_f32_16x16x32_bf16 v[104:107], v[158:161], v[190:193], v[104:107]
	v_mfma_f32_16x16x32_bf16 v[92:95], v[150:153], v[198:201], v[92:95]
	v_mfma_f32_16x16x32_bf16 v[88:91], v[158:161], v[198:201], v[88:91]
	v_mfma_f32_16x16x32_bf16 v[76:79], v[150:153], v[206:209], v[76:79]
	v_mfma_f32_16x16x32_bf16 v[72:75], v[158:161], v[206:209], v[72:75]
	v_mfma_f32_16x16x32_bf16 v[124:127], v[154:157], v[186:189], v[124:127]
	v_mfma_f32_16x16x32_bf16 v[120:123], v[162:165], v[186:189], v[120:123]
	v_mfma_f32_16x16x32_bf16 v[108:111], v[154:157], v[194:197], v[108:111]
	v_mfma_f32_16x16x32_bf16 v[104:107], v[162:165], v[194:197], v[104:107]
	v_mfma_f32_16x16x32_bf16 v[92:95], v[154:157], v[202:205], v[92:95]
	v_mfma_f32_16x16x32_bf16 v[88:91], v[162:165], v[202:205], v[88:91]
	v_mfma_f32_16x16x32_bf16 v[76:79], v[154:157], v[216:219], v[76:79]
	v_mfma_f32_16x16x32_bf16 v[72:75], v[162:165], v[216:219], v[72:75]
	s_nop 0
	s_nop 0
	v_mfma_f32_16x16x32_bf16 v[116:119], v[166:169], v[182:185], v[116:119]
	v_mfma_f32_16x16x32_bf16 v[112:115], v[174:177], v[182:185], v[112:115]
	v_mfma_f32_16x16x32_bf16 v[100:103], v[166:169], v[190:193], v[100:103]
	v_mfma_f32_16x16x32_bf16 v[96:99], v[174:177], v[190:193], v[96:99]
	v_mfma_f32_16x16x32_bf16 v[84:87], v[166:169], v[198:201], v[84:87]
	v_mfma_f32_16x16x32_bf16 v[80:83], v[174:177], v[198:201], v[80:83]
	v_mfma_f32_16x16x32_bf16 v[68:71], v[166:169], v[206:209], v[68:71]
	v_mfma_f32_16x16x32_bf16 v[64:67], v[174:177], v[206:209], v[64:67]
	v_mfma_f32_16x16x32_bf16 v[116:119], v[170:173], v[186:189], v[116:119]
	v_mfma_f32_16x16x32_bf16 v[112:115], v[178:181], v[186:189], v[112:115]
	v_mfma_f32_16x16x32_bf16 v[100:103], v[170:173], v[194:197], v[100:103]
	v_mfma_f32_16x16x32_bf16 v[96:99], v[178:181], v[194:197], v[96:99]
	v_mfma_f32_16x16x32_bf16 v[84:87], v[170:173], v[202:205], v[84:87]
	v_mfma_f32_16x16x32_bf16 v[80:83], v[178:181], v[202:205], v[80:83]
	v_mfma_f32_16x16x32_bf16 v[68:71], v[170:173], v[216:219], v[68:71]
	v_mfma_f32_16x16x32_bf16 v[64:67], v[178:181], v[216:219], v[64:67]
	s_nop 0
	s_barrier
; #define STAGE(bufoff, gbase) STAGE_(bufoff, gbase, voffA)
; #define STAGEB(bufoff, gbase) STAGE_(bufoff, gbase, voffB)
; #define LDA(dst, b, h) do { _Pragma("unroll") for (int m = 0; m < 4; ++m) _Pragma("unroll") for (int k = 0; k < 2; ++k) dst[m][k] = *LDSP(const bf16x8, lds + SA(b, h) + aoff + m * 2048 + k * 1024); } while (0)
; #define MMA(ai, bj, AT, BT) do { __builtin_amdgcn_s_setprio(1); \
;     _Pragma("unroll") for (int m = 0; m < 4; ++m) _Pragma("unroll") for (int n = 0; n < 2; ++n) _Pragma("unroll") for (int k = 0; k < 2; ++k) \
;       acc[ai][bj][m][n] = __builtin_amdgcn_mfma_f32_16x16x32_bf16(BT[n][k], AT[m][k], acc[ai][bj][m][n], 0, 0, 0); \
;     __builtin_amdgcn_s_setprio(0); } while (0)
; #define WAIT_V(n) asm volatile("s_waitcnt vmcnt(" #n ")" ::: "memory")
; #define WAIT_L(n) asm volatile("s_waitcnt lgkmcnt(" #n ")" ::: "memory")
; #define BAR __builtin_amdgcn_s_barrier()
; #define SCHED __builtin_amdgcn_sched_barrier(0)
; #define WAIT_V(n) asm volatile("s_waitcnt vmcnt(" #n ")" ::: "memory")
; #define BAR do { __builtin_amdgcn_sched_barrier(0); __builtin_amdgcn_s_barrier(); asm volatile("" ::: "memory"); __builtin_amdgcn_sched_barrier(0); } while (0)
; template <bool SP2, bool ALIGN_EPI, bool DUAL, class Epi> DI void gemm_phase2(const bf16_t* A, const bf16_t* Bt, const bf16_t* A2, const bf16_t* Bt2, int M, int N, int K, const Epi& E, lds_t* lds) {
;     ...
;     for (int t = 0; t < nt; t += 2) {
;       const bool last = (t == nt - 2);
;       const char* a1 = cA + (size_t)(t + 1) * kstep;
;       const char* a2 = last ? nA : cA + (size_t)(t + 2) * kstep; const char* b2 = last ? nB : cB + (size_t)(t + 2) * kstep;
;       const char* a3 = a2 + kstep; const char* b3 = b2 + kstep;
;     ...
;         LDA(At, 1, 1); STAGEB(SB(1, 0), b3); STAGEB(SB(1, 1), b3 + bstep); STAGE(SA(1, 0), a3);
;         WAIT_V(8); WAIT_L(0); BAR; MMA(1, 0, At, B0); MMA(1, 1, At, B1); BAR; SCHED;
	s_add_i32 s48, s51, s2
	v_lshl_add_u64 v[210:211], v[210:211], 0, s[22:23]
	s_mov_b32 m0, s48
	ds_read_b128 v[182:185], v148 offset:49152
	ds_read_b128 v[186:189], v148 offset:50176
	ds_read_b128 v[190:193], v148 offset:51200
	ds_read_b128 v[194:197], v148 offset:52224
	ds_read_b128 v[198:201], v148 offset:53248
	ds_read_b128 v[202:205], v148 offset:54272
	ds_read_b128 v[206:209], v148 offset:55296
	ds_read_b128 v[216:219], v148 offset:56320
	global_load_lds_dwordx4 v[210:211], off
	s_add_i32 m0, s48, 0x2000
	s_add_u32 s46, s46, 0x10080
	v_lshl_add_u64 v[210:211], v[220:221], 0, s[22:23]
	s_addc_u32 s47, s47, 0
	s_add_i32 s48, s52, s2
	global_load_lds_dwordx4 v[210:211], off
	v_lshl_add_u64 v[210:211], s[46:47], 0, v[132:133]
	s_mov_b32 m0, s48
	s_nop 0
	global_load_lds_dwordx4 v[210:211], off
	v_lshl_add_u64 v[210:211], s[46:47], 0, v[128:129]
	s_add_i32 m0, s48, 0x2000
	s_nop 0
	global_load_lds_dwordx4 v[210:211], off
	v_lshl_add_u64 v[210:211], v[222:223], 0, s[22:23]
	s_mov_b32 m0, s15
	s_nop 0
	global_load_lds_dwordx4 v[210:211], off
	v_lshl_add_u64 v[210:211], v[224:225], 0, s[22:23]
	s_mov_b32 m0, s18
	s_nop 0
	global_load_lds_dwordx4 v[210:211], off
	s_waitcnt vmcnt(8)
	s_waitcnt lgkmcnt(0)
	s_barrier
	s_nop 0
	s_waitcnt lgkmcnt(0)
	v_mfma_f32_16x16x32_bf16 v[60:63], v[150:153], v[182:185], v[60:63]
	v_mfma_f32_16x16x32_bf16 v[56:59], v[158:161], v[182:185], v[56:59]
	v_mfma_f32_16x16x32_bf16 v[44:47], v[150:153], v[190:193], v[44:47]
	v_mfma_f32_16x16x32_bf16 v[40:43], v[158:161], v[190:193], v[40:43]
	v_mfma_f32_16x16x32_bf16 v[28:31], v[150:153], v[198:201], v[28:31]
	v_mfma_f32_16x16x32_bf16 v[24:27], v[158:161], v[198:201], v[24:27]
	v_mfma_f32_16x16x32_bf16 v[12:15], v[150:153], v[206:209], v[12:15]
	v_mfma_f32_16x16x32_bf16 v[8:11], v[158:161], v[206:209], v[8:11]
	v_mfma_f32_16x16x32_bf16 v[60:63], v[154:157], v[186:189], v[60:63]
	v_mfma_f32_16x16x32_bf16 v[56:59], v[162:165], v[186:189], v[56:59]
	v_mfma_f32_16x16x32_bf16 v[44:47], v[154:157], v[194:197], v[44:47]
	v_mfma_f32_16x16x32_bf16 v[40:43], v[162:165], v[194:197], v[40:43]
	v_mfma_f32_16x16x32_bf16 v[28:31], v[154:157], v[202:205], v[28:31]
	v_mfma_f32_16x16x32_bf16 v[24:27], v[162:165], v[202:205], v[24:27]
	v_mfma_f32_16x16x32_bf16 v[12:15], v[154:157], v[216:219], v[12:15]
	v_mfma_f32_16x16x32_bf16 v[8:11], v[162:165], v[216:219], v[8:11]
	s_nop 0
	s_nop 0
	v_mfma_f32_16x16x32_bf16 v[52:55], v[166:169], v[182:185], v[52:55]
	v_mfma_f32_16x16x32_bf16 v[48:51], v[174:177], v[182:185], v[48:51]
	v_mfma_f32_16x16x32_bf16 v[36:39], v[166:169], v[190:193], v[36:39]
	v_mfma_f32_16x16x32_bf16 v[32:35], v[174:177], v[190:193], v[32:35]
	v_mfma_f32_16x16x32_bf16 v[20:23], v[166:169], v[198:201], v[20:23]
	v_mfma_f32_16x16x32_bf16 v[16:19], v[174:177], v[198:201], v[16:19]
	v_mfma_f32_16x16x32_bf16 v[4:7], v[166:169], v[206:209], v[4:7]
	v_mfma_f32_16x16x32_bf16 v[0:3], v[174:177], v[206:209], v[0:3]
	v_mfma_f32_16x16x32_bf16 v[52:55], v[170:173], v[186:189], v[52:55]
	v_mfma_f32_16x16x32_bf16 v[48:51], v[178:181], v[186:189], v[48:51]
	v_mfma_f32_16x16x32_bf16 v[36:39], v[170:173], v[194:197], v[36:39]
	v_mfma_f32_16x16x32_bf16 v[32:35], v[178:181], v[194:197], v[32:35]
	v_mfma_f32_16x16x32_bf16 v[20:23], v[170:173], v[202:205], v[20:23]
	v_mfma_f32_16x16x32_bf16 v[16:19], v[178:181], v[202:205], v[16:19]
	v_mfma_f32_16x16x32_bf16 v[4:7], v[170:173], v[216:219], v[4:7]
	v_mfma_f32_16x16x32_bf16 v[0:3], v[178:181], v[216:219], v[0:3]
	s_nop 0
	s_barrier
	s_add_i32 s50, s50, 2
	s_add_u32 s44, s44, 0x100
	s_addc_u32 s45, s45, 0
	s_add_u32 s35, s35, 0x100
	s_addc_u32 s43, s43, 0
	s_cmp_gt_u32 s50, 13
	s_cbranch_scc0 .LBB0_760
	s_and_b64 vcc, exec, s[28:29]
	s_cbranch_vccz .LBB0_763
	s_barrier

; #define STAGE(bufoff, gbase) STAGE_(bufoff, gbase, voffA)
; #define STAGEB(bufoff, gbase) STAGE_(bufoff, gbase, voffB)
; #define LDA(dst, b, h) do { _Pragma("unroll") for (int m = 0; m < 4; ++m) _Pragma("unroll") for (int k = 0; k < 2; ++k) dst[m][k] = *LDSP(const bf16x8, lds + SA(b, h) + aoff + m * 2048 + k * 1024); } while (0)
; #define LDB(dst, b, h) do { _Pragma("unroll") for (int n = 0; n < 2; ++n) _Pragma("unroll") for (int k = 0; k < 2; ++k) dst[n][k] = *LDSP(const bf16x8, lds + SB(b, h) + boff + n * 2048 + k * 1024); } while (0)
; #define MMA(ai, bj, AT, BT) do { __builtin_amdgcn_s_setprio(1); \
;     _Pragma("unroll") for (int m = 0; m < 4; ++m) _Pragma("unroll") for (int n = 0; n < 2; ++n) _Pragma("unroll") for (int k = 0; k < 2; ++k) \
;       acc[ai][bj][m][n] = __builtin_amdgcn_mfma_f32_16x16x32_bf16(BT[n][k], AT[m][k], acc[ai][bj][m][n], 0, 0, 0); \
;     __builtin_amdgcn_s_setprio(0); } while (0)
; #define WAIT_V(n) asm volatile("s_waitcnt vmcnt(" #n ")" ::: "memory")
; #define WAIT_L(n) asm volatile("s_waitcnt lgkmcnt(" #n ")" ::: "memory")
; #define BAR __builtin_amdgcn_s_barrier()
; #define SCHED __builtin_amdgcn_sched_barrier(0)
; #define WAIT_V(n) asm volatile("s_waitcnt vmcnt(" #n ")" ::: "memory")
; #define BAR do { __builtin_amdgcn_sched_barrier(0); __builtin_amdgcn_s_barrier(); asm volatile("" ::: "memory"); __builtin_amdgcn_sched_barrier(0); } while (0)
; template <bool SP2, bool ALIGN_EPI, bool DUAL, class Epi> DI void gemm_phase2(const bf16_t* A, const bf16_t* Bt, const bf16_t* A2, const bf16_t* Bt2, int M, int N, int K, const Epi& E, lds_t* lds) {
;     ...
;     for (int t = 0; t < nt; t += 2) {
;       const bool last = (t == nt - 2);
;       const char* a1 = cA + (size_t)(t + 1) * kstep;
;       const char* a2 = last ? nA : cA + (size_t)(t + 2) * kstep; const char* b2 = last ? nB : cB + (size_t)(t + 2) * kstep;
;       const char* a3 = a2 + kstep; const char* b3 = b2 + kstep;
;       if constexpr (SP2) {
;         LDB(B0, 0, 0); LDB(B1, 0, 1); SCHED; LDA(At, 0, 0); STAGE(SA(1, 1), a1 + hstep);
;         WAIT_V(8); WAIT_L(0); BAR; MMA(0, 0, At, B0); MMA(0, 1, At, B1); BAR; SCHED;
;         LDA(At, 0, 1); STAGEB(SB(0, 0), b2); STAGEB(SB(0, 1), b2 + bstep); STAGE(SA(0, 0), a2);
;         WAIT_V(8); WAIT_L(0); BAR; MMA(1, 0, At, B0); MMA(1, 1, At, B1); BAR; SCHED;
.LBB0_824:
	ds_read_b128 v[152:155], v149
	ds_read_b128 v[156:159], v149 offset:1024
	ds_read_b128 v[160:163], v149 offset:2048
	ds_read_b128 v[164:167], v149 offset:3072
	ds_read_b128 v[168:171], v150
	ds_read_b128 v[172:175], v150 offset:1024
	ds_read_b128 v[176:179], v150 offset:2048
	ds_read_b128 v[180:183], v150 offset:3072
	s_add_u32 s45, s46, 0xfff00080
	s_addc_u32 s48, s47, -1
	s_cmp_eq_u32 s39, 60
	s_cselect_b32 s51, s0, s48
	s_cselect_b32 s50, s1, s45
	s_cselect_b32 s49, s7, s35
	s_cselect_b32 s48, s27, s34
	v_lshl_add_u64 v[140:141], s[46:47], 0, v[136:137]
	s_add_i32 m0, s3, 0xc000
	ds_read_b128 v[184:187], v151
	ds_read_b128 v[188:191], v151 offset:1024
	ds_read_b128 v[192:195], v151 offset:2048
	ds_read_b128 v[196:199], v151 offset:3072
	ds_read_b128 v[200:203], v151 offset:4096
	ds_read_b128 v[204:207], v151 offset:5120
	ds_read_b128 v[208:211], v151 offset:6144
	ds_read_b128 v[216:219], v151 offset:7168
	global_load_lds_dwordx4 v[140:141], off
	v_lshl_add_u64 v[140:141], s[46:47], 0, v[138:139]
	s_add_i32 m0, s3, 0xe000
	s_nop 0
	global_load_lds_dwordx4 v[140:141], off
	s_waitcnt vmcnt(8)
	s_waitcnt lgkmcnt(0)
	s_barrier
	s_nop 0
	s_waitcnt lgkmcnt(0)
	v_mfma_f32_16x16x32_bf16 v[124:127], v[152:155], v[184:187], v[124:127]
	v_mfma_f32_16x16x32_bf16 v[120:123], v[160:163], v[184:187], v[120:123]
	v_mfma_f32_16x16x32_bf16 v[108:111], v[152:155], v[192:195], v[108:111]
	v_mfma_f32_16x16x32_bf16 v[104:107], v[160:163], v[192:195], v[104:107]
	v_mfma_f32_16x16x32_bf16 v[92:95], v[152:155], v[200:203], v[92:95]
	v_mfma_f32_16x16x32_bf16 v[88:91], v[160:163], v[200:203], v[88:91]
	v_mfma_f32_16x16x32_bf16 v[76:79], v[152:155], v[208:211], v[76:79]
	v_mfma_f32_16x16x32_bf16 v[72:75], v[160:163], v[208:211], v[72:75]
	v_mfma_f32_16x16x32_bf16 v[124:127], v[156:159], v[188:191], v[124:127]
	v_mfma_f32_16x16x32_bf16 v[120:123], v[164:167], v[188:191], v[120:123]
	v_mfma_f32_16x16x32_bf16 v[108:111], v[156:159], v[196:199], v[108:111]
	v_mfma_f32_16x16x32_bf16 v[104:107], v[164:167], v[196:199], v[104:107]
	v_mfma_f32_16x16x32_bf16 v[92:95], v[156:159], v[204:207], v[92:95]
	v_mfma_f32_16x16x32_bf16 v[88:91], v[164:167], v[204:207], v[88:91]
	v_mfma_f32_16x16x32_bf16 v[76:79], v[156:159], v[216:219], v[76:79]
	v_mfma_f32_16x16x32_bf16 v[72:75], v[164:167], v[216:219], v[72:75]
	s_nop 0
	s_nop 0
	v_mfma_f32_16x16x32_bf16 v[116:119], v[168:171], v[184:187], v[116:119]
	v_mfma_f32_16x16x32_bf16 v[112:115], v[176:179], v[184:187], v[112:115]
	v_mfma_f32_16x16x32_bf16 v[100:103], v[168:171], v[192:195], v[100:103]
	v_mfma_f32_16x16x32_bf16 v[96:99], v[176:179], v[192:195], v[96:99]
	v_mfma_f32_16x16x32_bf16 v[84:87], v[168:171], v[200:203], v[84:87]
	v_mfma_f32_16x16x32_bf16 v[80:83], v[176:179], v[200:203], v[80:83]
	v_mfma_f32_16x16x32_bf16 v[68:71], v[168:171], v[208:211], v[68:71]
	v_mfma_f32_16x16x32_bf16 v[64:67], v[176:179], v[208:211], v[64:67]
	v_mfma_f32_16x16x32_bf16 v[116:119], v[172:175], v[188:191], v[116:119]
	v_mfma_f32_16x16x32_bf16 v[112:115], v[180:183], v[188:191], v[112:115]
	v_mfma_f32_16x16x32_bf16 v[100:103], v[172:175], v[196:199], v[100:103]
	v_mfma_f32_16x16x32_bf16 v[96:99], v[180:183], v[196:199], v[96:99]
	v_mfma_f32_16x16x32_bf16 v[84:87], v[172:175], v[204:207], v[84:87]
	v_mfma_f32_16x16x32_bf16 v[80:83], v[180:183], v[204:207], v[80:83]
	v_mfma_f32_16x16x32_bf16 v[68:71], v[172:175], v[216:219], v[68:71]
	v_mfma_f32_16x16x32_bf16 v[64:67], v[180:183], v[216:219], v[64:67]
	s_nop 0
	s_barrier
	s_add_i32 s45, s18, s2
	v_lshl_add_u64 v[140:141], s[48:49], 0, v[130:131]
	s_mov_b32 m0, s45
	ds_read_b128 v[184:187], v151 offset:16384
	ds_read_b128 v[188:191], v151 offset:17408
	ds_read_b128 v[192:195], v151 offset:18432
	ds_read_b128 v[196:199], v151 offset:19456
	ds_read_b128 v[200:203], v151 offset:20480
	ds_read_b128 v[204:207], v151 offset:21504
	ds_read_b128 v[208:211], v151 offset:22528
	ds_read_b128 v[216:219], v151 offset:23552
	global_load_lds_dwordx4 v[140:141], off
	s_add_i32 m0, s45, 0x2000
	s_add_u32 s52, s48, 0x40000
	v_lshl_add_u64 v[220:221], s[48:49], 0, v[134:135]
	s_addc_u32 s53, s49, 0
	s_add_i32 s45, s19, s2
	global_load_lds_dwordx4 v[220:221], off
	v_lshl_add_u64 v[222:223], s[52:53], 0, v[130:131]
	s_mov_b32 m0, s45
	v_lshl_add_u64 v[224:225], s[50:51], 0, v[132:133]
	global_load_lds_dwordx4 v[222:223], off
	v_lshl_add_u64 v[222:223], s[52:53], 0, v[134:135]
	s_add_i32 m0, s45, 0x2000
	s_nop 0
	global_load_lds_dwordx4 v[222:223], off
	v_lshl_add_u64 v[222:223], s[50:51], 0, v[128:129]
	s_mov_b32 m0, s3
	s_nop 0
	global_load_lds_dwordx4 v[222:223], off
	s_mov_b32 m0, s8
	s_nop 0
	global_load_lds_dwordx4 v[224:225], off
	s_waitcnt vmcnt(8)
	s_waitcnt lgkmcnt(0)
	s_barrier
; #define STAGE(bufoff, gbase) STAGE_(bufoff, gbase, voffA)
; #define LDA(dst, b, h) do { _Pragma("unroll") for (int m = 0; m < 4; ++m) _Pragma("unroll") for (int k = 0; k < 2; ++k) dst[m][k] = *LDSP(const bf16x8, lds + SA(b, h) + aoff + m * 2048 + k * 1024); } while (0)
; #define LDB(dst, b, h) do { _Pragma("unroll") for (int n = 0; n < 2; ++n) _Pragma("unroll") for (int k = 0; k < 2; ++k) dst[n][k] = *LDSP(const bf16x8, lds + SB(b, h) + boff + n * 2048 + k * 1024); } while (0)
; #define MMA(ai, bj, AT, BT) do { __builtin_amdgcn_s_setprio(1); \
;     _Pragma("unroll") for (int m = 0; m < 4; ++m) _Pragma("unroll") for (int n = 0; n < 2; ++n) _Pragma("unroll") for (int k = 0; k < 2; ++k) \
;       acc[ai][bj][m][n] = __builtin_amdgcn_mfma_f32_16x16x32_bf16(BT[n][k], AT[m][k], acc[ai][bj][m][n], 0, 0, 0); \
;     __builtin_amdgcn_s_setprio(0); } while (0)
; #define WAIT_V(n) asm volatile("s_waitcnt vmcnt(" #n ")" ::: "memory")
; #define WAIT_L(n) asm volatile("s_waitcnt lgkmcnt(" #n ")" ::: "memory")
; #define BAR __builtin_amdgcn_s_barrier()
; #define SCHED __builtin_amdgcn_sched_barrier(0)
; #define WAIT_V(n) asm volatile("s_waitcnt vmcnt(" #n ")" ::: "memory")
; #define BAR do { __builtin_amdgcn_sched_barrier(0); __builtin_amdgcn_s_barrier(); asm volatile("" ::: "memory"); __builtin_amdgcn_sched_barrier(0); } while (0)
; template <bool SP2, bool ALIGN_EPI, bool DUAL, class Epi> DI void gemm_phase2(const bf16_t* A, const bf16_t* Bt, const bf16_t* A2, const bf16_t* Bt2, int M, int N, int K, const Epi& E, lds_t* lds) {
;     ...
;         WAIT_V(8); WAIT_L(0); BAR; MMA(1, 0, At, B0); MMA(1, 1, At, B1); BAR; SCHED;
;         LDB(B0, 1, 0); LDB(B1, 1, 1); SCHED; LDA(At, 1, 0); STAGE(SA(0, 1), a2 + hstep);
;         WAIT_V(8); WAIT_L(0); BAR; MMA(0, 0, At, B0); MMA(0, 1, At, B1); BAR; SCHED;
	s_nop 0
	s_waitcnt lgkmcnt(0)
	v_mfma_f32_16x16x32_bf16 v[60:63], v[152:155], v[184:187], v[60:63]
	v_mfma_f32_16x16x32_bf16 v[56:59], v[160:163], v[184:187], v[56:59]
	v_mfma_f32_16x16x32_bf16 v[44:47], v[152:155], v[192:195], v[44:47]
	v_mfma_f32_16x16x32_bf16 v[40:43], v[160:163], v[192:195], v[40:43]
	v_mfma_f32_16x16x32_bf16 v[28:31], v[152:155], v[200:203], v[28:31]
	v_mfma_f32_16x16x32_bf16 v[24:27], v[160:163], v[200:203], v[24:27]
	v_mfma_f32_16x16x32_bf16 v[12:15], v[152:155], v[208:211], v[12:15]
	v_mfma_f32_16x16x32_bf16 v[8:11], v[160:163], v[208:211], v[8:11]
	v_mfma_f32_16x16x32_bf16 v[60:63], v[156:159], v[188:191], v[60:63]
	v_mfma_f32_16x16x32_bf16 v[56:59], v[164:167], v[188:191], v[56:59]
	v_mfma_f32_16x16x32_bf16 v[44:47], v[156:159], v[196:199], v[44:47]
	v_mfma_f32_16x16x32_bf16 v[40:43], v[164:167], v[196:199], v[40:43]
	v_mfma_f32_16x16x32_bf16 v[28:31], v[156:159], v[204:207], v[28:31]
	v_mfma_f32_16x16x32_bf16 v[24:27], v[164:167], v[204:207], v[24:27]
	v_mfma_f32_16x16x32_bf16 v[12:15], v[156:159], v[216:219], v[12:15]
	v_mfma_f32_16x16x32_bf16 v[8:11], v[164:167], v[216:219], v[8:11]
	s_nop 0
	s_nop 0
	v_mfma_f32_16x16x32_bf16 v[52:55], v[168:171], v[184:187], v[52:55]
	v_mfma_f32_16x16x32_bf16 v[48:51], v[176:179], v[184:187], v[48:51]
	v_mfma_f32_16x16x32_bf16 v[36:39], v[168:171], v[192:195], v[36:39]
	v_mfma_f32_16x16x32_bf16 v[32:35], v[176:179], v[192:195], v[32:35]
	v_mfma_f32_16x16x32_bf16 v[20:23], v[168:171], v[200:203], v[20:23]
	v_mfma_f32_16x16x32_bf16 v[16:19], v[176:179], v[200:203], v[16:19]
	v_mfma_f32_16x16x32_bf16 v[4:7], v[168:171], v[208:211], v[4:7]
	v_mfma_f32_16x16x32_bf16 v[0:3], v[176:179], v[208:211], v[0:3]
	v_mfma_f32_16x16x32_bf16 v[52:55], v[172:175], v[188:191], v[52:55]
	v_mfma_f32_16x16x32_bf16 v[48:51], v[180:183], v[188:191], v[48:51]
	v_mfma_f32_16x16x32_bf16 v[36:39], v[172:175], v[196:199], v[36:39]
	v_mfma_f32_16x16x32_bf16 v[32:35], v[180:183], v[196:199], v[32:35]
	v_mfma_f32_16x16x32_bf16 v[20:23], v[172:175], v[204:207], v[20:23]
	v_mfma_f32_16x16x32_bf16 v[16:19], v[180:183], v[204:207], v[16:19]
	v_mfma_f32_16x16x32_bf16 v[4:7], v[172:175], v[216:219], v[4:7]
	v_mfma_f32_16x16x32_bf16 v[0:3], v[180:183], v[216:219], v[0:3]
	s_nop 0
	s_barrier
	s_add_i32 s45, 0, 0x18000
	s_add_i32 s52, 0, 0x1c000
	v_add_u32_e32 v164, s45, v143
	v_add_u32_e32 v180, s52, v143
	ds_read_b128 v[152:155], v164
	ds_read_b128 v[156:159], v164 offset:1024
	ds_read_b128 v[160:163], v164 offset:2048
	ds_read_b128 v[164:167], v164 offset:3072
	ds_read_b128 v[168:171], v180
	ds_read_b128 v[172:175], v180 offset:1024
	ds_read_b128 v[176:179], v180 offset:2048
	ds_read_b128 v[180:183], v180 offset:3072
	s_add_u32 s50, s50, 0x100000
	s_addc_u32 s51, s51, 0
	s_mov_b32 m0, s9
	v_lshl_add_u64 v[226:227], s[50:51], 0, v[128:129]
	ds_read_b128 v[184:187], v151 offset:32768
	ds_read_b128 v[188:191], v151 offset:33792
	ds_read_b128 v[192:195], v151 offset:34816
	ds_read_b128 v[196:199], v151 offset:35840
	ds_read_b128 v[200:203], v151 offset:36864
	ds_read_b128 v[204:207], v151 offset:37888
	ds_read_b128 v[208:211], v151 offset:38912
	ds_read_b128 v[216:219], v151 offset:39936
	global_load_lds_dwordx4 v[226:227], off
	v_lshl_add_u64 v[226:227], s[50:51], 0, v[132:133]
	s_mov_b32 m0, s10
	s_nop 0
	global_load_lds_dwordx4 v[226:227], off
	s_waitcnt vmcnt(8)
	s_waitcnt lgkmcnt(0)
	s_barrier
	s_nop 0
	s_waitcnt lgkmcnt(0)
	v_mfma_f32_16x16x32_bf16 v[124:127], v[152:155], v[184:187], v[124:127]
	v_mfma_f32_16x16x32_bf16 v[120:123], v[160:163], v[184:187], v[120:123]
	v_mfma_f32_16x16x32_bf16 v[108:111], v[152:155], v[192:195], v[108:111]
	v_mfma_f32_16x16x32_bf16 v[104:107], v[160:163], v[192:195], v[104:107]
	v_mfma_f32_16x16x32_bf16 v[92:95], v[152:155], v[200:203], v[92:95]
	v_mfma_f32_16x16x32_bf16 v[88:91], v[160:163], v[200:203], v[88:91]
	v_mfma_f32_16x16x32_bf16 v[76:79], v[152:155], v[208:211], v[76:79]
	v_mfma_f32_16x16x32_bf16 v[72:75], v[160:163], v[208:211], v[72:75]
	v_mfma_f32_16x16x32_bf16 v[124:127], v[156:159], v[188:191], v[124:127]
	v_mfma_f32_16x16x32_bf16 v[120:123], v[164:167], v[188:191], v[120:123]
	v_mfma_f32_16x16x32_bf16 v[108:111], v[156:159], v[196:199], v[108:111]
	v_mfma_f32_16x16x32_bf16 v[104:107], v[164:167], v[196:199], v[104:107]
	v_mfma_f32_16x16x32_bf16 v[92:95], v[156:159], v[204:207], v[92:95]
	v_mfma_f32_16x16x32_bf16 v[88:91], v[164:167], v[204:207], v[88:91]
	v_mfma_f32_16x16x32_bf16 v[76:79], v[156:159], v[216:219], v[76:79]
	v_mfma_f32_16x16x32_bf16 v[72:75], v[164:167], v[216:219], v[72:75]
	s_nop 0
	s_nop 0
	v_mfma_f32_16x16x32_bf16 v[116:119], v[168:171], v[184:187], v[116:119]
	v_mfma_f32_16x16x32_bf16 v[112:115], v[176:179], v[184:187], v[112:115]
	v_mfma_f32_16x16x32_bf16 v[100:103], v[168:171], v[192:195], v[100:103]
	v_mfma_f32_16x16x32_bf16 v[96:99], v[176:179], v[192:195], v[96:99]
	v_mfma_f32_16x16x32_bf16 v[84:87], v[168:171], v[200:203], v[84:87]
	v_mfma_f32_16x16x32_bf16 v[80:83], v[176:179], v[200:203], v[80:83]
	v_mfma_f32_16x16x32_bf16 v[68:71], v[168:171], v[208:211], v[68:71]
	v_mfma_f32_16x16x32_bf16 v[64:67], v[176:179], v[208:211], v[64:67]
	v_mfma_f32_16x16x32_bf16 v[116:119], v[172:175], v[188:191], v[116:119]
	v_mfma_f32_16x16x32_bf16 v[112:115], v[180:183], v[188:191], v[112:115]
	v_mfma_f32_16x16x32_bf16 v[100:103], v[172:175], v[196:199], v[100:103]
	v_mfma_f32_16x16x32_bf16 v[96:99], v[180:183], v[196:199], v[96:99]
	v_mfma_f32_16x16x32_bf16 v[84:87], v[172:175], v[204:207], v[84:87]
	v_mfma_f32_16x16x32_bf16 v[80:83], v[180:183], v[204:207], v[80:83]
	v_mfma_f32_16x16x32_bf16 v[68:71], v[172:175], v[216:219], v[68:71]
	v_mfma_f32_16x16x32_bf16 v[64:67], v[180:183], v[216:219], v[64:67]
	s_nop 0
	s_barrier
; #define STAGE(bufoff, gbase) STAGE_(bufoff, gbase, voffA)
; #define STAGEB(bufoff, gbase) STAGE_(bufoff, gbase, voffB)
; #define LDA(dst, b, h) do { _Pragma("unroll") for (int m = 0; m < 4; ++m) _Pragma("unroll") for (int k = 0; k < 2; ++k) dst[m][k] = *LDSP(const bf16x8, lds + SA(b, h) + aoff + m * 2048 + k * 1024); } while (0)
; #define MMA(ai, bj, AT, BT) do { __builtin_amdgcn_s_setprio(1); \
;     _Pragma("unroll") for (int m = 0; m < 4; ++m) _Pragma("unroll") for (int n = 0; n < 2; ++n) _Pragma("unroll") for (int k = 0; k < 2; ++k) \
;       acc[ai][bj][m][n] = __builtin_amdgcn_mfma_f32_16x16x32_bf16(BT[n][k], AT[m][k], acc[ai][bj][m][n], 0, 0, 0); \
;     __builtin_amdgcn_s_setprio(0); } while (0)
; #define WAIT_V(n) asm volatile("s_waitcnt vmcnt(" #n ")" ::: "memory")
; #define WAIT_L(n) asm volatile("s_waitcnt lgkmcnt(" #n ")" ::: "memory")
; #define BAR __builtin_amdgcn_s_barrier()
; #define SCHED __builtin_amdgcn_sched_barrier(0)
; #define WAIT_V(n) asm volatile("s_waitcnt vmcnt(" #n ")" ::: "memory")
; #define BAR do { __builtin_amdgcn_sched_barrier(0); __builtin_amdgcn_s_barrier(); asm volatile("" ::: "memory"); __builtin_amdgcn_sched_barrier(0); } while (0)
; template <bool SP2, bool ALIGN_EPI, bool DUAL, class Epi> DI void gemm_phase2(const bf16_t* A, const bf16_t* Bt, const bf16_t* A2, const bf16_t* Bt2, int M, int N, int K, const Epi& E, lds_t* lds) {
;     ...
;     for (int t = 0; t < nt; t += 2) {
;       const bool last = (t == nt - 2);
;       const char* a1 = cA + (size_t)(t + 1) * kstep;
;       const char* a2 = last ? nA : cA + (size_t)(t + 2) * kstep; const char* b2 = last ? nB : cB + (size_t)(t + 2) * kstep;
;       const char* a3 = a2 + kstep; const char* b3 = b2 + kstep;
;     ...
;         LDA(At, 1, 1); STAGEB(SB(1, 0), b3); STAGEB(SB(1, 1), b3 + bstep); STAGE(SA(1, 0), a3);
;         WAIT_V(8); WAIT_L(0); BAR; MMA(1, 0, At, B0); MMA(1, 1, At, B1); BAR; SCHED;
	s_add_i32 s45, s45, s2
	v_lshl_add_u64 v[140:141], v[140:141], 0, s[22:23]
	s_mov_b32 m0, s45
	ds_read_b128 v[184:187], v151 offset:49152
	ds_read_b128 v[188:191], v151 offset:50176
	ds_read_b128 v[192:195], v151 offset:51200
	ds_read_b128 v[196:199], v151 offset:52224
	ds_read_b128 v[200:203], v151 offset:53248
	ds_read_b128 v[204:207], v151 offset:54272
	ds_read_b128 v[208:211], v151 offset:55296
	ds_read_b128 v[216:219], v151 offset:56320
	global_load_lds_dwordx4 v[140:141], off
	s_add_i32 m0, s45, 0x2000
	s_add_u32 s48, s48, 0x40080
	v_lshl_add_u64 v[140:141], v[220:221], 0, s[22:23]
	s_addc_u32 s49, s49, 0
	s_add_i32 s45, s52, s2
	global_load_lds_dwordx4 v[140:141], off
	v_lshl_add_u64 v[140:141], s[48:49], 0, v[130:131]
	s_mov_b32 m0, s45
	s_nop 0
	global_load_lds_dwordx4 v[140:141], off
	v_lshl_add_u64 v[140:141], s[48:49], 0, v[134:135]
	s_add_i32 m0, s45, 0x2000
	s_nop 0
	global_load_lds_dwordx4 v[140:141], off
	v_lshl_add_u64 v[140:141], v[222:223], 0, s[22:23]
	s_mov_b32 m0, s14
	s_nop 0
	global_load_lds_dwordx4 v[140:141], off
	v_lshl_add_u64 v[140:141], v[224:225], 0, s[22:23]
	s_mov_b32 m0, s15
	s_nop 0
	global_load_lds_dwordx4 v[140:141], off
	s_waitcnt vmcnt(8)
	s_waitcnt lgkmcnt(0)
	s_barrier
	s_nop 0
	s_waitcnt lgkmcnt(0)
	v_mfma_f32_16x16x32_bf16 v[60:63], v[152:155], v[184:187], v[60:63]
	v_mfma_f32_16x16x32_bf16 v[56:59], v[160:163], v[184:187], v[56:59]
	v_mfma_f32_16x16x32_bf16 v[44:47], v[152:155], v[192:195], v[44:47]
	v_mfma_f32_16x16x32_bf16 v[40:43], v[160:163], v[192:195], v[40:43]
	v_mfma_f32_16x16x32_bf16 v[28:31], v[152:155], v[200:203], v[28:31]
	v_mfma_f32_16x16x32_bf16 v[24:27], v[160:163], v[200:203], v[24:27]
	v_mfma_f32_16x16x32_bf16 v[12:15], v[152:155], v[208:211], v[12:15]
	v_mfma_f32_16x16x32_bf16 v[8:11], v[160:163], v[208:211], v[8:11]
	v_mfma_f32_16x16x32_bf16 v[60:63], v[156:159], v[188:191], v[60:63]
	v_mfma_f32_16x16x32_bf16 v[56:59], v[164:167], v[188:191], v[56:59]
	v_mfma_f32_16x16x32_bf16 v[44:47], v[156:159], v[196:199], v[44:47]
	v_mfma_f32_16x16x32_bf16 v[40:43], v[164:167], v[196:199], v[40:43]
	v_mfma_f32_16x16x32_bf16 v[28:31], v[156:159], v[204:207], v[28:31]
	v_mfma_f32_16x16x32_bf16 v[24:27], v[164:167], v[204:207], v[24:27]
	v_mfma_f32_16x16x32_bf16 v[12:15], v[156:159], v[216:219], v[12:15]
	v_mfma_f32_16x16x32_bf16 v[8:11], v[164:167], v[216:219], v[8:11]
	s_nop 0
	s_nop 0
	v_mfma_f32_16x16x32_bf16 v[52:55], v[168:171], v[184:187], v[52:55]
	v_mfma_f32_16x16x32_bf16 v[48:51], v[176:179], v[184:187], v[48:51]
	v_mfma_f32_16x16x32_bf16 v[36:39], v[168:171], v[192:195], v[36:39]
	v_mfma_f32_16x16x32_bf16 v[32:35], v[176:179], v[192:195], v[32:35]
	v_mfma_f32_16x16x32_bf16 v[20:23], v[168:171], v[200:203], v[20:23]
	v_mfma_f32_16x16x32_bf16 v[16:19], v[176:179], v[200:203], v[16:19]
	v_mfma_f32_16x16x32_bf16 v[4:7], v[168:171], v[208:211], v[4:7]
	v_mfma_f32_16x16x32_bf16 v[0:3], v[176:179], v[208:211], v[0:3]
	v_mfma_f32_16x16x32_bf16 v[52:55], v[172:175], v[188:191], v[52:55]
	v_mfma_f32_16x16x32_bf16 v[48:51], v[180:183], v[188:191], v[48:51]
	v_mfma_f32_16x16x32_bf16 v[36:39], v[172:175], v[196:199], v[36:39]
	v_mfma_f32_16x16x32_bf16 v[32:35], v[180:183], v[196:199], v[32:35]
	v_mfma_f32_16x16x32_bf16 v[20:23], v[172:175], v[204:207], v[20:23]
	v_mfma_f32_16x16x32_bf16 v[16:19], v[180:183], v[204:207], v[16:19]
	v_mfma_f32_16x16x32_bf16 v[4:7], v[172:175], v[216:219], v[4:7]
	v_mfma_f32_16x16x32_bf16 v[0:3], v[180:183], v[216:219], v[0:3]
	s_nop 0
	s_barrier
	s_add_i32 s39, s39, 2
	s_add_u32 s46, s46, 0x100
	s_addc_u32 s47, s47, 0
	s_add_u32 s34, s34, 0x100
	s_addc_u32 s35, s35, 0
	s_cmp_gt_u32 s39, 61
	s_cbranch_scc0 .LBB0_824
	s_and_b64 vcc, exec, s[28:29]
	s_cbranch_vccz .LBB0_827
	s_barrier

; #define STAGE(bufoff, gbase) STAGE_(bufoff, gbase, voffA)
; #define STAGEB(bufoff, gbase) STAGE_(bufoff, gbase, voffB)
; #define LDA(dst, b, h) do { _Pragma("unroll") for (int m = 0; m < 4; ++m) _Pragma("unroll") for (int k = 0; k < 2; ++k) dst[m][k] = *LDSP(const bf16x8, lds + SA(b, h) + aoff + m * 2048 + k * 1024); } while (0)
; #define LDB(dst, b, h) do { _Pragma("unroll") for (int n = 0; n < 2; ++n) _Pragma("unroll") for (int k = 0; k < 2; ++k) dst[n][k] = *LDSP(const bf16x8, lds + SB(b, h) + boff + n * 2048 + k * 1024); } while (0)
; #define MMA(ai, bj, AT, BT) do { __builtin_amdgcn_s_setprio(1); \
;     _Pragma("unroll") for (int m = 0; m < 4; ++m) _Pragma("unroll") for (int n = 0; n < 2; ++n) _Pragma("unroll") for (int k = 0; k < 2; ++k) \
;       acc[ai][bj][m][n] = __builtin_amdgcn_mfma_f32_16x16x32_bf16(BT[n][k], AT[m][k], acc[ai][bj][m][n], 0, 0, 0); \
;     __builtin_amdgcn_s_setprio(0); } while (0)
; #define WAIT_V(n) asm volatile("s_waitcnt vmcnt(" #n ")" ::: "memory")
; #define WAIT_L(n) asm volatile("s_waitcnt lgkmcnt(" #n ")" ::: "memory")
; #define BAR __builtin_amdgcn_s_barrier()
; #define SCHED __builtin_amdgcn_sched_barrier(0)
; #define WAIT_V(n) asm volatile("s_waitcnt vmcnt(" #n ")" ::: "memory")
; #define BAR do { __builtin_amdgcn_sched_barrier(0); __builtin_amdgcn_s_barrier(); asm volatile("" ::: "memory"); __builtin_amdgcn_sched_barrier(0); } while (0)
; template <bool SP2, bool ALIGN_EPI, bool DUAL, class Epi> DI void gemm_phase2(const bf16_t* A, const bf16_t* Bt, const bf16_t* A2, const bf16_t* Bt2, int M, int N, int K, const Epi& E, lds_t* lds) {
;     ...
;     for (int t = 0; t < nt; t += 2) {
;       const bool last = (t == nt - 2);
;       const char* a1 = cA + (size_t)(t + 1) * kstep;
;       const char* a2 = last ? nA : cA + (size_t)(t + 2) * kstep; const char* b2 = last ? nB : cB + (size_t)(t + 2) * kstep;
;       const char* a3 = a2 + kstep; const char* b3 = b2 + kstep;
;       if constexpr (SP2) {
;         LDB(B0, 0, 0); LDB(B1, 0, 1); SCHED; LDA(At, 0, 0); STAGE(SA(1, 1), a1 + hstep);
;         WAIT_V(8); WAIT_L(0); BAR; MMA(0, 0, At, B0); MMA(0, 1, At, B1); BAR; SCHED;
;         LDA(At, 0, 1); STAGEB(SB(0, 0), b2); STAGEB(SB(0, 1), b2 + bstep); STAGE(SA(0, 0), a2);
;         WAIT_V(8); WAIT_L(0); BAR; MMA(1, 0, At, B0); MMA(1, 1, At, B1); BAR; SCHED;
.LBB0_900:
	ds_read_b128 v[140:143], v160
	ds_read_b128 v[144:147], v160 offset:1024
	ds_read_b128 v[148:151], v160 offset:2048
	ds_read_b128 v[152:155], v160 offset:3072
	ds_read_b128 v[164:167], v161
	ds_read_b128 v[168:171], v161 offset:1024
	ds_read_b128 v[172:175], v161 offset:2048
	ds_read_b128 v[176:179], v161 offset:3072
	s_add_u32 s27, s42, 0xfff00080
	s_addc_u32 s41, s43, -1
	s_cmp_eq_u32 s21, 60
	s_cselect_b32 s47, s0, s41
	s_cselect_b32 s46, s1, s27
	s_cselect_b32 s45, s2, s15
	s_cselect_b32 s44, s3, s14
	v_lshl_add_u64 v[216:217], s[42:43], 0, v[136:137]
	s_add_i32 m0, s11, 0xc000
	ds_read_b128 v[180:183], v162
	ds_read_b128 v[184:187], v162 offset:1024
	ds_read_b128 v[188:191], v162 offset:2048
	ds_read_b128 v[192:195], v162 offset:3072
	ds_read_b128 v[196:199], v162 offset:4096
	ds_read_b128 v[200:203], v162 offset:5120
	ds_read_b128 v[204:207], v162 offset:6144
	ds_read_b128 v[208:211], v162 offset:7168
	global_load_lds_dwordx4 v[216:217], off
	v_lshl_add_u64 v[216:217], s[42:43], 0, v[138:139]
	s_add_i32 m0, s11, 0xe000
	s_nop 0
	global_load_lds_dwordx4 v[216:217], off
	s_waitcnt vmcnt(8)
	s_waitcnt lgkmcnt(0)
	s_barrier
	s_nop 0
	s_waitcnt lgkmcnt(0)
	v_mfma_f32_16x16x32_bf16 v[124:127], v[140:143], v[180:183], v[124:127]
	v_mfma_f32_16x16x32_bf16 v[120:123], v[148:151], v[180:183], v[120:123]
	v_mfma_f32_16x16x32_bf16 v[108:111], v[140:143], v[188:191], v[108:111]
	v_mfma_f32_16x16x32_bf16 v[104:107], v[148:151], v[188:191], v[104:107]
	v_mfma_f32_16x16x32_bf16 v[92:95], v[140:143], v[196:199], v[92:95]
	v_mfma_f32_16x16x32_bf16 v[88:91], v[148:151], v[196:199], v[88:91]
	v_mfma_f32_16x16x32_bf16 v[76:79], v[140:143], v[204:207], v[76:79]
	v_mfma_f32_16x16x32_bf16 v[72:75], v[148:151], v[204:207], v[72:75]
	v_mfma_f32_16x16x32_bf16 v[124:127], v[144:147], v[184:187], v[124:127]
	v_mfma_f32_16x16x32_bf16 v[120:123], v[152:155], v[184:187], v[120:123]
	v_mfma_f32_16x16x32_bf16 v[108:111], v[144:147], v[192:195], v[108:111]
	v_mfma_f32_16x16x32_bf16 v[104:107], v[152:155], v[192:195], v[104:107]
	v_mfma_f32_16x16x32_bf16 v[92:95], v[144:147], v[200:203], v[92:95]
	v_mfma_f32_16x16x32_bf16 v[88:91], v[152:155], v[200:203], v[88:91]
	v_mfma_f32_16x16x32_bf16 v[76:79], v[144:147], v[208:211], v[76:79]
	v_mfma_f32_16x16x32_bf16 v[72:75], v[152:155], v[208:211], v[72:75]
	s_nop 0
	s_nop 0
	v_mfma_f32_16x16x32_bf16 v[116:119], v[164:167], v[180:183], v[116:119]
	v_mfma_f32_16x16x32_bf16 v[112:115], v[172:175], v[180:183], v[112:115]
	v_mfma_f32_16x16x32_bf16 v[100:103], v[164:167], v[188:191], v[100:103]
	v_mfma_f32_16x16x32_bf16 v[96:99], v[172:175], v[188:191], v[96:99]
	v_mfma_f32_16x16x32_bf16 v[84:87], v[164:167], v[196:199], v[84:87]
	v_mfma_f32_16x16x32_bf16 v[80:83], v[172:175], v[196:199], v[80:83]
	v_mfma_f32_16x16x32_bf16 v[68:71], v[164:167], v[204:207], v[68:71]
	v_mfma_f32_16x16x32_bf16 v[64:67], v[172:175], v[204:207], v[64:67]
	v_mfma_f32_16x16x32_bf16 v[116:119], v[168:171], v[184:187], v[116:119]
	v_mfma_f32_16x16x32_bf16 v[112:115], v[176:179], v[184:187], v[112:115]
	v_mfma_f32_16x16x32_bf16 v[100:103], v[168:171], v[192:195], v[100:103]
	v_mfma_f32_16x16x32_bf16 v[96:99], v[176:179], v[192:195], v[96:99]
	v_mfma_f32_16x16x32_bf16 v[84:87], v[168:171], v[200:203], v[84:87]
	v_mfma_f32_16x16x32_bf16 v[80:83], v[176:179], v[200:203], v[80:83]
	v_mfma_f32_16x16x32_bf16 v[68:71], v[168:171], v[208:211], v[68:71]
	v_mfma_f32_16x16x32_bf16 v[64:67], v[176:179], v[208:211], v[64:67]
	s_nop 0
	s_barrier
	s_add_i32 s27, s49, s10
	v_lshl_add_u64 v[216:217], s[44:45], 0, v[130:131]
	s_mov_b32 m0, s27
	ds_read_b128 v[180:183], v162 offset:16384
	ds_read_b128 v[184:187], v162 offset:17408
	ds_read_b128 v[188:191], v162 offset:18432
	ds_read_b128 v[192:195], v162 offset:19456
	ds_read_b128 v[196:199], v162 offset:20480
	ds_read_b128 v[200:203], v162 offset:21504
	ds_read_b128 v[204:207], v162 offset:22528
	ds_read_b128 v[208:211], v162 offset:23552
	global_load_lds_dwordx4 v[216:217], off
	s_add_i32 m0, s27, 0x2000
	s_add_u32 s54, s44, 0x40000
	v_lshl_add_u64 v[218:219], s[44:45], 0, v[134:135]
	s_addc_u32 s55, s45, 0
	s_add_i32 s27, s50, s10
	global_load_lds_dwordx4 v[218:219], off
	v_lshl_add_u64 v[220:221], s[54:55], 0, v[130:131]
	s_mov_b32 m0, s27
	v_lshl_add_u64 v[222:223], s[46:47], 0, v[132:133]
	global_load_lds_dwordx4 v[220:221], off
	v_lshl_add_u64 v[220:221], s[54:55], 0, v[134:135]
	s_add_i32 m0, s27, 0x2000
	s_nop 0
	global_load_lds_dwordx4 v[220:221], off
	v_lshl_add_u64 v[220:221], s[46:47], 0, v[128:129]
	s_mov_b32 m0, s11
	s_nop 0
	global_load_lds_dwordx4 v[220:221], off
	s_mov_b32 m0, s18
	s_nop 0
	global_load_lds_dwordx4 v[222:223], off
	s_waitcnt vmcnt(8)
	s_waitcnt lgkmcnt(0)
	s_barrier
; #define STAGE(bufoff, gbase) STAGE_(bufoff, gbase, voffA)
; #define LDA(dst, b, h) do { _Pragma("unroll") for (int m = 0; m < 4; ++m) _Pragma("unroll") for (int k = 0; k < 2; ++k) dst[m][k] = *LDSP(const bf16x8, lds + SA(b, h) + aoff + m * 2048 + k * 1024); } while (0)
; #define LDB(dst, b, h) do { _Pragma("unroll") for (int n = 0; n < 2; ++n) _Pragma("unroll") for (int k = 0; k < 2; ++k) dst[n][k] = *LDSP(const bf16x8, lds + SB(b, h) + boff + n * 2048 + k * 1024); } while (0)
; #define MMA(ai, bj, AT, BT) do { __builtin_amdgcn_s_setprio(1); \
;     _Pragma("unroll") for (int m = 0; m < 4; ++m) _Pragma("unroll") for (int n = 0; n < 2; ++n) _Pragma("unroll") for (int k = 0; k < 2; ++k) \
;       acc[ai][bj][m][n] = __builtin_amdgcn_mfma_f32_16x16x32_bf16(BT[n][k], AT[m][k], acc[ai][bj][m][n], 0, 0, 0); \
;     __builtin_amdgcn_s_setprio(0); } while (0)
; #define WAIT_V(n) asm volatile("s_waitcnt vmcnt(" #n ")" ::: "memory")
; #define WAIT_L(n) asm volatile("s_waitcnt lgkmcnt(" #n ")" ::: "memory")
; #define BAR __builtin_amdgcn_s_barrier()
; #define SCHED __builtin_amdgcn_sched_barrier(0)
; #define WAIT_V(n) asm volatile("s_waitcnt vmcnt(" #n ")" ::: "memory")
; #define BAR do { __builtin_amdgcn_sched_barrier(0); __builtin_amdgcn_s_barrier(); asm volatile("" ::: "memory"); __builtin_amdgcn_sched_barrier(0); } while (0)
; template <bool SP2, bool ALIGN_EPI, bool DUAL, class Epi> DI void gemm_phase2(const bf16_t* A, const bf16_t* Bt, const bf16_t* A2, const bf16_t* Bt2, int M, int N, int K, const Epi& E, lds_t* lds) {
;     ...
;         WAIT_V(8); WAIT_L(0); BAR; MMA(1, 0, At, B0); MMA(1, 1, At, B1); BAR; SCHED;
;         LDB(B0, 1, 0); LDB(B1, 1, 1); SCHED; LDA(At, 1, 0); STAGE(SA(0, 1), a2 + hstep);
;         WAIT_V(8); WAIT_L(0); BAR; MMA(0, 0, At, B0); MMA(0, 1, At, B1); BAR; SCHED;
	s_nop 0
	s_waitcnt lgkmcnt(0)
	v_mfma_f32_16x16x32_bf16 v[60:63], v[140:143], v[180:183], v[60:63]
	v_mfma_f32_16x16x32_bf16 v[56:59], v[148:151], v[180:183], v[56:59]
	v_mfma_f32_16x16x32_bf16 v[44:47], v[140:143], v[188:191], v[44:47]
	v_mfma_f32_16x16x32_bf16 v[40:43], v[148:151], v[188:191], v[40:43]
	v_mfma_f32_16x16x32_bf16 v[28:31], v[140:143], v[196:199], v[28:31]
	v_mfma_f32_16x16x32_bf16 v[24:27], v[148:151], v[196:199], v[24:27]
	v_mfma_f32_16x16x32_bf16 v[12:15], v[140:143], v[204:207], v[12:15]
	v_mfma_f32_16x16x32_bf16 v[8:11], v[148:151], v[204:207], v[8:11]
	v_mfma_f32_16x16x32_bf16 v[60:63], v[144:147], v[184:187], v[60:63]
	v_mfma_f32_16x16x32_bf16 v[56:59], v[152:155], v[184:187], v[56:59]
	v_mfma_f32_16x16x32_bf16 v[44:47], v[144:147], v[192:195], v[44:47]
	v_mfma_f32_16x16x32_bf16 v[40:43], v[152:155], v[192:195], v[40:43]
	v_mfma_f32_16x16x32_bf16 v[28:31], v[144:147], v[200:203], v[28:31]
	v_mfma_f32_16x16x32_bf16 v[24:27], v[152:155], v[200:203], v[24:27]
	v_mfma_f32_16x16x32_bf16 v[12:15], v[144:147], v[208:211], v[12:15]
	v_mfma_f32_16x16x32_bf16 v[8:11], v[152:155], v[208:211], v[8:11]
	s_nop 0
	s_nop 0
	v_mfma_f32_16x16x32_bf16 v[52:55], v[164:167], v[180:183], v[52:55]
	v_mfma_f32_16x16x32_bf16 v[48:51], v[172:175], v[180:183], v[48:51]
	v_mfma_f32_16x16x32_bf16 v[36:39], v[164:167], v[188:191], v[36:39]
	v_mfma_f32_16x16x32_bf16 v[32:35], v[172:175], v[188:191], v[32:35]
	v_mfma_f32_16x16x32_bf16 v[20:23], v[164:167], v[196:199], v[20:23]
	v_mfma_f32_16x16x32_bf16 v[16:19], v[172:175], v[196:199], v[16:19]
	v_mfma_f32_16x16x32_bf16 v[4:7], v[164:167], v[204:207], v[4:7]
	v_mfma_f32_16x16x32_bf16 v[0:3], v[172:175], v[204:207], v[0:3]
	v_mfma_f32_16x16x32_bf16 v[52:55], v[168:171], v[184:187], v[52:55]
	v_mfma_f32_16x16x32_bf16 v[48:51], v[176:179], v[184:187], v[48:51]
	v_mfma_f32_16x16x32_bf16 v[36:39], v[168:171], v[192:195], v[36:39]
	v_mfma_f32_16x16x32_bf16 v[32:35], v[176:179], v[192:195], v[32:35]
	v_mfma_f32_16x16x32_bf16 v[20:23], v[168:171], v[200:203], v[20:23]
	v_mfma_f32_16x16x32_bf16 v[16:19], v[176:179], v[200:203], v[16:19]
	v_mfma_f32_16x16x32_bf16 v[4:7], v[168:171], v[208:211], v[4:7]
	v_mfma_f32_16x16x32_bf16 v[0:3], v[176:179], v[208:211], v[0:3]
	s_nop 0
	s_barrier
	s_add_i32 s27, 0, 0x18000
	s_add_i32 s41, 0, 0x1c000
	v_add_u32_e32 v152, s27, v157
	v_add_u32_e32 v176, s41, v157
	ds_read_b128 v[140:143], v152
	ds_read_b128 v[144:147], v152 offset:1024
	ds_read_b128 v[148:151], v152 offset:2048
	ds_read_b128 v[152:155], v152 offset:3072
	ds_read_b128 v[164:167], v176
	ds_read_b128 v[168:171], v176 offset:1024
	ds_read_b128 v[172:175], v176 offset:2048
	ds_read_b128 v[176:179], v176 offset:3072
	s_add_u32 s46, s46, 0x100000
	s_addc_u32 s47, s47, 0
	s_mov_b32 m0, s19
	v_lshl_add_u64 v[224:225], s[46:47], 0, v[128:129]
	ds_read_b128 v[180:183], v162 offset:32768
	ds_read_b128 v[184:187], v162 offset:33792
	ds_read_b128 v[188:191], v162 offset:34816
	ds_read_b128 v[192:195], v162 offset:35840
	ds_read_b128 v[196:199], v162 offset:36864
	ds_read_b128 v[200:203], v162 offset:37888
	ds_read_b128 v[204:207], v162 offset:38912
	ds_read_b128 v[208:211], v162 offset:39936
	global_load_lds_dwordx4 v[224:225], off
	v_lshl_add_u64 v[224:225], s[46:47], 0, v[132:133]
	s_mov_b32 m0, s33
	s_nop 0
	global_load_lds_dwordx4 v[224:225], off
	s_waitcnt vmcnt(8)
	s_waitcnt lgkmcnt(0)
	s_barrier
	s_nop 0
	s_waitcnt lgkmcnt(0)
	v_mfma_f32_16x16x32_bf16 v[124:127], v[140:143], v[180:183], v[124:127]
	v_mfma_f32_16x16x32_bf16 v[120:123], v[148:151], v[180:183], v[120:123]
	v_mfma_f32_16x16x32_bf16 v[108:111], v[140:143], v[188:191], v[108:111]
	v_mfma_f32_16x16x32_bf16 v[104:107], v[148:151], v[188:191], v[104:107]
	v_mfma_f32_16x16x32_bf16 v[92:95], v[140:143], v[196:199], v[92:95]
	v_mfma_f32_16x16x32_bf16 v[88:91], v[148:151], v[196:199], v[88:91]
	v_mfma_f32_16x16x32_bf16 v[76:79], v[140:143], v[204:207], v[76:79]
	v_mfma_f32_16x16x32_bf16 v[72:75], v[148:151], v[204:207], v[72:75]
	v_mfma_f32_16x16x32_bf16 v[124:127], v[144:147], v[184:187], v[124:127]
	v_mfma_f32_16x16x32_bf16 v[120:123], v[152:155], v[184:187], v[120:123]
	v_mfma_f32_16x16x32_bf16 v[108:111], v[144:147], v[192:195], v[108:111]
	v_mfma_f32_16x16x32_bf16 v[104:107], v[152:155], v[192:195], v[104:107]
	v_mfma_f32_16x16x32_bf16 v[92:95], v[144:147], v[200:203], v[92:95]
	v_mfma_f32_16x16x32_bf16 v[88:91], v[152:155], v[200:203], v[88:91]
	v_mfma_f32_16x16x32_bf16 v[76:79], v[144:147], v[208:211], v[76:79]
	v_mfma_f32_16x16x32_bf16 v[72:75], v[152:155], v[208:211], v[72:75]
	s_nop 0
	s_nop 0
	v_mfma_f32_16x16x32_bf16 v[116:119], v[164:167], v[180:183], v[116:119]
	v_mfma_f32_16x16x32_bf16 v[112:115], v[172:175], v[180:183], v[112:115]
	v_mfma_f32_16x16x32_bf16 v[100:103], v[164:167], v[188:191], v[100:103]
	v_mfma_f32_16x16x32_bf16 v[96:99], v[172:175], v[188:191], v[96:99]
	v_mfma_f32_16x16x32_bf16 v[84:87], v[164:167], v[196:199], v[84:87]
	v_mfma_f32_16x16x32_bf16 v[80:83], v[172:175], v[196:199], v[80:83]
	v_mfma_f32_16x16x32_bf16 v[68:71], v[164:167], v[204:207], v[68:71]
	v_mfma_f32_16x16x32_bf16 v[64:67], v[172:175], v[204:207], v[64:67]
	v_mfma_f32_16x16x32_bf16 v[116:119], v[168:171], v[184:187], v[116:119]
	v_mfma_f32_16x16x32_bf16 v[112:115], v[176:179], v[184:187], v[112:115]
	v_mfma_f32_16x16x32_bf16 v[100:103], v[168:171], v[192:195], v[100:103]
	v_mfma_f32_16x16x32_bf16 v[96:99], v[176:179], v[192:195], v[96:99]
	v_mfma_f32_16x16x32_bf16 v[84:87], v[168:171], v[200:203], v[84:87]
	v_mfma_f32_16x16x32_bf16 v[80:83], v[176:179], v[200:203], v[80:83]
	v_mfma_f32_16x16x32_bf16 v[68:71], v[168:171], v[208:211], v[68:71]
	v_mfma_f32_16x16x32_bf16 v[64:67], v[176:179], v[208:211], v[64:67]
	s_nop 0
	s_barrier
; #define STAGE(bufoff, gbase) STAGE_(bufoff, gbase, voffA)
; #define STAGEB(bufoff, gbase) STAGE_(bufoff, gbase, voffB)
; #define LDA(dst, b, h) do { _Pragma("unroll") for (int m = 0; m < 4; ++m) _Pragma("unroll") for (int k = 0; k < 2; ++k) dst[m][k] = *LDSP(const bf16x8, lds + SA(b, h) + aoff + m * 2048 + k * 1024); } while (0)
; #define MMA(ai, bj, AT, BT) do { __builtin_amdgcn_s_setprio(1); \
;     _Pragma("unroll") for (int m = 0; m < 4; ++m) _Pragma("unroll") for (int n = 0; n < 2; ++n) _Pragma("unroll") for (int k = 0; k < 2; ++k) \
;       acc[ai][bj][m][n] = __builtin_amdgcn_mfma_f32_16x16x32_bf16(BT[n][k], AT[m][k], acc[ai][bj][m][n], 0, 0, 0); \
;     __builtin_amdgcn_s_setprio(0); } while (0)
; #define WAIT_V(n) asm volatile("s_waitcnt vmcnt(" #n ")" ::: "memory")
; #define WAIT_L(n) asm volatile("s_waitcnt lgkmcnt(" #n ")" ::: "memory")
; #define BAR __builtin_amdgcn_s_barrier()
; #define SCHED __builtin_amdgcn_sched_barrier(0)
; #define WAIT_V(n) asm volatile("s_waitcnt vmcnt(" #n ")" ::: "memory")
; #define BAR do { __builtin_amdgcn_sched_barrier(0); __builtin_amdgcn_s_barrier(); asm volatile("" ::: "memory"); __builtin_amdgcn_sched_barrier(0); } while (0)
; template <bool SP2, bool ALIGN_EPI, bool DUAL, class Epi> DI void gemm_phase2(const bf16_t* A, const bf16_t* Bt, const bf16_t* A2, const bf16_t* Bt2, int M, int N, int K, const Epi& E, lds_t* lds) {
;     ...
;     for (int t = 0; t < nt; t += 2) {
;       const bool last = (t == nt - 2);
;       const char* a1 = cA + (size_t)(t + 1) * kstep;
;       const char* a2 = last ? nA : cA + (size_t)(t + 2) * kstep; const char* b2 = last ? nB : cB + (size_t)(t + 2) * kstep;
;       const char* a3 = a2 + kstep; const char* b3 = b2 + kstep;
;     ...
;         LDA(At, 1, 1); STAGEB(SB(1, 0), b3); STAGEB(SB(1, 1), b3 + bstep); STAGE(SA(1, 0), a3);
;         WAIT_V(8); WAIT_L(0); BAR; MMA(1, 0, At, B0); MMA(1, 1, At, B1); BAR; SCHED;
	s_add_i32 s27, s27, s10
	v_lshl_add_u64 v[216:217], v[216:217], 0, s[8:9]
	s_mov_b32 m0, s27
	ds_read_b128 v[180:183], v162 offset:49152
	ds_read_b128 v[184:187], v162 offset:50176
	ds_read_b128 v[188:191], v162 offset:51200
	ds_read_b128 v[192:195], v162 offset:52224
	ds_read_b128 v[196:199], v162 offset:53248
	ds_read_b128 v[200:203], v162 offset:54272
	ds_read_b128 v[204:207], v162 offset:55296
	ds_read_b128 v[208:211], v162 offset:56320
	global_load_lds_dwordx4 v[216:217], off
	s_add_i32 m0, s27, 0x2000
	s_add_u32 s44, s44, 0x40080
	v_lshl_add_u64 v[216:217], v[218:219], 0, s[8:9]
	s_addc_u32 s45, s45, 0
	s_add_i32 s27, s41, s10
	global_load_lds_dwordx4 v[216:217], off
	v_lshl_add_u64 v[216:217], s[44:45], 0, v[130:131]
	s_mov_b32 m0, s27
	s_nop 0
	global_load_lds_dwordx4 v[216:217], off
	v_lshl_add_u64 v[216:217], s[44:45], 0, v[134:135]
	s_add_i32 m0, s27, 0x2000
	s_nop 0
	global_load_lds_dwordx4 v[216:217], off
	v_lshl_add_u64 v[216:217], v[220:221], 0, s[8:9]
	s_mov_b32 m0, s39
	s_nop 0
	global_load_lds_dwordx4 v[216:217], off
	v_lshl_add_u64 v[216:217], v[222:223], 0, s[8:9]
	s_mov_b32 m0, s48
	s_nop 0
	global_load_lds_dwordx4 v[216:217], off
	s_waitcnt vmcnt(8)
	s_waitcnt lgkmcnt(0)
	s_barrier
	s_nop 0
	s_waitcnt lgkmcnt(0)
	v_mfma_f32_16x16x32_bf16 v[60:63], v[140:143], v[180:183], v[60:63]
	v_mfma_f32_16x16x32_bf16 v[56:59], v[148:151], v[180:183], v[56:59]
	v_mfma_f32_16x16x32_bf16 v[44:47], v[140:143], v[188:191], v[44:47]
	v_mfma_f32_16x16x32_bf16 v[40:43], v[148:151], v[188:191], v[40:43]
	v_mfma_f32_16x16x32_bf16 v[28:31], v[140:143], v[196:199], v[28:31]
	v_mfma_f32_16x16x32_bf16 v[24:27], v[148:151], v[196:199], v[24:27]
	v_mfma_f32_16x16x32_bf16 v[12:15], v[140:143], v[204:207], v[12:15]
	v_mfma_f32_16x16x32_bf16 v[8:11], v[148:151], v[204:207], v[8:11]
	v_mfma_f32_16x16x32_bf16 v[60:63], v[144:147], v[184:187], v[60:63]
	v_mfma_f32_16x16x32_bf16 v[56:59], v[152:155], v[184:187], v[56:59]
	v_mfma_f32_16x16x32_bf16 v[44:47], v[144:147], v[192:195], v[44:47]
	v_mfma_f32_16x16x32_bf16 v[40:43], v[152:155], v[192:195], v[40:43]
	v_mfma_f32_16x16x32_bf16 v[28:31], v[144:147], v[200:203], v[28:31]
	v_mfma_f32_16x16x32_bf16 v[24:27], v[152:155], v[200:203], v[24:27]
	v_mfma_f32_16x16x32_bf16 v[12:15], v[144:147], v[208:211], v[12:15]
	v_mfma_f32_16x16x32_bf16 v[8:11], v[152:155], v[208:211], v[8:11]
	s_nop 0
	s_nop 0
	v_mfma_f32_16x16x32_bf16 v[52:55], v[164:167], v[180:183], v[52:55]
	v_mfma_f32_16x16x32_bf16 v[48:51], v[172:175], v[180:183], v[48:51]
	v_mfma_f32_16x16x32_bf16 v[36:39], v[164:167], v[188:191], v[36:39]
	v_mfma_f32_16x16x32_bf16 v[32:35], v[172:175], v[188:191], v[32:35]
	v_mfma_f32_16x16x32_bf16 v[20:23], v[164:167], v[196:199], v[20:23]
	v_mfma_f32_16x16x32_bf16 v[16:19], v[172:175], v[196:199], v[16:19]
	v_mfma_f32_16x16x32_bf16 v[4:7], v[164:167], v[204:207], v[4:7]
	v_mfma_f32_16x16x32_bf16 v[0:3], v[172:175], v[204:207], v[0:3]
	v_mfma_f32_16x16x32_bf16 v[52:55], v[168:171], v[184:187], v[52:55]
	v_mfma_f32_16x16x32_bf16 v[48:51], v[176:179], v[184:187], v[48:51]
	v_mfma_f32_16x16x32_bf16 v[36:39], v[168:171], v[192:195], v[36:39]
	v_mfma_f32_16x16x32_bf16 v[32:35], v[176:179], v[192:195], v[32:35]
	v_mfma_f32_16x16x32_bf16 v[20:23], v[168:171], v[200:203], v[20:23]
	v_mfma_f32_16x16x32_bf16 v[16:19], v[176:179], v[200:203], v[16:19]
	v_mfma_f32_16x16x32_bf16 v[4:7], v[168:171], v[208:211], v[4:7]
	v_mfma_f32_16x16x32_bf16 v[0:3], v[176:179], v[208:211], v[0:3]
	s_nop 0
	s_barrier
	s_add_i32 s21, s21, 2
	s_add_u32 s42, s42, 0x100
	s_addc_u32 s43, s43, 0
	s_add_u32 s14, s14, 0x100
	s_addc_u32 s15, s15, 0
	s_cmp_gt_u32 s21, 61
	s_cbranch_scc0 .LBB0_900
	s_and_b64 vcc, exec, s[22:23]
	s_cbranch_vccz .LBB0_903
	s_barrier
